# hand-written quadrant K-loops: per-segment s_setprio toggles removed
# speedup vs baseline: 1.0043x; 1.0004x over previous
.Lq_lin_0_k:
	v_add_u32_e32 v165, 0x10000, v162
	ds_read_b128 v[138:141], v165
	ds_read_b128 v[166:169], v165 offset:1024
	ds_read_b128 v[170:173], v165 offset:2048
	ds_read_b128 v[174:177], v165 offset:3072
	ds_read_b128 v[206:209], v164 offset:0
	ds_read_b128 v[210:213], v164 offset:1024
	ds_read_b128 v[214:217], v164 offset:2048
	ds_read_b128 v[218:221], v164 offset:3072
	ds_read_b128 v[222:225], v164 offset:4096
	ds_read_b128 v[226:229], v164 offset:5120
	ds_read_b128 v[230:233], v164 offset:6144
	ds_read_b128 v[234:237], v164 offset:7168
	v_lshl_add_u64 v[142:143], s[74:75], 0, v[132:133]
	s_add_i32 m0, s5, 0xc000
	v_lshl_add_u64 v[160:161], s[74:75], 0, v[130:131]
	global_load_lds_dwordx4 v[142:143], off
	s_add_i32 m0, s5, 0xe000
	v_lshl_add_u64 v[178:179], s[2:3], 0, v[144:145]
	global_load_lds_dwordx4 v[160:161], off
	s_add_i32 m0, s5, 0x1c000
	v_lshl_add_u64 v[238:239], s[2:3], 0, v[128:129]
	global_load_lds_dwordx4 v[178:179], off
	s_add_i32 m0, s5, 0x1e000
	s_add_u32 s74, s74, 0x80
	s_addc_u32 s75, s75, 0
	global_load_lds_dwordx4 v[238:239], off
	s_add_u32 s2, s2, 0x80
	s_addc_u32 s3, s3, 0
	s_waitcnt vmcnt(8)
	s_waitcnt lgkmcnt(0)
	s_barrier
	v_mfma_f32_16x16x32_bf16 v[124:127], v[138:141], v[206:209], v[124:127]
	v_mfma_f32_16x16x32_bf16 v[120:123], v[170:173], v[206:209], v[120:123]
	v_mfma_f32_16x16x32_bf16 v[108:111], v[138:141], v[214:217], v[108:111]
	v_mfma_f32_16x16x32_bf16 v[104:107], v[170:173], v[214:217], v[104:107]
	v_mfma_f32_16x16x32_bf16 v[92:95], v[138:141], v[222:225], v[92:95]
	v_mfma_f32_16x16x32_bf16 v[88:91], v[170:173], v[222:225], v[88:91]
	v_mfma_f32_16x16x32_bf16 v[76:79], v[138:141], v[230:233], v[76:79]
	v_mfma_f32_16x16x32_bf16 v[72:75], v[170:173], v[230:233], v[72:75]
	v_mfma_f32_16x16x32_bf16 v[124:127], v[166:169], v[210:213], v[124:127]
	v_mfma_f32_16x16x32_bf16 v[120:123], v[174:177], v[210:213], v[120:123]
	v_mfma_f32_16x16x32_bf16 v[108:111], v[166:169], v[218:221], v[108:111]
	v_mfma_f32_16x16x32_bf16 v[104:107], v[174:177], v[218:221], v[104:107]
	v_mfma_f32_16x16x32_bf16 v[92:95], v[166:169], v[226:229], v[92:95]
	v_mfma_f32_16x16x32_bf16 v[88:91], v[174:177], v[226:229], v[88:91]
	v_mfma_f32_16x16x32_bf16 v[76:79], v[166:169], v[234:237], v[76:79]
	v_mfma_f32_16x16x32_bf16 v[72:75], v[174:177], v[234:237], v[72:75]
	s_barrier
	v_add_u32_e32 v165, 0x18000, v162
	ds_read_b128 v[138:141], v165
	ds_read_b128 v[166:169], v165 offset:1024
	ds_read_b128 v[170:173], v165 offset:2048
	ds_read_b128 v[174:177], v165 offset:3072
	ds_read_b128 v[206:209], v164 offset:32768
	ds_read_b128 v[210:213], v164 offset:33792
	ds_read_b128 v[214:217], v164 offset:34816
	ds_read_b128 v[218:221], v164 offset:35840
	ds_read_b128 v[222:225], v164 offset:36864
	ds_read_b128 v[226:229], v164 offset:37888
	ds_read_b128 v[230:233], v164 offset:38912
	ds_read_b128 v[234:237], v164 offset:39936
	v_lshl_add_u64 v[142:143], s[74:75], 0, v[132:133]
	s_add_i32 m0, s5, 0x0
	v_lshl_add_u64 v[160:161], s[74:75], 0, v[130:131]
	global_load_lds_dwordx4 v[142:143], off
	s_add_i32 m0, s5, 0x2000
	v_lshl_add_u64 v[178:179], s[2:3], 0, v[144:145]
	global_load_lds_dwordx4 v[160:161], off
	s_add_i32 m0, s5, 0x10000
	v_lshl_add_u64 v[238:239], s[2:3], 0, v[128:129]
	global_load_lds_dwordx4 v[178:179], off
	s_add_i32 m0, s5, 0x12000
	s_add_u32 s74, s74, 0x80
	s_addc_u32 s75, s75, 0
	global_load_lds_dwordx4 v[238:239], off
	s_add_u32 s2, s2, 0x80
	s_addc_u32 s3, s3, 0
	s_waitcnt vmcnt(8)
	s_waitcnt lgkmcnt(0)
	s_barrier
	v_mfma_f32_16x16x32_bf16 v[124:127], v[138:141], v[206:209], v[124:127]
	v_mfma_f32_16x16x32_bf16 v[120:123], v[170:173], v[206:209], v[120:123]
	v_mfma_f32_16x16x32_bf16 v[108:111], v[138:141], v[214:217], v[108:111]
	v_mfma_f32_16x16x32_bf16 v[104:107], v[170:173], v[214:217], v[104:107]
	v_mfma_f32_16x16x32_bf16 v[92:95], v[138:141], v[222:225], v[92:95]
	v_mfma_f32_16x16x32_bf16 v[88:91], v[170:173], v[222:225], v[88:91]
	v_mfma_f32_16x16x32_bf16 v[76:79], v[138:141], v[230:233], v[76:79]
	v_mfma_f32_16x16x32_bf16 v[72:75], v[170:173], v[230:233], v[72:75]
	v_mfma_f32_16x16x32_bf16 v[124:127], v[166:169], v[210:213], v[124:127]
	v_mfma_f32_16x16x32_bf16 v[120:123], v[174:177], v[210:213], v[120:123]
	v_mfma_f32_16x16x32_bf16 v[108:111], v[166:169], v[218:221], v[108:111]
	v_mfma_f32_16x16x32_bf16 v[104:107], v[174:177], v[218:221], v[104:107]
	v_mfma_f32_16x16x32_bf16 v[92:95], v[166:169], v[226:229], v[92:95]
	v_mfma_f32_16x16x32_bf16 v[88:91], v[174:177], v[226:229], v[88:91]
	v_mfma_f32_16x16x32_bf16 v[76:79], v[166:169], v[234:237], v[76:79]
	v_mfma_f32_16x16x32_bf16 v[72:75], v[174:177], v[234:237], v[72:75]
	s_barrier
	v_add_u32_e32 v165, 0x14000, v162
	ds_read_b128 v[138:141], v165
	ds_read_b128 v[166:169], v165 offset:1024
	ds_read_b128 v[170:173], v165 offset:2048
	ds_read_b128 v[174:177], v165 offset:3072
	ds_read_b128 v[206:209], v164 offset:16384
	ds_read_b128 v[210:213], v164 offset:17408
	ds_read_b128 v[214:217], v164 offset:18432
	ds_read_b128 v[218:221], v164 offset:19456
	ds_read_b128 v[222:225], v164 offset:20480
	ds_read_b128 v[226:229], v164 offset:21504
	ds_read_b128 v[230:233], v164 offset:22528
	ds_read_b128 v[234:237], v164 offset:23552
	v_lshl_add_u64 v[142:143], s[74:75], 0, v[132:133]
	s_add_i32 m0, s5, 0x8000
	v_lshl_add_u64 v[160:161], s[74:75], 0, v[130:131]
	global_load_lds_dwordx4 v[142:143], off
	s_add_i32 m0, s5, 0xa000
	v_lshl_add_u64 v[178:179], s[2:3], 0, v[144:145]
	global_load_lds_dwordx4 v[160:161], off
	s_add_i32 m0, s5, 0x18000
	v_lshl_add_u64 v[238:239], s[2:3], 0, v[128:129]
	global_load_lds_dwordx4 v[178:179], off
	s_add_i32 m0, s5, 0x1a000
	s_add_u32 s74, s74, 0x80
	s_addc_u32 s75, s75, 0
	global_load_lds_dwordx4 v[238:239], off
	s_add_u32 s2, s2, 0x80
	s_addc_u32 s3, s3, 0
	s_waitcnt vmcnt(8)
	s_waitcnt lgkmcnt(0)
	s_barrier
	v_mfma_f32_16x16x32_bf16 v[124:127], v[138:141], v[206:209], v[124:127]
	v_mfma_f32_16x16x32_bf16 v[120:123], v[170:173], v[206:209], v[120:123]
	v_mfma_f32_16x16x32_bf16 v[108:111], v[138:141], v[214:217], v[108:111]
	v_mfma_f32_16x16x32_bf16 v[104:107], v[170:173], v[214:217], v[104:107]
	v_mfma_f32_16x16x32_bf16 v[92:95], v[138:141], v[222:225], v[92:95]
	v_mfma_f32_16x16x32_bf16 v[88:91], v[170:173], v[222:225], v[88:91]
	v_mfma_f32_16x16x32_bf16 v[76:79], v[138:141], v[230:233], v[76:79]
	v_mfma_f32_16x16x32_bf16 v[72:75], v[170:173], v[230:233], v[72:75]
	v_mfma_f32_16x16x32_bf16 v[124:127], v[166:169], v[210:213], v[124:127]
	v_mfma_f32_16x16x32_bf16 v[120:123], v[174:177], v[210:213], v[120:123]
	v_mfma_f32_16x16x32_bf16 v[108:111], v[166:169], v[218:221], v[108:111]
	v_mfma_f32_16x16x32_bf16 v[104:107], v[174:177], v[218:221], v[104:107]
	v_mfma_f32_16x16x32_bf16 v[92:95], v[166:169], v[226:229], v[92:95]
	v_mfma_f32_16x16x32_bf16 v[88:91], v[174:177], v[226:229], v[88:91]
	v_mfma_f32_16x16x32_bf16 v[76:79], v[166:169], v[234:237], v[76:79]
	v_mfma_f32_16x16x32_bf16 v[72:75], v[174:177], v[234:237], v[72:75]
	s_barrier
	v_add_u32_e32 v165, 0x1c000, v162
	ds_read_b128 v[138:141], v165
	ds_read_b128 v[166:169], v165 offset:1024
	ds_read_b128 v[170:173], v165 offset:2048
	ds_read_b128 v[174:177], v165 offset:3072
	ds_read_b128 v[206:209], v164 offset:49152
	ds_read_b128 v[210:213], v164 offset:50176
	ds_read_b128 v[214:217], v164 offset:51200
	ds_read_b128 v[218:221], v164 offset:52224
	ds_read_b128 v[222:225], v164 offset:53248
	ds_read_b128 v[226:229], v164 offset:54272
	ds_read_b128 v[230:233], v164 offset:55296
	ds_read_b128 v[234:237], v164 offset:56320
	v_lshl_add_u64 v[142:143], s[74:75], 0, v[132:133]
	s_add_i32 m0, s5, 0x4000
	v_lshl_add_u64 v[160:161], s[74:75], 0, v[130:131]
	global_load_lds_dwordx4 v[142:143], off
	s_add_i32 m0, s5, 0x6000
	v_lshl_add_u64 v[178:179], s[2:3], 0, v[144:145]
	global_load_lds_dwordx4 v[160:161], off
	s_add_i32 m0, s5, 0x14000
	v_lshl_add_u64 v[238:239], s[2:3], 0, v[128:129]
	global_load_lds_dwordx4 v[178:179], off
	s_add_i32 m0, s5, 0x16000
	s_add_u32 s74, s74, 0x80
	s_addc_u32 s75, s75, 0
	global_load_lds_dwordx4 v[238:239], off
	s_add_u32 s2, s2, 0x80
	s_addc_u32 s3, s3, 0
	s_waitcnt vmcnt(8)
	s_waitcnt lgkmcnt(0)
	s_barrier
	v_mfma_f32_16x16x32_bf16 v[124:127], v[138:141], v[206:209], v[124:127]
	v_mfma_f32_16x16x32_bf16 v[120:123], v[170:173], v[206:209], v[120:123]
	v_mfma_f32_16x16x32_bf16 v[108:111], v[138:141], v[214:217], v[108:111]
	v_mfma_f32_16x16x32_bf16 v[104:107], v[170:173], v[214:217], v[104:107]
	v_mfma_f32_16x16x32_bf16 v[92:95], v[138:141], v[222:225], v[92:95]
	v_mfma_f32_16x16x32_bf16 v[88:91], v[170:173], v[222:225], v[88:91]
	v_mfma_f32_16x16x32_bf16 v[76:79], v[138:141], v[230:233], v[76:79]
	v_mfma_f32_16x16x32_bf16 v[72:75], v[170:173], v[230:233], v[72:75]
	v_mfma_f32_16x16x32_bf16 v[124:127], v[166:169], v[210:213], v[124:127]
	v_mfma_f32_16x16x32_bf16 v[120:123], v[174:177], v[210:213], v[120:123]
	v_mfma_f32_16x16x32_bf16 v[108:111], v[166:169], v[218:221], v[108:111]
	v_mfma_f32_16x16x32_bf16 v[104:107], v[174:177], v[218:221], v[104:107]
	v_mfma_f32_16x16x32_bf16 v[92:95], v[166:169], v[226:229], v[92:95]
	v_mfma_f32_16x16x32_bf16 v[88:91], v[174:177], v[226:229], v[88:91]
	v_mfma_f32_16x16x32_bf16 v[76:79], v[166:169], v[234:237], v[76:79]
	v_mfma_f32_16x16x32_bf16 v[72:75], v[174:177], v[234:237], v[72:75]
	s_barrier
	s_add_i32 s8, s8, 1
	s_cmp_lt_u32 s8, 7
	s_cbranch_scc1 .Lq_lin_0_k
	v_add_u32_e32 v165, 0x10000, v162
	ds_read_b128 v[138:141], v165
	ds_read_b128 v[166:169], v165 offset:1024
	ds_read_b128 v[170:173], v165 offset:2048
	ds_read_b128 v[174:177], v165 offset:3072
	ds_read_b128 v[206:209], v164 offset:0
	ds_read_b128 v[210:213], v164 offset:1024
	ds_read_b128 v[214:217], v164 offset:2048
	ds_read_b128 v[218:221], v164 offset:3072
	ds_read_b128 v[222:225], v164 offset:4096
	ds_read_b128 v[226:229], v164 offset:5120
	ds_read_b128 v[230:233], v164 offset:6144
	ds_read_b128 v[234:237], v164 offset:7168
	v_lshl_add_u64 v[142:143], s[74:75], 0, v[132:133]
	s_add_i32 m0, s5, 0xc000
	v_lshl_add_u64 v[160:161], s[74:75], 0, v[130:131]
	global_load_lds_dwordx4 v[142:143], off
	s_add_i32 m0, s5, 0xe000
	v_lshl_add_u64 v[178:179], s[2:3], 0, v[144:145]
	global_load_lds_dwordx4 v[160:161], off
	s_add_i32 m0, s5, 0x1c000
	v_lshl_add_u64 v[238:239], s[2:3], 0, v[128:129]
	global_load_lds_dwordx4 v[178:179], off
	s_add_i32 m0, s5, 0x1e000
	s_add_u32 s74, s74, 0x80
	s_addc_u32 s75, s75, 0
	global_load_lds_dwordx4 v[238:239], off
	s_add_u32 s2, s2, 0x80
	s_addc_u32 s3, s3, 0
	s_waitcnt vmcnt(8)
	s_waitcnt lgkmcnt(0)
	s_barrier
	v_mfma_f32_16x16x32_bf16 v[124:127], v[138:141], v[206:209], v[124:127]
	v_mfma_f32_16x16x32_bf16 v[120:123], v[170:173], v[206:209], v[120:123]
	v_mfma_f32_16x16x32_bf16 v[108:111], v[138:141], v[214:217], v[108:111]
	v_mfma_f32_16x16x32_bf16 v[104:107], v[170:173], v[214:217], v[104:107]
	v_mfma_f32_16x16x32_bf16 v[92:95], v[138:141], v[222:225], v[92:95]
	v_mfma_f32_16x16x32_bf16 v[88:91], v[170:173], v[222:225], v[88:91]
	v_mfma_f32_16x16x32_bf16 v[76:79], v[138:141], v[230:233], v[76:79]
	v_mfma_f32_16x16x32_bf16 v[72:75], v[170:173], v[230:233], v[72:75]
	v_mfma_f32_16x16x32_bf16 v[124:127], v[166:169], v[210:213], v[124:127]
	v_mfma_f32_16x16x32_bf16 v[120:123], v[174:177], v[210:213], v[120:123]
	v_mfma_f32_16x16x32_bf16 v[108:111], v[166:169], v[218:221], v[108:111]
	v_mfma_f32_16x16x32_bf16 v[104:107], v[174:177], v[218:221], v[104:107]
	v_mfma_f32_16x16x32_bf16 v[92:95], v[166:169], v[226:229], v[92:95]
	v_mfma_f32_16x16x32_bf16 v[88:91], v[174:177], v[226:229], v[88:91]
	v_mfma_f32_16x16x32_bf16 v[76:79], v[166:169], v[234:237], v[76:79]
	v_mfma_f32_16x16x32_bf16 v[72:75], v[174:177], v[234:237], v[72:75]
	s_barrier
	v_add_u32_e32 v165, 0x18000, v162
	ds_read_b128 v[138:141], v165
	ds_read_b128 v[166:169], v165 offset:1024
	ds_read_b128 v[170:173], v165 offset:2048
	ds_read_b128 v[174:177], v165 offset:3072
	ds_read_b128 v[206:209], v164 offset:32768
	ds_read_b128 v[210:213], v164 offset:33792
	ds_read_b128 v[214:217], v164 offset:34816
	ds_read_b128 v[218:221], v164 offset:35840
	ds_read_b128 v[222:225], v164 offset:36864
	ds_read_b128 v[226:229], v164 offset:37888
	ds_read_b128 v[230:233], v164 offset:38912
	ds_read_b128 v[234:237], v164 offset:39936
	s_waitcnt vmcnt(4)
	s_waitcnt lgkmcnt(0)
	s_barrier
	v_mfma_f32_16x16x32_bf16 v[124:127], v[138:141], v[206:209], v[124:127]
	v_mfma_f32_16x16x32_bf16 v[120:123], v[170:173], v[206:209], v[120:123]
	v_mfma_f32_16x16x32_bf16 v[108:111], v[138:141], v[214:217], v[108:111]
	v_mfma_f32_16x16x32_bf16 v[104:107], v[170:173], v[214:217], v[104:107]
	v_mfma_f32_16x16x32_bf16 v[92:95], v[138:141], v[222:225], v[92:95]
	v_mfma_f32_16x16x32_bf16 v[88:91], v[170:173], v[222:225], v[88:91]
	v_mfma_f32_16x16x32_bf16 v[76:79], v[138:141], v[230:233], v[76:79]
	v_mfma_f32_16x16x32_bf16 v[72:75], v[170:173], v[230:233], v[72:75]
	v_mfma_f32_16x16x32_bf16 v[124:127], v[166:169], v[210:213], v[124:127]
	v_mfma_f32_16x16x32_bf16 v[120:123], v[174:177], v[210:213], v[120:123]
	v_mfma_f32_16x16x32_bf16 v[108:111], v[166:169], v[218:221], v[108:111]
	v_mfma_f32_16x16x32_bf16 v[104:107], v[174:177], v[218:221], v[104:107]
	v_mfma_f32_16x16x32_bf16 v[92:95], v[166:169], v[226:229], v[92:95]
	v_mfma_f32_16x16x32_bf16 v[88:91], v[174:177], v[226:229], v[88:91]
	v_mfma_f32_16x16x32_bf16 v[76:79], v[166:169], v[234:237], v[76:79]
	v_mfma_f32_16x16x32_bf16 v[72:75], v[174:177], v[234:237], v[72:75]
	s_barrier
	v_add_u32_e32 v165, 0x14000, v162
	ds_read_b128 v[138:141], v165
	ds_read_b128 v[166:169], v165 offset:1024
	ds_read_b128 v[170:173], v165 offset:2048
	ds_read_b128 v[174:177], v165 offset:3072
	ds_read_b128 v[206:209], v164 offset:16384
	ds_read_b128 v[210:213], v164 offset:17408
	ds_read_b128 v[214:217], v164 offset:18432
	ds_read_b128 v[218:221], v164 offset:19456
	ds_read_b128 v[222:225], v164 offset:20480
	ds_read_b128 v[226:229], v164 offset:21504
	ds_read_b128 v[230:233], v164 offset:22528
	ds_read_b128 v[234:237], v164 offset:23552
	s_waitcnt vmcnt(0)
	s_waitcnt lgkmcnt(0)
	s_barrier
	v_mfma_f32_16x16x32_bf16 v[124:127], v[138:141], v[206:209], v[124:127]
	v_mfma_f32_16x16x32_bf16 v[120:123], v[170:173], v[206:209], v[120:123]
	v_mfma_f32_16x16x32_bf16 v[108:111], v[138:141], v[214:217], v[108:111]
	v_mfma_f32_16x16x32_bf16 v[104:107], v[170:173], v[214:217], v[104:107]
	v_mfma_f32_16x16x32_bf16 v[92:95], v[138:141], v[222:225], v[92:95]
	v_mfma_f32_16x16x32_bf16 v[88:91], v[170:173], v[222:225], v[88:91]
	v_mfma_f32_16x16x32_bf16 v[76:79], v[138:141], v[230:233], v[76:79]
	v_mfma_f32_16x16x32_bf16 v[72:75], v[170:173], v[230:233], v[72:75]
	v_mfma_f32_16x16x32_bf16 v[124:127], v[166:169], v[210:213], v[124:127]
	v_mfma_f32_16x16x32_bf16 v[120:123], v[174:177], v[210:213], v[120:123]
	v_mfma_f32_16x16x32_bf16 v[108:111], v[166:169], v[218:221], v[108:111]
	v_mfma_f32_16x16x32_bf16 v[104:107], v[174:177], v[218:221], v[104:107]
	v_mfma_f32_16x16x32_bf16 v[92:95], v[166:169], v[226:229], v[92:95]
	v_mfma_f32_16x16x32_bf16 v[88:91], v[174:177], v[226:229], v[88:91]
	v_mfma_f32_16x16x32_bf16 v[76:79], v[166:169], v[234:237], v[76:79]
	v_mfma_f32_16x16x32_bf16 v[72:75], v[174:177], v[234:237], v[72:75]
	s_barrier
	v_add_u32_e32 v165, 0x1c000, v162
	ds_read_b128 v[138:141], v165
	ds_read_b128 v[166:169], v165 offset:1024
	ds_read_b128 v[170:173], v165 offset:2048
	ds_read_b128 v[174:177], v165 offset:3072
	ds_read_b128 v[206:209], v164 offset:49152
	ds_read_b128 v[210:213], v164 offset:50176
	ds_read_b128 v[214:217], v164 offset:51200
	ds_read_b128 v[218:221], v164 offset:52224
	ds_read_b128 v[222:225], v164 offset:53248
	ds_read_b128 v[226:229], v164 offset:54272
	ds_read_b128 v[230:233], v164 offset:55296
	ds_read_b128 v[234:237], v164 offset:56320
	s_waitcnt lgkmcnt(0)
	s_barrier
	v_mfma_f32_16x16x32_bf16 v[124:127], v[138:141], v[206:209], v[124:127]
	v_mfma_f32_16x16x32_bf16 v[120:123], v[170:173], v[206:209], v[120:123]
	v_mfma_f32_16x16x32_bf16 v[108:111], v[138:141], v[214:217], v[108:111]
	v_mfma_f32_16x16x32_bf16 v[104:107], v[170:173], v[214:217], v[104:107]
	v_mfma_f32_16x16x32_bf16 v[92:95], v[138:141], v[222:225], v[92:95]
	v_mfma_f32_16x16x32_bf16 v[88:91], v[170:173], v[222:225], v[88:91]
	v_mfma_f32_16x16x32_bf16 v[76:79], v[138:141], v[230:233], v[76:79]
	v_mfma_f32_16x16x32_bf16 v[72:75], v[170:173], v[230:233], v[72:75]
	v_mfma_f32_16x16x32_bf16 v[124:127], v[166:169], v[210:213], v[124:127]
	v_mfma_f32_16x16x32_bf16 v[120:123], v[174:177], v[210:213], v[120:123]
	v_mfma_f32_16x16x32_bf16 v[108:111], v[166:169], v[218:221], v[108:111]
	v_mfma_f32_16x16x32_bf16 v[104:107], v[174:177], v[218:221], v[104:107]
	v_mfma_f32_16x16x32_bf16 v[92:95], v[166:169], v[226:229], v[92:95]
	v_mfma_f32_16x16x32_bf16 v[88:91], v[174:177], v[226:229], v[88:91]
	v_mfma_f32_16x16x32_bf16 v[76:79], v[166:169], v[234:237], v[76:79]
	v_mfma_f32_16x16x32_bf16 v[72:75], v[174:177], v[234:237], v[72:75]
	s_barrier
	s_branch .Lq_lin_exit

.Lq_lin_1_k:
	v_add_u32_e32 v165, 0x14000, v162
	ds_read_b128 v[190:193], v165
	ds_read_b128 v[194:197], v165 offset:1024
	ds_read_b128 v[198:201], v165 offset:2048
	ds_read_b128 v[202:205], v165 offset:3072
	ds_read_b128 v[206:209], v164 offset:0
	ds_read_b128 v[210:213], v164 offset:1024
	ds_read_b128 v[214:217], v164 offset:2048
	ds_read_b128 v[218:221], v164 offset:3072
	ds_read_b128 v[222:225], v164 offset:4096
	ds_read_b128 v[226:229], v164 offset:5120
	ds_read_b128 v[230:233], v164 offset:6144
	ds_read_b128 v[234:237], v164 offset:7168
	v_lshl_add_u64 v[142:143], s[74:75], 0, v[132:133]
	s_add_i32 m0, s5, 0xc000
	v_lshl_add_u64 v[160:161], s[74:75], 0, v[130:131]
	global_load_lds_dwordx4 v[142:143], off
	s_add_i32 m0, s5, 0xe000
	v_lshl_add_u64 v[178:179], s[2:3], 0, v[144:145]
	global_load_lds_dwordx4 v[160:161], off
	s_add_i32 m0, s5, 0x18000
	v_lshl_add_u64 v[238:239], s[2:3], 0, v[128:129]
	global_load_lds_dwordx4 v[178:179], off
	s_add_i32 m0, s5, 0x1a000
	s_add_u32 s74, s74, 0x80
	s_addc_u32 s75, s75, 0
	global_load_lds_dwordx4 v[238:239], off
	s_add_u32 s2, s2, 0x80
	s_addc_u32 s3, s3, 0
	s_waitcnt vmcnt(8)
	s_waitcnt lgkmcnt(0)
	s_barrier
	v_mfma_f32_16x16x32_bf16 v[116:119], v[190:193], v[206:209], v[116:119]
	v_mfma_f32_16x16x32_bf16 v[112:115], v[198:201], v[206:209], v[112:115]
	v_mfma_f32_16x16x32_bf16 v[100:103], v[190:193], v[214:217], v[100:103]
	v_mfma_f32_16x16x32_bf16 v[96:99], v[198:201], v[214:217], v[96:99]
	v_mfma_f32_16x16x32_bf16 v[84:87], v[190:193], v[222:225], v[84:87]
	v_mfma_f32_16x16x32_bf16 v[80:83], v[198:201], v[222:225], v[80:83]
	v_mfma_f32_16x16x32_bf16 v[68:71], v[190:193], v[230:233], v[68:71]
	v_mfma_f32_16x16x32_bf16 v[64:67], v[198:201], v[230:233], v[64:67]
	v_mfma_f32_16x16x32_bf16 v[116:119], v[194:197], v[210:213], v[116:119]
	v_mfma_f32_16x16x32_bf16 v[112:115], v[202:205], v[210:213], v[112:115]
	v_mfma_f32_16x16x32_bf16 v[100:103], v[194:197], v[218:221], v[100:103]
	v_mfma_f32_16x16x32_bf16 v[96:99], v[202:205], v[218:221], v[96:99]
	v_mfma_f32_16x16x32_bf16 v[84:87], v[194:197], v[226:229], v[84:87]
	v_mfma_f32_16x16x32_bf16 v[80:83], v[202:205], v[226:229], v[80:83]
	v_mfma_f32_16x16x32_bf16 v[68:71], v[194:197], v[234:237], v[68:71]
	v_mfma_f32_16x16x32_bf16 v[64:67], v[202:205], v[234:237], v[64:67]
	s_barrier
	v_add_u32_e32 v165, 0x1c000, v162
	ds_read_b128 v[190:193], v165
	ds_read_b128 v[194:197], v165 offset:1024
	ds_read_b128 v[198:201], v165 offset:2048
	ds_read_b128 v[202:205], v165 offset:3072
	ds_read_b128 v[206:209], v164 offset:32768
	ds_read_b128 v[210:213], v164 offset:33792
	ds_read_b128 v[214:217], v164 offset:34816
	ds_read_b128 v[218:221], v164 offset:35840
	ds_read_b128 v[222:225], v164 offset:36864
	ds_read_b128 v[226:229], v164 offset:37888
	ds_read_b128 v[230:233], v164 offset:38912
	ds_read_b128 v[234:237], v164 offset:39936
	v_lshl_add_u64 v[142:143], s[74:75], 0, v[132:133]
	s_add_i32 m0, s5, 0x0
	v_lshl_add_u64 v[160:161], s[74:75], 0, v[130:131]
	global_load_lds_dwordx4 v[142:143], off
	s_add_i32 m0, s5, 0x2000
	v_lshl_add_u64 v[178:179], s[2:3], 0, v[144:145]
	global_load_lds_dwordx4 v[160:161], off
	s_add_i32 m0, s5, 0x14000
	v_lshl_add_u64 v[238:239], s[2:3], 0, v[128:129]
	global_load_lds_dwordx4 v[178:179], off
	s_add_i32 m0, s5, 0x16000
	s_add_u32 s74, s74, 0x80
	s_addc_u32 s75, s75, 0
	global_load_lds_dwordx4 v[238:239], off
	s_add_u32 s2, s2, 0x80
	s_addc_u32 s3, s3, 0
	s_waitcnt vmcnt(8)
	s_waitcnt lgkmcnt(0)
	s_barrier
	v_mfma_f32_16x16x32_bf16 v[116:119], v[190:193], v[206:209], v[116:119]
	v_mfma_f32_16x16x32_bf16 v[112:115], v[198:201], v[206:209], v[112:115]
	v_mfma_f32_16x16x32_bf16 v[100:103], v[190:193], v[214:217], v[100:103]
	v_mfma_f32_16x16x32_bf16 v[96:99], v[198:201], v[214:217], v[96:99]
	v_mfma_f32_16x16x32_bf16 v[84:87], v[190:193], v[222:225], v[84:87]
	v_mfma_f32_16x16x32_bf16 v[80:83], v[198:201], v[222:225], v[80:83]
	v_mfma_f32_16x16x32_bf16 v[68:71], v[190:193], v[230:233], v[68:71]
	v_mfma_f32_16x16x32_bf16 v[64:67], v[198:201], v[230:233], v[64:67]
	v_mfma_f32_16x16x32_bf16 v[116:119], v[194:197], v[210:213], v[116:119]
	v_mfma_f32_16x16x32_bf16 v[112:115], v[202:205], v[210:213], v[112:115]
	v_mfma_f32_16x16x32_bf16 v[100:103], v[194:197], v[218:221], v[100:103]
	v_mfma_f32_16x16x32_bf16 v[96:99], v[202:205], v[218:221], v[96:99]
	v_mfma_f32_16x16x32_bf16 v[84:87], v[194:197], v[226:229], v[84:87]
	v_mfma_f32_16x16x32_bf16 v[80:83], v[202:205], v[226:229], v[80:83]
	v_mfma_f32_16x16x32_bf16 v[68:71], v[194:197], v[234:237], v[68:71]
	v_mfma_f32_16x16x32_bf16 v[64:67], v[202:205], v[234:237], v[64:67]
	s_barrier
	v_add_u32_e32 v165, 0x10000, v162
	ds_read_b128 v[190:193], v165
	ds_read_b128 v[194:197], v165 offset:1024
	ds_read_b128 v[198:201], v165 offset:2048
	ds_read_b128 v[202:205], v165 offset:3072
	ds_read_b128 v[206:209], v164 offset:16384
	ds_read_b128 v[210:213], v164 offset:17408
	ds_read_b128 v[214:217], v164 offset:18432
	ds_read_b128 v[218:221], v164 offset:19456
	ds_read_b128 v[222:225], v164 offset:20480
	ds_read_b128 v[226:229], v164 offset:21504
	ds_read_b128 v[230:233], v164 offset:22528
	ds_read_b128 v[234:237], v164 offset:23552
	v_lshl_add_u64 v[142:143], s[74:75], 0, v[132:133]
	s_add_i32 m0, s5, 0x8000
	v_lshl_add_u64 v[160:161], s[74:75], 0, v[130:131]
	global_load_lds_dwordx4 v[142:143], off
	s_add_i32 m0, s5, 0xa000
	v_lshl_add_u64 v[178:179], s[2:3], 0, v[144:145]
	global_load_lds_dwordx4 v[160:161], off
	s_add_i32 m0, s5, 0x1c000
	v_lshl_add_u64 v[238:239], s[2:3], 0, v[128:129]
	global_load_lds_dwordx4 v[178:179], off
	s_add_i32 m0, s5, 0x1e000
	s_add_u32 s74, s74, 0x80
	s_addc_u32 s75, s75, 0
	global_load_lds_dwordx4 v[238:239], off
	s_add_u32 s2, s2, 0x80
	s_addc_u32 s3, s3, 0
	s_waitcnt vmcnt(8)
	s_waitcnt lgkmcnt(0)
	s_barrier
	v_mfma_f32_16x16x32_bf16 v[116:119], v[190:193], v[206:209], v[116:119]
	v_mfma_f32_16x16x32_bf16 v[112:115], v[198:201], v[206:209], v[112:115]
	v_mfma_f32_16x16x32_bf16 v[100:103], v[190:193], v[214:217], v[100:103]
	v_mfma_f32_16x16x32_bf16 v[96:99], v[198:201], v[214:217], v[96:99]
	v_mfma_f32_16x16x32_bf16 v[84:87], v[190:193], v[222:225], v[84:87]
	v_mfma_f32_16x16x32_bf16 v[80:83], v[198:201], v[222:225], v[80:83]
	v_mfma_f32_16x16x32_bf16 v[68:71], v[190:193], v[230:233], v[68:71]
	v_mfma_f32_16x16x32_bf16 v[64:67], v[198:201], v[230:233], v[64:67]
	v_mfma_f32_16x16x32_bf16 v[116:119], v[194:197], v[210:213], v[116:119]
	v_mfma_f32_16x16x32_bf16 v[112:115], v[202:205], v[210:213], v[112:115]
	v_mfma_f32_16x16x32_bf16 v[100:103], v[194:197], v[218:221], v[100:103]
	v_mfma_f32_16x16x32_bf16 v[96:99], v[202:205], v[218:221], v[96:99]
	v_mfma_f32_16x16x32_bf16 v[84:87], v[194:197], v[226:229], v[84:87]
	v_mfma_f32_16x16x32_bf16 v[80:83], v[202:205], v[226:229], v[80:83]
	v_mfma_f32_16x16x32_bf16 v[68:71], v[194:197], v[234:237], v[68:71]
	v_mfma_f32_16x16x32_bf16 v[64:67], v[202:205], v[234:237], v[64:67]
	s_barrier
	v_add_u32_e32 v165, 0x18000, v162
	ds_read_b128 v[190:193], v165
	ds_read_b128 v[194:197], v165 offset:1024
	ds_read_b128 v[198:201], v165 offset:2048
	ds_read_b128 v[202:205], v165 offset:3072
	ds_read_b128 v[206:209], v164 offset:49152
	ds_read_b128 v[210:213], v164 offset:50176
	ds_read_b128 v[214:217], v164 offset:51200
	ds_read_b128 v[218:221], v164 offset:52224
	ds_read_b128 v[222:225], v164 offset:53248
	ds_read_b128 v[226:229], v164 offset:54272
	ds_read_b128 v[230:233], v164 offset:55296
	ds_read_b128 v[234:237], v164 offset:56320
	v_lshl_add_u64 v[142:143], s[74:75], 0, v[132:133]
	s_add_i32 m0, s5, 0x4000
	v_lshl_add_u64 v[160:161], s[74:75], 0, v[130:131]
	global_load_lds_dwordx4 v[142:143], off
	s_add_i32 m0, s5, 0x6000
	v_lshl_add_u64 v[178:179], s[2:3], 0, v[144:145]
	global_load_lds_dwordx4 v[160:161], off
	s_add_i32 m0, s5, 0x10000
	v_lshl_add_u64 v[238:239], s[2:3], 0, v[128:129]
	global_load_lds_dwordx4 v[178:179], off
	s_add_i32 m0, s5, 0x12000
	s_add_u32 s74, s74, 0x80
	s_addc_u32 s75, s75, 0
	global_load_lds_dwordx4 v[238:239], off
	s_add_u32 s2, s2, 0x80
	s_addc_u32 s3, s3, 0
	s_waitcnt vmcnt(8)
	s_waitcnt lgkmcnt(0)
	s_barrier
	v_mfma_f32_16x16x32_bf16 v[116:119], v[190:193], v[206:209], v[116:119]
	v_mfma_f32_16x16x32_bf16 v[112:115], v[198:201], v[206:209], v[112:115]
	v_mfma_f32_16x16x32_bf16 v[100:103], v[190:193], v[214:217], v[100:103]
	v_mfma_f32_16x16x32_bf16 v[96:99], v[198:201], v[214:217], v[96:99]
	v_mfma_f32_16x16x32_bf16 v[84:87], v[190:193], v[222:225], v[84:87]
	v_mfma_f32_16x16x32_bf16 v[80:83], v[198:201], v[222:225], v[80:83]
	v_mfma_f32_16x16x32_bf16 v[68:71], v[190:193], v[230:233], v[68:71]
	v_mfma_f32_16x16x32_bf16 v[64:67], v[198:201], v[230:233], v[64:67]
	v_mfma_f32_16x16x32_bf16 v[116:119], v[194:197], v[210:213], v[116:119]
	v_mfma_f32_16x16x32_bf16 v[112:115], v[202:205], v[210:213], v[112:115]
	v_mfma_f32_16x16x32_bf16 v[100:103], v[194:197], v[218:221], v[100:103]
	v_mfma_f32_16x16x32_bf16 v[96:99], v[202:205], v[218:221], v[96:99]
	v_mfma_f32_16x16x32_bf16 v[84:87], v[194:197], v[226:229], v[84:87]
	v_mfma_f32_16x16x32_bf16 v[80:83], v[202:205], v[226:229], v[80:83]
	v_mfma_f32_16x16x32_bf16 v[68:71], v[194:197], v[234:237], v[68:71]
	v_mfma_f32_16x16x32_bf16 v[64:67], v[202:205], v[234:237], v[64:67]
	s_barrier
	s_add_i32 s8, s8, 1
	s_cmp_lt_u32 s8, 7
	s_cbranch_scc1 .Lq_lin_1_k
	v_add_u32_e32 v165, 0x14000, v162
	ds_read_b128 v[190:193], v165
	ds_read_b128 v[194:197], v165 offset:1024
	ds_read_b128 v[198:201], v165 offset:2048
	ds_read_b128 v[202:205], v165 offset:3072
	ds_read_b128 v[206:209], v164 offset:0
	ds_read_b128 v[210:213], v164 offset:1024
	ds_read_b128 v[214:217], v164 offset:2048
	ds_read_b128 v[218:221], v164 offset:3072
	ds_read_b128 v[222:225], v164 offset:4096
	ds_read_b128 v[226:229], v164 offset:5120
	ds_read_b128 v[230:233], v164 offset:6144
	ds_read_b128 v[234:237], v164 offset:7168
	v_lshl_add_u64 v[142:143], s[74:75], 0, v[132:133]
	s_add_i32 m0, s5, 0xc000
	v_lshl_add_u64 v[160:161], s[74:75], 0, v[130:131]
	global_load_lds_dwordx4 v[142:143], off
	s_add_i32 m0, s5, 0xe000
	v_lshl_add_u64 v[178:179], s[2:3], 0, v[144:145]
	global_load_lds_dwordx4 v[160:161], off
	s_add_i32 m0, s5, 0x18000
	v_lshl_add_u64 v[238:239], s[2:3], 0, v[128:129]
	global_load_lds_dwordx4 v[178:179], off
	s_add_i32 m0, s5, 0x1a000
	s_add_u32 s74, s74, 0x80
	s_addc_u32 s75, s75, 0
	global_load_lds_dwordx4 v[238:239], off
	s_add_u32 s2, s2, 0x80
	s_addc_u32 s3, s3, 0
	s_waitcnt vmcnt(8)
	s_waitcnt lgkmcnt(0)
	s_barrier
	v_mfma_f32_16x16x32_bf16 v[116:119], v[190:193], v[206:209], v[116:119]
	v_mfma_f32_16x16x32_bf16 v[112:115], v[198:201], v[206:209], v[112:115]
	v_mfma_f32_16x16x32_bf16 v[100:103], v[190:193], v[214:217], v[100:103]
	v_mfma_f32_16x16x32_bf16 v[96:99], v[198:201], v[214:217], v[96:99]
	v_mfma_f32_16x16x32_bf16 v[84:87], v[190:193], v[222:225], v[84:87]
	v_mfma_f32_16x16x32_bf16 v[80:83], v[198:201], v[222:225], v[80:83]
	v_mfma_f32_16x16x32_bf16 v[68:71], v[190:193], v[230:233], v[68:71]
	v_mfma_f32_16x16x32_bf16 v[64:67], v[198:201], v[230:233], v[64:67]
	v_mfma_f32_16x16x32_bf16 v[116:119], v[194:197], v[210:213], v[116:119]
	v_mfma_f32_16x16x32_bf16 v[112:115], v[202:205], v[210:213], v[112:115]
	v_mfma_f32_16x16x32_bf16 v[100:103], v[194:197], v[218:221], v[100:103]
	v_mfma_f32_16x16x32_bf16 v[96:99], v[202:205], v[218:221], v[96:99]
	v_mfma_f32_16x16x32_bf16 v[84:87], v[194:197], v[226:229], v[84:87]
	v_mfma_f32_16x16x32_bf16 v[80:83], v[202:205], v[226:229], v[80:83]
	v_mfma_f32_16x16x32_bf16 v[68:71], v[194:197], v[234:237], v[68:71]
	v_mfma_f32_16x16x32_bf16 v[64:67], v[202:205], v[234:237], v[64:67]
	s_barrier
	v_add_u32_e32 v165, 0x1c000, v162
	ds_read_b128 v[190:193], v165
	ds_read_b128 v[194:197], v165 offset:1024
	ds_read_b128 v[198:201], v165 offset:2048
	ds_read_b128 v[202:205], v165 offset:3072
	ds_read_b128 v[206:209], v164 offset:32768
	ds_read_b128 v[210:213], v164 offset:33792
	ds_read_b128 v[214:217], v164 offset:34816
	ds_read_b128 v[218:221], v164 offset:35840
	ds_read_b128 v[222:225], v164 offset:36864
	ds_read_b128 v[226:229], v164 offset:37888
	ds_read_b128 v[230:233], v164 offset:38912
	ds_read_b128 v[234:237], v164 offset:39936
	s_waitcnt vmcnt(4)
	s_waitcnt lgkmcnt(0)
	s_barrier
	v_mfma_f32_16x16x32_bf16 v[116:119], v[190:193], v[206:209], v[116:119]
	v_mfma_f32_16x16x32_bf16 v[112:115], v[198:201], v[206:209], v[112:115]
	v_mfma_f32_16x16x32_bf16 v[100:103], v[190:193], v[214:217], v[100:103]
	v_mfma_f32_16x16x32_bf16 v[96:99], v[198:201], v[214:217], v[96:99]
	v_mfma_f32_16x16x32_bf16 v[84:87], v[190:193], v[222:225], v[84:87]
	v_mfma_f32_16x16x32_bf16 v[80:83], v[198:201], v[222:225], v[80:83]
	v_mfma_f32_16x16x32_bf16 v[68:71], v[190:193], v[230:233], v[68:71]
	v_mfma_f32_16x16x32_bf16 v[64:67], v[198:201], v[230:233], v[64:67]
	v_mfma_f32_16x16x32_bf16 v[116:119], v[194:197], v[210:213], v[116:119]
	v_mfma_f32_16x16x32_bf16 v[112:115], v[202:205], v[210:213], v[112:115]
	v_mfma_f32_16x16x32_bf16 v[100:103], v[194:197], v[218:221], v[100:103]
	v_mfma_f32_16x16x32_bf16 v[96:99], v[202:205], v[218:221], v[96:99]
	v_mfma_f32_16x16x32_bf16 v[84:87], v[194:197], v[226:229], v[84:87]
	v_mfma_f32_16x16x32_bf16 v[80:83], v[202:205], v[226:229], v[80:83]
	v_mfma_f32_16x16x32_bf16 v[68:71], v[194:197], v[234:237], v[68:71]
	v_mfma_f32_16x16x32_bf16 v[64:67], v[202:205], v[234:237], v[64:67]
	s_barrier
	v_add_u32_e32 v165, 0x10000, v162
	ds_read_b128 v[190:193], v165
	ds_read_b128 v[194:197], v165 offset:1024
	ds_read_b128 v[198:201], v165 offset:2048
	ds_read_b128 v[202:205], v165 offset:3072
	ds_read_b128 v[206:209], v164 offset:16384
	ds_read_b128 v[210:213], v164 offset:17408
	ds_read_b128 v[214:217], v164 offset:18432
	ds_read_b128 v[218:221], v164 offset:19456
	ds_read_b128 v[222:225], v164 offset:20480
	ds_read_b128 v[226:229], v164 offset:21504
	ds_read_b128 v[230:233], v164 offset:22528
	ds_read_b128 v[234:237], v164 offset:23552
	s_waitcnt vmcnt(0)
	s_waitcnt lgkmcnt(0)
	s_barrier
	v_mfma_f32_16x16x32_bf16 v[116:119], v[190:193], v[206:209], v[116:119]
	v_mfma_f32_16x16x32_bf16 v[112:115], v[198:201], v[206:209], v[112:115]
	v_mfma_f32_16x16x32_bf16 v[100:103], v[190:193], v[214:217], v[100:103]
	v_mfma_f32_16x16x32_bf16 v[96:99], v[198:201], v[214:217], v[96:99]
	v_mfma_f32_16x16x32_bf16 v[84:87], v[190:193], v[222:225], v[84:87]
	v_mfma_f32_16x16x32_bf16 v[80:83], v[198:201], v[222:225], v[80:83]
	v_mfma_f32_16x16x32_bf16 v[68:71], v[190:193], v[230:233], v[68:71]
	v_mfma_f32_16x16x32_bf16 v[64:67], v[198:201], v[230:233], v[64:67]
	v_mfma_f32_16x16x32_bf16 v[116:119], v[194:197], v[210:213], v[116:119]
	v_mfma_f32_16x16x32_bf16 v[112:115], v[202:205], v[210:213], v[112:115]
	v_mfma_f32_16x16x32_bf16 v[100:103], v[194:197], v[218:221], v[100:103]
	v_mfma_f32_16x16x32_bf16 v[96:99], v[202:205], v[218:221], v[96:99]
	v_mfma_f32_16x16x32_bf16 v[84:87], v[194:197], v[226:229], v[84:87]
	v_mfma_f32_16x16x32_bf16 v[80:83], v[202:205], v[226:229], v[80:83]
	v_mfma_f32_16x16x32_bf16 v[68:71], v[194:197], v[234:237], v[68:71]
	v_mfma_f32_16x16x32_bf16 v[64:67], v[202:205], v[234:237], v[64:67]
	s_barrier
	v_add_u32_e32 v165, 0x18000, v162
	ds_read_b128 v[190:193], v165
	ds_read_b128 v[194:197], v165 offset:1024
	ds_read_b128 v[198:201], v165 offset:2048
	ds_read_b128 v[202:205], v165 offset:3072
	ds_read_b128 v[206:209], v164 offset:49152
	ds_read_b128 v[210:213], v164 offset:50176
	ds_read_b128 v[214:217], v164 offset:51200
	ds_read_b128 v[218:221], v164 offset:52224
	ds_read_b128 v[222:225], v164 offset:53248
	ds_read_b128 v[226:229], v164 offset:54272
	ds_read_b128 v[230:233], v164 offset:55296
	ds_read_b128 v[234:237], v164 offset:56320
	s_waitcnt lgkmcnt(0)
	s_barrier
	v_mfma_f32_16x16x32_bf16 v[116:119], v[190:193], v[206:209], v[116:119]
	v_mfma_f32_16x16x32_bf16 v[112:115], v[198:201], v[206:209], v[112:115]
	v_mfma_f32_16x16x32_bf16 v[100:103], v[190:193], v[214:217], v[100:103]
	v_mfma_f32_16x16x32_bf16 v[96:99], v[198:201], v[214:217], v[96:99]
	v_mfma_f32_16x16x32_bf16 v[84:87], v[190:193], v[222:225], v[84:87]
	v_mfma_f32_16x16x32_bf16 v[80:83], v[198:201], v[222:225], v[80:83]
	v_mfma_f32_16x16x32_bf16 v[68:71], v[190:193], v[230:233], v[68:71]
	v_mfma_f32_16x16x32_bf16 v[64:67], v[198:201], v[230:233], v[64:67]
	v_mfma_f32_16x16x32_bf16 v[116:119], v[194:197], v[210:213], v[116:119]
	v_mfma_f32_16x16x32_bf16 v[112:115], v[202:205], v[210:213], v[112:115]
	v_mfma_f32_16x16x32_bf16 v[100:103], v[194:197], v[218:221], v[100:103]
	v_mfma_f32_16x16x32_bf16 v[96:99], v[202:205], v[218:221], v[96:99]
	v_mfma_f32_16x16x32_bf16 v[84:87], v[194:197], v[226:229], v[84:87]
	v_mfma_f32_16x16x32_bf16 v[80:83], v[202:205], v[226:229], v[80:83]
	v_mfma_f32_16x16x32_bf16 v[68:71], v[194:197], v[234:237], v[68:71]
	v_mfma_f32_16x16x32_bf16 v[64:67], v[202:205], v[234:237], v[64:67]
	s_barrier
	s_branch .Lq_lin_exit

.Lq_lin_2_k:
	v_add_u32_e32 v165, 0x10000, v162
	ds_read_b128 v[138:141], v165
	ds_read_b128 v[166:169], v165 offset:1024
	ds_read_b128 v[170:173], v165 offset:2048
	ds_read_b128 v[174:177], v165 offset:3072
	ds_read_b128 v[206:209], v164 offset:16384
	ds_read_b128 v[210:213], v164 offset:17408
	ds_read_b128 v[214:217], v164 offset:18432
	ds_read_b128 v[218:221], v164 offset:19456
	ds_read_b128 v[222:225], v164 offset:20480
	ds_read_b128 v[226:229], v164 offset:21504
	ds_read_b128 v[230:233], v164 offset:22528
	ds_read_b128 v[234:237], v164 offset:23552
	v_lshl_add_u64 v[142:143], s[74:75], 0, v[132:133]
	s_add_i32 m0, s5, 0x8000
	v_lshl_add_u64 v[160:161], s[74:75], 0, v[130:131]
	global_load_lds_dwordx4 v[142:143], off
	s_add_i32 m0, s5, 0xa000
	v_lshl_add_u64 v[178:179], s[2:3], 0, v[144:145]
	global_load_lds_dwordx4 v[160:161], off
	s_add_i32 m0, s5, 0x1c000
	v_lshl_add_u64 v[238:239], s[2:3], 0, v[128:129]
	global_load_lds_dwordx4 v[178:179], off
	s_add_i32 m0, s5, 0x1e000
	s_add_u32 s74, s74, 0x80
	s_addc_u32 s75, s75, 0
	global_load_lds_dwordx4 v[238:239], off
	s_add_u32 s2, s2, 0x80
	s_addc_u32 s3, s3, 0
	s_waitcnt vmcnt(8)
	s_waitcnt lgkmcnt(0)
	s_barrier
	v_mfma_f32_16x16x32_bf16 v[60:63], v[138:141], v[206:209], v[60:63]
	v_mfma_f32_16x16x32_bf16 v[56:59], v[170:173], v[206:209], v[56:59]
	v_mfma_f32_16x16x32_bf16 v[44:47], v[138:141], v[214:217], v[44:47]
	v_mfma_f32_16x16x32_bf16 v[40:43], v[170:173], v[214:217], v[40:43]
	v_mfma_f32_16x16x32_bf16 v[28:31], v[138:141], v[222:225], v[28:31]
	v_mfma_f32_16x16x32_bf16 v[24:27], v[170:173], v[222:225], v[24:27]
	v_mfma_f32_16x16x32_bf16 v[12:15], v[138:141], v[230:233], v[12:15]
	v_mfma_f32_16x16x32_bf16 v[8:11], v[170:173], v[230:233], v[8:11]
	v_mfma_f32_16x16x32_bf16 v[60:63], v[166:169], v[210:213], v[60:63]
	v_mfma_f32_16x16x32_bf16 v[56:59], v[174:177], v[210:213], v[56:59]
	v_mfma_f32_16x16x32_bf16 v[44:47], v[166:169], v[218:221], v[44:47]
	v_mfma_f32_16x16x32_bf16 v[40:43], v[174:177], v[218:221], v[40:43]
	v_mfma_f32_16x16x32_bf16 v[28:31], v[166:169], v[226:229], v[28:31]
	v_mfma_f32_16x16x32_bf16 v[24:27], v[174:177], v[226:229], v[24:27]
	v_mfma_f32_16x16x32_bf16 v[12:15], v[166:169], v[234:237], v[12:15]
	v_mfma_f32_16x16x32_bf16 v[8:11], v[174:177], v[234:237], v[8:11]
	s_barrier
	v_add_u32_e32 v165, 0x18000, v162
	ds_read_b128 v[138:141], v165
	ds_read_b128 v[166:169], v165 offset:1024
	ds_read_b128 v[170:173], v165 offset:2048
	ds_read_b128 v[174:177], v165 offset:3072
	ds_read_b128 v[206:209], v164 offset:49152
	ds_read_b128 v[210:213], v164 offset:50176
	ds_read_b128 v[214:217], v164 offset:51200
	ds_read_b128 v[218:221], v164 offset:52224
	ds_read_b128 v[222:225], v164 offset:53248
	ds_read_b128 v[226:229], v164 offset:54272
	ds_read_b128 v[230:233], v164 offset:55296
	ds_read_b128 v[234:237], v164 offset:56320
	v_lshl_add_u64 v[142:143], s[74:75], 0, v[132:133]
	s_add_i32 m0, s5, 0x4000
	v_lshl_add_u64 v[160:161], s[74:75], 0, v[130:131]
	global_load_lds_dwordx4 v[142:143], off
	s_add_i32 m0, s5, 0x6000
	v_lshl_add_u64 v[178:179], s[2:3], 0, v[144:145]
	global_load_lds_dwordx4 v[160:161], off
	s_add_i32 m0, s5, 0x10000
	v_lshl_add_u64 v[238:239], s[2:3], 0, v[128:129]
	global_load_lds_dwordx4 v[178:179], off
	s_add_i32 m0, s5, 0x12000
	s_add_u32 s74, s74, 0x80
	s_addc_u32 s75, s75, 0
	global_load_lds_dwordx4 v[238:239], off
	s_add_u32 s2, s2, 0x80
	s_addc_u32 s3, s3, 0
	s_waitcnt vmcnt(8)
	s_waitcnt lgkmcnt(0)
	s_barrier
	v_mfma_f32_16x16x32_bf16 v[60:63], v[138:141], v[206:209], v[60:63]
	v_mfma_f32_16x16x32_bf16 v[56:59], v[170:173], v[206:209], v[56:59]
	v_mfma_f32_16x16x32_bf16 v[44:47], v[138:141], v[214:217], v[44:47]
	v_mfma_f32_16x16x32_bf16 v[40:43], v[170:173], v[214:217], v[40:43]
	v_mfma_f32_16x16x32_bf16 v[28:31], v[138:141], v[222:225], v[28:31]
	v_mfma_f32_16x16x32_bf16 v[24:27], v[170:173], v[222:225], v[24:27]
	v_mfma_f32_16x16x32_bf16 v[12:15], v[138:141], v[230:233], v[12:15]
	v_mfma_f32_16x16x32_bf16 v[8:11], v[170:173], v[230:233], v[8:11]
	v_mfma_f32_16x16x32_bf16 v[60:63], v[166:169], v[210:213], v[60:63]
	v_mfma_f32_16x16x32_bf16 v[56:59], v[174:177], v[210:213], v[56:59]
	v_mfma_f32_16x16x32_bf16 v[44:47], v[166:169], v[218:221], v[44:47]
	v_mfma_f32_16x16x32_bf16 v[40:43], v[174:177], v[218:221], v[40:43]
	v_mfma_f32_16x16x32_bf16 v[28:31], v[166:169], v[226:229], v[28:31]
	v_mfma_f32_16x16x32_bf16 v[24:27], v[174:177], v[226:229], v[24:27]
	v_mfma_f32_16x16x32_bf16 v[12:15], v[166:169], v[234:237], v[12:15]
	v_mfma_f32_16x16x32_bf16 v[8:11], v[174:177], v[234:237], v[8:11]
	s_barrier
	v_add_u32_e32 v165, 0x14000, v162
	ds_read_b128 v[138:141], v165
	ds_read_b128 v[166:169], v165 offset:1024
	ds_read_b128 v[170:173], v165 offset:2048
	ds_read_b128 v[174:177], v165 offset:3072
	ds_read_b128 v[206:209], v164 offset:0
	ds_read_b128 v[210:213], v164 offset:1024
	ds_read_b128 v[214:217], v164 offset:2048
	ds_read_b128 v[218:221], v164 offset:3072
	ds_read_b128 v[222:225], v164 offset:4096
	ds_read_b128 v[226:229], v164 offset:5120
	ds_read_b128 v[230:233], v164 offset:6144
	ds_read_b128 v[234:237], v164 offset:7168
	v_lshl_add_u64 v[142:143], s[74:75], 0, v[132:133]
	s_add_i32 m0, s5, 0xc000
	v_lshl_add_u64 v[160:161], s[74:75], 0, v[130:131]
	global_load_lds_dwordx4 v[142:143], off
	s_add_i32 m0, s5, 0xe000
	v_lshl_add_u64 v[178:179], s[2:3], 0, v[144:145]
	global_load_lds_dwordx4 v[160:161], off
	s_add_i32 m0, s5, 0x18000
	v_lshl_add_u64 v[238:239], s[2:3], 0, v[128:129]
	global_load_lds_dwordx4 v[178:179], off
	s_add_i32 m0, s5, 0x1a000
	s_add_u32 s74, s74, 0x80
	s_addc_u32 s75, s75, 0
	global_load_lds_dwordx4 v[238:239], off
	s_add_u32 s2, s2, 0x80
	s_addc_u32 s3, s3, 0
	s_waitcnt vmcnt(8)
	s_waitcnt lgkmcnt(0)
	s_barrier
	v_mfma_f32_16x16x32_bf16 v[60:63], v[138:141], v[206:209], v[60:63]
	v_mfma_f32_16x16x32_bf16 v[56:59], v[170:173], v[206:209], v[56:59]
	v_mfma_f32_16x16x32_bf16 v[44:47], v[138:141], v[214:217], v[44:47]
	v_mfma_f32_16x16x32_bf16 v[40:43], v[170:173], v[214:217], v[40:43]
	v_mfma_f32_16x16x32_bf16 v[28:31], v[138:141], v[222:225], v[28:31]
	v_mfma_f32_16x16x32_bf16 v[24:27], v[170:173], v[222:225], v[24:27]
	v_mfma_f32_16x16x32_bf16 v[12:15], v[138:141], v[230:233], v[12:15]
	v_mfma_f32_16x16x32_bf16 v[8:11], v[170:173], v[230:233], v[8:11]
	v_mfma_f32_16x16x32_bf16 v[60:63], v[166:169], v[210:213], v[60:63]
	v_mfma_f32_16x16x32_bf16 v[56:59], v[174:177], v[210:213], v[56:59]
	v_mfma_f32_16x16x32_bf16 v[44:47], v[166:169], v[218:221], v[44:47]
	v_mfma_f32_16x16x32_bf16 v[40:43], v[174:177], v[218:221], v[40:43]
	v_mfma_f32_16x16x32_bf16 v[28:31], v[166:169], v[226:229], v[28:31]
	v_mfma_f32_16x16x32_bf16 v[24:27], v[174:177], v[226:229], v[24:27]
	v_mfma_f32_16x16x32_bf16 v[12:15], v[166:169], v[234:237], v[12:15]
	v_mfma_f32_16x16x32_bf16 v[8:11], v[174:177], v[234:237], v[8:11]
	s_barrier
	v_add_u32_e32 v165, 0x1c000, v162
	ds_read_b128 v[138:141], v165
	ds_read_b128 v[166:169], v165 offset:1024
	ds_read_b128 v[170:173], v165 offset:2048
	ds_read_b128 v[174:177], v165 offset:3072
	ds_read_b128 v[206:209], v164 offset:32768
	ds_read_b128 v[210:213], v164 offset:33792
	ds_read_b128 v[214:217], v164 offset:34816
	ds_read_b128 v[218:221], v164 offset:35840
	ds_read_b128 v[222:225], v164 offset:36864
	ds_read_b128 v[226:229], v164 offset:37888
	ds_read_b128 v[230:233], v164 offset:38912
	ds_read_b128 v[234:237], v164 offset:39936
	v_lshl_add_u64 v[142:143], s[74:75], 0, v[132:133]
	s_add_i32 m0, s5, 0x0
	v_lshl_add_u64 v[160:161], s[74:75], 0, v[130:131]
	global_load_lds_dwordx4 v[142:143], off
	s_add_i32 m0, s5, 0x2000
	v_lshl_add_u64 v[178:179], s[2:3], 0, v[144:145]
	global_load_lds_dwordx4 v[160:161], off
	s_add_i32 m0, s5, 0x14000
	v_lshl_add_u64 v[238:239], s[2:3], 0, v[128:129]
	global_load_lds_dwordx4 v[178:179], off
	s_add_i32 m0, s5, 0x16000
	s_add_u32 s74, s74, 0x80
	s_addc_u32 s75, s75, 0
	global_load_lds_dwordx4 v[238:239], off
	s_add_u32 s2, s2, 0x80
	s_addc_u32 s3, s3, 0
	s_waitcnt vmcnt(8)
	s_waitcnt lgkmcnt(0)
	s_barrier
	v_mfma_f32_16x16x32_bf16 v[60:63], v[138:141], v[206:209], v[60:63]
	v_mfma_f32_16x16x32_bf16 v[56:59], v[170:173], v[206:209], v[56:59]
	v_mfma_f32_16x16x32_bf16 v[44:47], v[138:141], v[214:217], v[44:47]
	v_mfma_f32_16x16x32_bf16 v[40:43], v[170:173], v[214:217], v[40:43]
	v_mfma_f32_16x16x32_bf16 v[28:31], v[138:141], v[222:225], v[28:31]
	v_mfma_f32_16x16x32_bf16 v[24:27], v[170:173], v[222:225], v[24:27]
	v_mfma_f32_16x16x32_bf16 v[12:15], v[138:141], v[230:233], v[12:15]
	v_mfma_f32_16x16x32_bf16 v[8:11], v[170:173], v[230:233], v[8:11]
	v_mfma_f32_16x16x32_bf16 v[60:63], v[166:169], v[210:213], v[60:63]
	v_mfma_f32_16x16x32_bf16 v[56:59], v[174:177], v[210:213], v[56:59]
	v_mfma_f32_16x16x32_bf16 v[44:47], v[166:169], v[218:221], v[44:47]
	v_mfma_f32_16x16x32_bf16 v[40:43], v[174:177], v[218:221], v[40:43]
	v_mfma_f32_16x16x32_bf16 v[28:31], v[166:169], v[226:229], v[28:31]
	v_mfma_f32_16x16x32_bf16 v[24:27], v[174:177], v[226:229], v[24:27]
	v_mfma_f32_16x16x32_bf16 v[12:15], v[166:169], v[234:237], v[12:15]
	v_mfma_f32_16x16x32_bf16 v[8:11], v[174:177], v[234:237], v[8:11]
	s_barrier
	s_add_i32 s8, s8, 1
	s_cmp_lt_u32 s8, 7
	s_cbranch_scc1 .Lq_lin_2_k
	v_add_u32_e32 v165, 0x10000, v162
	ds_read_b128 v[138:141], v165
	ds_read_b128 v[166:169], v165 offset:1024
	ds_read_b128 v[170:173], v165 offset:2048
	ds_read_b128 v[174:177], v165 offset:3072
	ds_read_b128 v[206:209], v164 offset:16384
	ds_read_b128 v[210:213], v164 offset:17408
	ds_read_b128 v[214:217], v164 offset:18432
	ds_read_b128 v[218:221], v164 offset:19456
	ds_read_b128 v[222:225], v164 offset:20480
	ds_read_b128 v[226:229], v164 offset:21504
	ds_read_b128 v[230:233], v164 offset:22528
	ds_read_b128 v[234:237], v164 offset:23552
	v_lshl_add_u64 v[142:143], s[74:75], 0, v[132:133]
	s_add_i32 m0, s5, 0x8000
	v_lshl_add_u64 v[160:161], s[74:75], 0, v[130:131]
	global_load_lds_dwordx4 v[142:143], off
	s_add_i32 m0, s5, 0xa000
	v_lshl_add_u64 v[178:179], s[2:3], 0, v[144:145]
	global_load_lds_dwordx4 v[160:161], off
	s_add_i32 m0, s5, 0x1c000
	v_lshl_add_u64 v[238:239], s[2:3], 0, v[128:129]
	global_load_lds_dwordx4 v[178:179], off
	s_add_i32 m0, s5, 0x1e000
	s_add_u32 s74, s74, 0x80
	s_addc_u32 s75, s75, 0
	global_load_lds_dwordx4 v[238:239], off
	s_add_u32 s2, s2, 0x80
	s_addc_u32 s3, s3, 0
	s_waitcnt vmcnt(8)
	s_waitcnt lgkmcnt(0)
	s_barrier
	v_mfma_f32_16x16x32_bf16 v[60:63], v[138:141], v[206:209], v[60:63]
	v_mfma_f32_16x16x32_bf16 v[56:59], v[170:173], v[206:209], v[56:59]
	v_mfma_f32_16x16x32_bf16 v[44:47], v[138:141], v[214:217], v[44:47]
	v_mfma_f32_16x16x32_bf16 v[40:43], v[170:173], v[214:217], v[40:43]
	v_mfma_f32_16x16x32_bf16 v[28:31], v[138:141], v[222:225], v[28:31]
	v_mfma_f32_16x16x32_bf16 v[24:27], v[170:173], v[222:225], v[24:27]
	v_mfma_f32_16x16x32_bf16 v[12:15], v[138:141], v[230:233], v[12:15]
	v_mfma_f32_16x16x32_bf16 v[8:11], v[170:173], v[230:233], v[8:11]
	v_mfma_f32_16x16x32_bf16 v[60:63], v[166:169], v[210:213], v[60:63]
	v_mfma_f32_16x16x32_bf16 v[56:59], v[174:177], v[210:213], v[56:59]
	v_mfma_f32_16x16x32_bf16 v[44:47], v[166:169], v[218:221], v[44:47]
	v_mfma_f32_16x16x32_bf16 v[40:43], v[174:177], v[218:221], v[40:43]
	v_mfma_f32_16x16x32_bf16 v[28:31], v[166:169], v[226:229], v[28:31]
	v_mfma_f32_16x16x32_bf16 v[24:27], v[174:177], v[226:229], v[24:27]
	v_mfma_f32_16x16x32_bf16 v[12:15], v[166:169], v[234:237], v[12:15]
	v_mfma_f32_16x16x32_bf16 v[8:11], v[174:177], v[234:237], v[8:11]
	s_barrier
	v_add_u32_e32 v165, 0x18000, v162
	ds_read_b128 v[138:141], v165
	ds_read_b128 v[166:169], v165 offset:1024
	ds_read_b128 v[170:173], v165 offset:2048
	ds_read_b128 v[174:177], v165 offset:3072
	ds_read_b128 v[206:209], v164 offset:49152
	ds_read_b128 v[210:213], v164 offset:50176
	ds_read_b128 v[214:217], v164 offset:51200
	ds_read_b128 v[218:221], v164 offset:52224
	ds_read_b128 v[222:225], v164 offset:53248
	ds_read_b128 v[226:229], v164 offset:54272
	ds_read_b128 v[230:233], v164 offset:55296
	ds_read_b128 v[234:237], v164 offset:56320
	s_waitcnt vmcnt(4)
	s_waitcnt lgkmcnt(0)
	s_barrier
	v_mfma_f32_16x16x32_bf16 v[60:63], v[138:141], v[206:209], v[60:63]
	v_mfma_f32_16x16x32_bf16 v[56:59], v[170:173], v[206:209], v[56:59]
	v_mfma_f32_16x16x32_bf16 v[44:47], v[138:141], v[214:217], v[44:47]
	v_mfma_f32_16x16x32_bf16 v[40:43], v[170:173], v[214:217], v[40:43]
	v_mfma_f32_16x16x32_bf16 v[28:31], v[138:141], v[222:225], v[28:31]
	v_mfma_f32_16x16x32_bf16 v[24:27], v[170:173], v[222:225], v[24:27]
	v_mfma_f32_16x16x32_bf16 v[12:15], v[138:141], v[230:233], v[12:15]
	v_mfma_f32_16x16x32_bf16 v[8:11], v[170:173], v[230:233], v[8:11]
	v_mfma_f32_16x16x32_bf16 v[60:63], v[166:169], v[210:213], v[60:63]
	v_mfma_f32_16x16x32_bf16 v[56:59], v[174:177], v[210:213], v[56:59]
	v_mfma_f32_16x16x32_bf16 v[44:47], v[166:169], v[218:221], v[44:47]
	v_mfma_f32_16x16x32_bf16 v[40:43], v[174:177], v[218:221], v[40:43]
	v_mfma_f32_16x16x32_bf16 v[28:31], v[166:169], v[226:229], v[28:31]
	v_mfma_f32_16x16x32_bf16 v[24:27], v[174:177], v[226:229], v[24:27]
	v_mfma_f32_16x16x32_bf16 v[12:15], v[166:169], v[234:237], v[12:15]
	v_mfma_f32_16x16x32_bf16 v[8:11], v[174:177], v[234:237], v[8:11]
	s_barrier
	v_add_u32_e32 v165, 0x14000, v162
	ds_read_b128 v[138:141], v165
	ds_read_b128 v[166:169], v165 offset:1024
	ds_read_b128 v[170:173], v165 offset:2048
	ds_read_b128 v[174:177], v165 offset:3072
	ds_read_b128 v[206:209], v164 offset:0
	ds_read_b128 v[210:213], v164 offset:1024
	ds_read_b128 v[214:217], v164 offset:2048
	ds_read_b128 v[218:221], v164 offset:3072
	ds_read_b128 v[222:225], v164 offset:4096
	ds_read_b128 v[226:229], v164 offset:5120
	ds_read_b128 v[230:233], v164 offset:6144
	ds_read_b128 v[234:237], v164 offset:7168
	s_waitcnt vmcnt(0)
	s_waitcnt lgkmcnt(0)
	s_barrier
	v_mfma_f32_16x16x32_bf16 v[60:63], v[138:141], v[206:209], v[60:63]
	v_mfma_f32_16x16x32_bf16 v[56:59], v[170:173], v[206:209], v[56:59]
	v_mfma_f32_16x16x32_bf16 v[44:47], v[138:141], v[214:217], v[44:47]
	v_mfma_f32_16x16x32_bf16 v[40:43], v[170:173], v[214:217], v[40:43]
	v_mfma_f32_16x16x32_bf16 v[28:31], v[138:141], v[222:225], v[28:31]
	v_mfma_f32_16x16x32_bf16 v[24:27], v[170:173], v[222:225], v[24:27]
	v_mfma_f32_16x16x32_bf16 v[12:15], v[138:141], v[230:233], v[12:15]
	v_mfma_f32_16x16x32_bf16 v[8:11], v[170:173], v[230:233], v[8:11]
	v_mfma_f32_16x16x32_bf16 v[60:63], v[166:169], v[210:213], v[60:63]
	v_mfma_f32_16x16x32_bf16 v[56:59], v[174:177], v[210:213], v[56:59]
	v_mfma_f32_16x16x32_bf16 v[44:47], v[166:169], v[218:221], v[44:47]
	v_mfma_f32_16x16x32_bf16 v[40:43], v[174:177], v[218:221], v[40:43]
	v_mfma_f32_16x16x32_bf16 v[28:31], v[166:169], v[226:229], v[28:31]
	v_mfma_f32_16x16x32_bf16 v[24:27], v[174:177], v[226:229], v[24:27]
	v_mfma_f32_16x16x32_bf16 v[12:15], v[166:169], v[234:237], v[12:15]
	v_mfma_f32_16x16x32_bf16 v[8:11], v[174:177], v[234:237], v[8:11]
	s_barrier
	v_add_u32_e32 v165, 0x1c000, v162
	ds_read_b128 v[138:141], v165
	ds_read_b128 v[166:169], v165 offset:1024
	ds_read_b128 v[170:173], v165 offset:2048
	ds_read_b128 v[174:177], v165 offset:3072
	ds_read_b128 v[206:209], v164 offset:32768
	ds_read_b128 v[210:213], v164 offset:33792
	ds_read_b128 v[214:217], v164 offset:34816
	ds_read_b128 v[218:221], v164 offset:35840
	ds_read_b128 v[222:225], v164 offset:36864
	ds_read_b128 v[226:229], v164 offset:37888
	ds_read_b128 v[230:233], v164 offset:38912
	ds_read_b128 v[234:237], v164 offset:39936
	s_waitcnt lgkmcnt(0)
	s_barrier
	v_mfma_f32_16x16x32_bf16 v[60:63], v[138:141], v[206:209], v[60:63]
	v_mfma_f32_16x16x32_bf16 v[56:59], v[170:173], v[206:209], v[56:59]
	v_mfma_f32_16x16x32_bf16 v[44:47], v[138:141], v[214:217], v[44:47]
	v_mfma_f32_16x16x32_bf16 v[40:43], v[170:173], v[214:217], v[40:43]
	v_mfma_f32_16x16x32_bf16 v[28:31], v[138:141], v[222:225], v[28:31]
	v_mfma_f32_16x16x32_bf16 v[24:27], v[170:173], v[222:225], v[24:27]
	v_mfma_f32_16x16x32_bf16 v[12:15], v[138:141], v[230:233], v[12:15]
	v_mfma_f32_16x16x32_bf16 v[8:11], v[170:173], v[230:233], v[8:11]
	v_mfma_f32_16x16x32_bf16 v[60:63], v[166:169], v[210:213], v[60:63]
	v_mfma_f32_16x16x32_bf16 v[56:59], v[174:177], v[210:213], v[56:59]
	v_mfma_f32_16x16x32_bf16 v[44:47], v[166:169], v[218:221], v[44:47]
	v_mfma_f32_16x16x32_bf16 v[40:43], v[174:177], v[218:221], v[40:43]
	v_mfma_f32_16x16x32_bf16 v[28:31], v[166:169], v[226:229], v[28:31]
	v_mfma_f32_16x16x32_bf16 v[24:27], v[174:177], v[226:229], v[24:27]
	v_mfma_f32_16x16x32_bf16 v[12:15], v[166:169], v[234:237], v[12:15]
	v_mfma_f32_16x16x32_bf16 v[8:11], v[174:177], v[234:237], v[8:11]
	s_barrier
	s_branch .Lq_lin_exit

.Lq_lin_3_k:
	v_add_u32_e32 v165, 0x14000, v162
	ds_read_b128 v[190:193], v165
	ds_read_b128 v[194:197], v165 offset:1024
	ds_read_b128 v[198:201], v165 offset:2048
	ds_read_b128 v[202:205], v165 offset:3072
	ds_read_b128 v[206:209], v164 offset:16384
	ds_read_b128 v[210:213], v164 offset:17408
	ds_read_b128 v[214:217], v164 offset:18432
	ds_read_b128 v[218:221], v164 offset:19456
	ds_read_b128 v[222:225], v164 offset:20480
	ds_read_b128 v[226:229], v164 offset:21504
	ds_read_b128 v[230:233], v164 offset:22528
	ds_read_b128 v[234:237], v164 offset:23552
	v_lshl_add_u64 v[142:143], s[74:75], 0, v[132:133]
	s_add_i32 m0, s5, 0x8000
	v_lshl_add_u64 v[160:161], s[74:75], 0, v[130:131]
	global_load_lds_dwordx4 v[142:143], off
	s_add_i32 m0, s5, 0xa000
	v_lshl_add_u64 v[178:179], s[2:3], 0, v[144:145]
	global_load_lds_dwordx4 v[160:161], off
	s_add_i32 m0, s5, 0x18000
	v_lshl_add_u64 v[238:239], s[2:3], 0, v[128:129]
	global_load_lds_dwordx4 v[178:179], off
	s_add_i32 m0, s5, 0x1a000
	s_add_u32 s74, s74, 0x80
	s_addc_u32 s75, s75, 0
	global_load_lds_dwordx4 v[238:239], off
	s_add_u32 s2, s2, 0x80
	s_addc_u32 s3, s3, 0
	s_waitcnt vmcnt(8)
	s_waitcnt lgkmcnt(0)
	s_barrier
	v_mfma_f32_16x16x32_bf16 v[52:55], v[190:193], v[206:209], v[52:55]
	v_mfma_f32_16x16x32_bf16 v[48:51], v[198:201], v[206:209], v[48:51]
	v_mfma_f32_16x16x32_bf16 v[36:39], v[190:193], v[214:217], v[36:39]
	v_mfma_f32_16x16x32_bf16 v[32:35], v[198:201], v[214:217], v[32:35]
	v_mfma_f32_16x16x32_bf16 v[20:23], v[190:193], v[222:225], v[20:23]
	v_mfma_f32_16x16x32_bf16 v[16:19], v[198:201], v[222:225], v[16:19]
	v_mfma_f32_16x16x32_bf16 v[4:7], v[190:193], v[230:233], v[4:7]
	v_mfma_f32_16x16x32_bf16 v[0:3], v[198:201], v[230:233], v[0:3]
	v_mfma_f32_16x16x32_bf16 v[52:55], v[194:197], v[210:213], v[52:55]
	v_mfma_f32_16x16x32_bf16 v[48:51], v[202:205], v[210:213], v[48:51]
	v_mfma_f32_16x16x32_bf16 v[36:39], v[194:197], v[218:221], v[36:39]
	v_mfma_f32_16x16x32_bf16 v[32:35], v[202:205], v[218:221], v[32:35]
	v_mfma_f32_16x16x32_bf16 v[20:23], v[194:197], v[226:229], v[20:23]
	v_mfma_f32_16x16x32_bf16 v[16:19], v[202:205], v[226:229], v[16:19]
	v_mfma_f32_16x16x32_bf16 v[4:7], v[194:197], v[234:237], v[4:7]
	v_mfma_f32_16x16x32_bf16 v[0:3], v[202:205], v[234:237], v[0:3]
	s_barrier
	v_add_u32_e32 v165, 0x1c000, v162
	ds_read_b128 v[190:193], v165
	ds_read_b128 v[194:197], v165 offset:1024
	ds_read_b128 v[198:201], v165 offset:2048
	ds_read_b128 v[202:205], v165 offset:3072
	ds_read_b128 v[206:209], v164 offset:49152
	ds_read_b128 v[210:213], v164 offset:50176
	ds_read_b128 v[214:217], v164 offset:51200
	ds_read_b128 v[218:221], v164 offset:52224
	ds_read_b128 v[222:225], v164 offset:53248
	ds_read_b128 v[226:229], v164 offset:54272
	ds_read_b128 v[230:233], v164 offset:55296
	ds_read_b128 v[234:237], v164 offset:56320
	v_lshl_add_u64 v[142:143], s[74:75], 0, v[132:133]
	s_add_i32 m0, s5, 0x4000
	v_lshl_add_u64 v[160:161], s[74:75], 0, v[130:131]
	global_load_lds_dwordx4 v[142:143], off
	s_add_i32 m0, s5, 0x6000
	v_lshl_add_u64 v[178:179], s[2:3], 0, v[144:145]
	global_load_lds_dwordx4 v[160:161], off
	s_add_i32 m0, s5, 0x14000
	v_lshl_add_u64 v[238:239], s[2:3], 0, v[128:129]
	global_load_lds_dwordx4 v[178:179], off
	s_add_i32 m0, s5, 0x16000
	s_add_u32 s74, s74, 0x80
	s_addc_u32 s75, s75, 0
	global_load_lds_dwordx4 v[238:239], off
	s_add_u32 s2, s2, 0x80
	s_addc_u32 s3, s3, 0
	s_waitcnt vmcnt(8)
	s_waitcnt lgkmcnt(0)
	s_barrier
	v_mfma_f32_16x16x32_bf16 v[52:55], v[190:193], v[206:209], v[52:55]
	v_mfma_f32_16x16x32_bf16 v[48:51], v[198:201], v[206:209], v[48:51]
	v_mfma_f32_16x16x32_bf16 v[36:39], v[190:193], v[214:217], v[36:39]
	v_mfma_f32_16x16x32_bf16 v[32:35], v[198:201], v[214:217], v[32:35]
	v_mfma_f32_16x16x32_bf16 v[20:23], v[190:193], v[222:225], v[20:23]
	v_mfma_f32_16x16x32_bf16 v[16:19], v[198:201], v[222:225], v[16:19]
	v_mfma_f32_16x16x32_bf16 v[4:7], v[190:193], v[230:233], v[4:7]
	v_mfma_f32_16x16x32_bf16 v[0:3], v[198:201], v[230:233], v[0:3]
	v_mfma_f32_16x16x32_bf16 v[52:55], v[194:197], v[210:213], v[52:55]
	v_mfma_f32_16x16x32_bf16 v[48:51], v[202:205], v[210:213], v[48:51]
	v_mfma_f32_16x16x32_bf16 v[36:39], v[194:197], v[218:221], v[36:39]
	v_mfma_f32_16x16x32_bf16 v[32:35], v[202:205], v[218:221], v[32:35]
	v_mfma_f32_16x16x32_bf16 v[20:23], v[194:197], v[226:229], v[20:23]
	v_mfma_f32_16x16x32_bf16 v[16:19], v[202:205], v[226:229], v[16:19]
	v_mfma_f32_16x16x32_bf16 v[4:7], v[194:197], v[234:237], v[4:7]
	v_mfma_f32_16x16x32_bf16 v[0:3], v[202:205], v[234:237], v[0:3]
	s_barrier
	v_add_u32_e32 v165, 0x10000, v162
	ds_read_b128 v[190:193], v165
	ds_read_b128 v[194:197], v165 offset:1024
	ds_read_b128 v[198:201], v165 offset:2048
	ds_read_b128 v[202:205], v165 offset:3072
	ds_read_b128 v[206:209], v164 offset:0
	ds_read_b128 v[210:213], v164 offset:1024
	ds_read_b128 v[214:217], v164 offset:2048
	ds_read_b128 v[218:221], v164 offset:3072
	ds_read_b128 v[222:225], v164 offset:4096
	ds_read_b128 v[226:229], v164 offset:5120
	ds_read_b128 v[230:233], v164 offset:6144
	ds_read_b128 v[234:237], v164 offset:7168
	v_lshl_add_u64 v[142:143], s[74:75], 0, v[132:133]
	s_add_i32 m0, s5, 0xc000
	v_lshl_add_u64 v[160:161], s[74:75], 0, v[130:131]
	global_load_lds_dwordx4 v[142:143], off
	s_add_i32 m0, s5, 0xe000
	v_lshl_add_u64 v[178:179], s[2:3], 0, v[144:145]
	global_load_lds_dwordx4 v[160:161], off
	s_add_i32 m0, s5, 0x1c000
	v_lshl_add_u64 v[238:239], s[2:3], 0, v[128:129]
	global_load_lds_dwordx4 v[178:179], off
	s_add_i32 m0, s5, 0x1e000
	s_add_u32 s74, s74, 0x80
	s_addc_u32 s75, s75, 0
	global_load_lds_dwordx4 v[238:239], off
	s_add_u32 s2, s2, 0x80
	s_addc_u32 s3, s3, 0
	s_waitcnt vmcnt(8)
	s_waitcnt lgkmcnt(0)
	s_barrier
	v_mfma_f32_16x16x32_bf16 v[52:55], v[190:193], v[206:209], v[52:55]
	v_mfma_f32_16x16x32_bf16 v[48:51], v[198:201], v[206:209], v[48:51]
	v_mfma_f32_16x16x32_bf16 v[36:39], v[190:193], v[214:217], v[36:39]
	v_mfma_f32_16x16x32_bf16 v[32:35], v[198:201], v[214:217], v[32:35]
	v_mfma_f32_16x16x32_bf16 v[20:23], v[190:193], v[222:225], v[20:23]
	v_mfma_f32_16x16x32_bf16 v[16:19], v[198:201], v[222:225], v[16:19]
	v_mfma_f32_16x16x32_bf16 v[4:7], v[190:193], v[230:233], v[4:7]
	v_mfma_f32_16x16x32_bf16 v[0:3], v[198:201], v[230:233], v[0:3]
	v_mfma_f32_16x16x32_bf16 v[52:55], v[194:197], v[210:213], v[52:55]
	v_mfma_f32_16x16x32_bf16 v[48:51], v[202:205], v[210:213], v[48:51]
	v_mfma_f32_16x16x32_bf16 v[36:39], v[194:197], v[218:221], v[36:39]
	v_mfma_f32_16x16x32_bf16 v[32:35], v[202:205], v[218:221], v[32:35]
	v_mfma_f32_16x16x32_bf16 v[20:23], v[194:197], v[226:229], v[20:23]
	v_mfma_f32_16x16x32_bf16 v[16:19], v[202:205], v[226:229], v[16:19]
	v_mfma_f32_16x16x32_bf16 v[4:7], v[194:197], v[234:237], v[4:7]
	v_mfma_f32_16x16x32_bf16 v[0:3], v[202:205], v[234:237], v[0:3]
	s_barrier
	v_add_u32_e32 v165, 0x18000, v162
	ds_read_b128 v[190:193], v165
	ds_read_b128 v[194:197], v165 offset:1024
	ds_read_b128 v[198:201], v165 offset:2048
	ds_read_b128 v[202:205], v165 offset:3072
	ds_read_b128 v[206:209], v164 offset:32768
	ds_read_b128 v[210:213], v164 offset:33792
	ds_read_b128 v[214:217], v164 offset:34816
	ds_read_b128 v[218:221], v164 offset:35840
	ds_read_b128 v[222:225], v164 offset:36864
	ds_read_b128 v[226:229], v164 offset:37888
	ds_read_b128 v[230:233], v164 offset:38912
	ds_read_b128 v[234:237], v164 offset:39936
	v_lshl_add_u64 v[142:143], s[74:75], 0, v[132:133]
	s_add_i32 m0, s5, 0x0
	v_lshl_add_u64 v[160:161], s[74:75], 0, v[130:131]
	global_load_lds_dwordx4 v[142:143], off
	s_add_i32 m0, s5, 0x2000
	v_lshl_add_u64 v[178:179], s[2:3], 0, v[144:145]
	global_load_lds_dwordx4 v[160:161], off
	s_add_i32 m0, s5, 0x10000
	v_lshl_add_u64 v[238:239], s[2:3], 0, v[128:129]
	global_load_lds_dwordx4 v[178:179], off
	s_add_i32 m0, s5, 0x12000
	s_add_u32 s74, s74, 0x80
	s_addc_u32 s75, s75, 0
	global_load_lds_dwordx4 v[238:239], off
	s_add_u32 s2, s2, 0x80
	s_addc_u32 s3, s3, 0
	s_waitcnt vmcnt(8)
	s_waitcnt lgkmcnt(0)
	s_barrier
	v_mfma_f32_16x16x32_bf16 v[52:55], v[190:193], v[206:209], v[52:55]
	v_mfma_f32_16x16x32_bf16 v[48:51], v[198:201], v[206:209], v[48:51]
	v_mfma_f32_16x16x32_bf16 v[36:39], v[190:193], v[214:217], v[36:39]
	v_mfma_f32_16x16x32_bf16 v[32:35], v[198:201], v[214:217], v[32:35]
	v_mfma_f32_16x16x32_bf16 v[20:23], v[190:193], v[222:225], v[20:23]
	v_mfma_f32_16x16x32_bf16 v[16:19], v[198:201], v[222:225], v[16:19]
	v_mfma_f32_16x16x32_bf16 v[4:7], v[190:193], v[230:233], v[4:7]
	v_mfma_f32_16x16x32_bf16 v[0:3], v[198:201], v[230:233], v[0:3]
	v_mfma_f32_16x16x32_bf16 v[52:55], v[194:197], v[210:213], v[52:55]
	v_mfma_f32_16x16x32_bf16 v[48:51], v[202:205], v[210:213], v[48:51]
	v_mfma_f32_16x16x32_bf16 v[36:39], v[194:197], v[218:221], v[36:39]
	v_mfma_f32_16x16x32_bf16 v[32:35], v[202:205], v[218:221], v[32:35]
	v_mfma_f32_16x16x32_bf16 v[20:23], v[194:197], v[226:229], v[20:23]
	v_mfma_f32_16x16x32_bf16 v[16:19], v[202:205], v[226:229], v[16:19]
	v_mfma_f32_16x16x32_bf16 v[4:7], v[194:197], v[234:237], v[4:7]
	v_mfma_f32_16x16x32_bf16 v[0:3], v[202:205], v[234:237], v[0:3]
	s_barrier
	s_add_i32 s8, s8, 1
	s_cmp_lt_u32 s8, 7
	s_cbranch_scc1 .Lq_lin_3_k
	v_add_u32_e32 v165, 0x14000, v162
	ds_read_b128 v[190:193], v165
	ds_read_b128 v[194:197], v165 offset:1024
	ds_read_b128 v[198:201], v165 offset:2048
	ds_read_b128 v[202:205], v165 offset:3072
	ds_read_b128 v[206:209], v164 offset:16384
	ds_read_b128 v[210:213], v164 offset:17408
	ds_read_b128 v[214:217], v164 offset:18432
	ds_read_b128 v[218:221], v164 offset:19456
	ds_read_b128 v[222:225], v164 offset:20480
	ds_read_b128 v[226:229], v164 offset:21504
	ds_read_b128 v[230:233], v164 offset:22528
	ds_read_b128 v[234:237], v164 offset:23552
	v_lshl_add_u64 v[142:143], s[74:75], 0, v[132:133]
	s_add_i32 m0, s5, 0x8000
	v_lshl_add_u64 v[160:161], s[74:75], 0, v[130:131]
	global_load_lds_dwordx4 v[142:143], off
	s_add_i32 m0, s5, 0xa000
	v_lshl_add_u64 v[178:179], s[2:3], 0, v[144:145]
	global_load_lds_dwordx4 v[160:161], off
	s_add_i32 m0, s5, 0x18000
	v_lshl_add_u64 v[238:239], s[2:3], 0, v[128:129]
	global_load_lds_dwordx4 v[178:179], off
	s_add_i32 m0, s5, 0x1a000
	s_add_u32 s74, s74, 0x80
	s_addc_u32 s75, s75, 0
	global_load_lds_dwordx4 v[238:239], off
	s_add_u32 s2, s2, 0x80
	s_addc_u32 s3, s3, 0
	s_waitcnt vmcnt(8)
	s_waitcnt lgkmcnt(0)
	s_barrier
	v_mfma_f32_16x16x32_bf16 v[52:55], v[190:193], v[206:209], v[52:55]
	v_mfma_f32_16x16x32_bf16 v[48:51], v[198:201], v[206:209], v[48:51]
	v_mfma_f32_16x16x32_bf16 v[36:39], v[190:193], v[214:217], v[36:39]
	v_mfma_f32_16x16x32_bf16 v[32:35], v[198:201], v[214:217], v[32:35]
	v_mfma_f32_16x16x32_bf16 v[20:23], v[190:193], v[222:225], v[20:23]
	v_mfma_f32_16x16x32_bf16 v[16:19], v[198:201], v[222:225], v[16:19]
	v_mfma_f32_16x16x32_bf16 v[4:7], v[190:193], v[230:233], v[4:7]
	v_mfma_f32_16x16x32_bf16 v[0:3], v[198:201], v[230:233], v[0:3]
	v_mfma_f32_16x16x32_bf16 v[52:55], v[194:197], v[210:213], v[52:55]
	v_mfma_f32_16x16x32_bf16 v[48:51], v[202:205], v[210:213], v[48:51]
	v_mfma_f32_16x16x32_bf16 v[36:39], v[194:197], v[218:221], v[36:39]
	v_mfma_f32_16x16x32_bf16 v[32:35], v[202:205], v[218:221], v[32:35]
	v_mfma_f32_16x16x32_bf16 v[20:23], v[194:197], v[226:229], v[20:23]
	v_mfma_f32_16x16x32_bf16 v[16:19], v[202:205], v[226:229], v[16:19]
	v_mfma_f32_16x16x32_bf16 v[4:7], v[194:197], v[234:237], v[4:7]
	v_mfma_f32_16x16x32_bf16 v[0:3], v[202:205], v[234:237], v[0:3]
	s_barrier
	v_add_u32_e32 v165, 0x1c000, v162
	ds_read_b128 v[190:193], v165
	ds_read_b128 v[194:197], v165 offset:1024
	ds_read_b128 v[198:201], v165 offset:2048
	ds_read_b128 v[202:205], v165 offset:3072
	ds_read_b128 v[206:209], v164 offset:49152
	ds_read_b128 v[210:213], v164 offset:50176
	ds_read_b128 v[214:217], v164 offset:51200
	ds_read_b128 v[218:221], v164 offset:52224
	ds_read_b128 v[222:225], v164 offset:53248
	ds_read_b128 v[226:229], v164 offset:54272
	ds_read_b128 v[230:233], v164 offset:55296
	ds_read_b128 v[234:237], v164 offset:56320
	s_waitcnt vmcnt(4)
	s_waitcnt lgkmcnt(0)
	s_barrier
	v_mfma_f32_16x16x32_bf16 v[52:55], v[190:193], v[206:209], v[52:55]
	v_mfma_f32_16x16x32_bf16 v[48:51], v[198:201], v[206:209], v[48:51]
	v_mfma_f32_16x16x32_bf16 v[36:39], v[190:193], v[214:217], v[36:39]
	v_mfma_f32_16x16x32_bf16 v[32:35], v[198:201], v[214:217], v[32:35]
	v_mfma_f32_16x16x32_bf16 v[20:23], v[190:193], v[222:225], v[20:23]
	v_mfma_f32_16x16x32_bf16 v[16:19], v[198:201], v[222:225], v[16:19]
	v_mfma_f32_16x16x32_bf16 v[4:7], v[190:193], v[230:233], v[4:7]
	v_mfma_f32_16x16x32_bf16 v[0:3], v[198:201], v[230:233], v[0:3]
	v_mfma_f32_16x16x32_bf16 v[52:55], v[194:197], v[210:213], v[52:55]
	v_mfma_f32_16x16x32_bf16 v[48:51], v[202:205], v[210:213], v[48:51]
	v_mfma_f32_16x16x32_bf16 v[36:39], v[194:197], v[218:221], v[36:39]
	v_mfma_f32_16x16x32_bf16 v[32:35], v[202:205], v[218:221], v[32:35]
	v_mfma_f32_16x16x32_bf16 v[20:23], v[194:197], v[226:229], v[20:23]
	v_mfma_f32_16x16x32_bf16 v[16:19], v[202:205], v[226:229], v[16:19]
	v_mfma_f32_16x16x32_bf16 v[4:7], v[194:197], v[234:237], v[4:7]
	v_mfma_f32_16x16x32_bf16 v[0:3], v[202:205], v[234:237], v[0:3]
	s_barrier
	v_add_u32_e32 v165, 0x10000, v162
	ds_read_b128 v[190:193], v165
	ds_read_b128 v[194:197], v165 offset:1024
	ds_read_b128 v[198:201], v165 offset:2048
	ds_read_b128 v[202:205], v165 offset:3072
	ds_read_b128 v[206:209], v164 offset:0
	ds_read_b128 v[210:213], v164 offset:1024
	ds_read_b128 v[214:217], v164 offset:2048
	ds_read_b128 v[218:221], v164 offset:3072
	ds_read_b128 v[222:225], v164 offset:4096
	ds_read_b128 v[226:229], v164 offset:5120
	ds_read_b128 v[230:233], v164 offset:6144
	ds_read_b128 v[234:237], v164 offset:7168
	s_waitcnt vmcnt(0)
	s_waitcnt lgkmcnt(0)
	s_barrier
	v_mfma_f32_16x16x32_bf16 v[52:55], v[190:193], v[206:209], v[52:55]
	v_mfma_f32_16x16x32_bf16 v[48:51], v[198:201], v[206:209], v[48:51]
	v_mfma_f32_16x16x32_bf16 v[36:39], v[190:193], v[214:217], v[36:39]
	v_mfma_f32_16x16x32_bf16 v[32:35], v[198:201], v[214:217], v[32:35]
	v_mfma_f32_16x16x32_bf16 v[20:23], v[190:193], v[222:225], v[20:23]
	v_mfma_f32_16x16x32_bf16 v[16:19], v[198:201], v[222:225], v[16:19]
	v_mfma_f32_16x16x32_bf16 v[4:7], v[190:193], v[230:233], v[4:7]
	v_mfma_f32_16x16x32_bf16 v[0:3], v[198:201], v[230:233], v[0:3]
	v_mfma_f32_16x16x32_bf16 v[52:55], v[194:197], v[210:213], v[52:55]
	v_mfma_f32_16x16x32_bf16 v[48:51], v[202:205], v[210:213], v[48:51]
	v_mfma_f32_16x16x32_bf16 v[36:39], v[194:197], v[218:221], v[36:39]
	v_mfma_f32_16x16x32_bf16 v[32:35], v[202:205], v[218:221], v[32:35]
	v_mfma_f32_16x16x32_bf16 v[20:23], v[194:197], v[226:229], v[20:23]
	v_mfma_f32_16x16x32_bf16 v[16:19], v[202:205], v[226:229], v[16:19]
	v_mfma_f32_16x16x32_bf16 v[4:7], v[194:197], v[234:237], v[4:7]
	v_mfma_f32_16x16x32_bf16 v[0:3], v[202:205], v[234:237], v[0:3]
	s_barrier
	v_add_u32_e32 v165, 0x18000, v162
	ds_read_b128 v[190:193], v165
	ds_read_b128 v[194:197], v165 offset:1024
	ds_read_b128 v[198:201], v165 offset:2048
	ds_read_b128 v[202:205], v165 offset:3072
	ds_read_b128 v[206:209], v164 offset:32768
	ds_read_b128 v[210:213], v164 offset:33792
	ds_read_b128 v[214:217], v164 offset:34816
	ds_read_b128 v[218:221], v164 offset:35840
	ds_read_b128 v[222:225], v164 offset:36864
	ds_read_b128 v[226:229], v164 offset:37888
	ds_read_b128 v[230:233], v164 offset:38912
	ds_read_b128 v[234:237], v164 offset:39936
	s_waitcnt lgkmcnt(0)
	s_barrier
	v_mfma_f32_16x16x32_bf16 v[52:55], v[190:193], v[206:209], v[52:55]
	v_mfma_f32_16x16x32_bf16 v[48:51], v[198:201], v[206:209], v[48:51]
	v_mfma_f32_16x16x32_bf16 v[36:39], v[190:193], v[214:217], v[36:39]
	v_mfma_f32_16x16x32_bf16 v[32:35], v[198:201], v[214:217], v[32:35]
	v_mfma_f32_16x16x32_bf16 v[20:23], v[190:193], v[222:225], v[20:23]
	v_mfma_f32_16x16x32_bf16 v[16:19], v[198:201], v[222:225], v[16:19]
	v_mfma_f32_16x16x32_bf16 v[4:7], v[190:193], v[230:233], v[4:7]
	v_mfma_f32_16x16x32_bf16 v[0:3], v[198:201], v[230:233], v[0:3]
	v_mfma_f32_16x16x32_bf16 v[52:55], v[194:197], v[210:213], v[52:55]
	v_mfma_f32_16x16x32_bf16 v[48:51], v[202:205], v[210:213], v[48:51]
	v_mfma_f32_16x16x32_bf16 v[36:39], v[194:197], v[218:221], v[36:39]
	v_mfma_f32_16x16x32_bf16 v[32:35], v[202:205], v[218:221], v[32:35]
	v_mfma_f32_16x16x32_bf16 v[20:23], v[194:197], v[226:229], v[20:23]
	v_mfma_f32_16x16x32_bf16 v[16:19], v[202:205], v[226:229], v[16:19]
	v_mfma_f32_16x16x32_bf16 v[4:7], v[194:197], v[234:237], v[4:7]
	v_mfma_f32_16x16x32_bf16 v[0:3], v[202:205], v[234:237], v[0:3]
	s_barrier
	s_branch .Lq_lin_exit

.Lq_lout_0_k:
	v_add_u32_e32 v144, 0x10000, v178
	ds_read_b128 v[28:31], v144
	ds_read_b128 v[32:35], v144 offset:1024
	ds_read_b128 v[40:43], v144 offset:2048
	ds_read_b128 v[44:47], v144 offset:3072
	ds_read_b128 v[200:203], v190 offset:0
	ds_read_b128 v[204:207], v190 offset:1024
	ds_read_b128 v[208:211], v190 offset:2048
	ds_read_b128 v[212:215], v190 offset:3072
	ds_read_b128 v[216:219], v190 offset:4096
	ds_read_b128 v[220:223], v190 offset:5120
	ds_read_b128 v[224:227], v190 offset:6144
	ds_read_b128 v[228:231], v190 offset:7168
	v_lshl_add_u64 v[176:177], s[88:89], 0, v[160:161]
	s_add_i32 m0, s9, 0xc000
	v_lshl_add_u64 v[232:233], s[88:89], 0, v[162:163]
	global_load_lds_dwordx4 v[176:177], off
	s_add_i32 m0, s9, 0xe000
	v_lshl_add_u64 v[234:235], s[82:83], 0, v[160:161]
	global_load_lds_dwordx4 v[232:233], off
	s_add_i32 m0, s9, 0x1c000
	v_lshl_add_u64 v[236:237], s[82:83], 0, v[162:163]
	global_load_lds_dwordx4 v[234:235], off
	s_add_i32 m0, s9, 0x1e000
	s_add_u32 s88, s88, 0x80
	s_addc_u32 s89, s89, 0
	global_load_lds_dwordx4 v[236:237], off
	s_add_u32 s82, s82, 0x80
	s_addc_u32 s83, s83, 0
	s_waitcnt vmcnt(8)
	s_waitcnt lgkmcnt(0)
	s_barrier
	v_mfma_f32_16x16x32_bf16 v[140:143], v[28:31], v[200:203], v[140:143]
	v_mfma_f32_16x16x32_bf16 v[136:139], v[40:43], v[200:203], v[136:139]
	v_mfma_f32_16x16x32_bf16 v[124:127], v[28:31], v[208:211], v[124:127]
	v_mfma_f32_16x16x32_bf16 v[120:123], v[40:43], v[208:211], v[120:123]
	v_mfma_f32_16x16x32_bf16 v[108:111], v[28:31], v[216:219], v[108:111]
	v_mfma_f32_16x16x32_bf16 v[104:107], v[40:43], v[216:219], v[104:107]
	v_mfma_f32_16x16x32_bf16 v[92:95], v[28:31], v[224:227], v[92:95]
	v_mfma_f32_16x16x32_bf16 v[88:91], v[40:43], v[224:227], v[88:91]
	v_mfma_f32_16x16x32_bf16 v[140:143], v[32:35], v[204:207], v[140:143]
	v_mfma_f32_16x16x32_bf16 v[136:139], v[44:47], v[204:207], v[136:139]
	v_mfma_f32_16x16x32_bf16 v[124:127], v[32:35], v[212:215], v[124:127]
	v_mfma_f32_16x16x32_bf16 v[120:123], v[44:47], v[212:215], v[120:123]
	v_mfma_f32_16x16x32_bf16 v[108:111], v[32:35], v[220:223], v[108:111]
	v_mfma_f32_16x16x32_bf16 v[104:107], v[44:47], v[220:223], v[104:107]
	v_mfma_f32_16x16x32_bf16 v[92:95], v[32:35], v[228:231], v[92:95]
	v_mfma_f32_16x16x32_bf16 v[88:91], v[44:47], v[228:231], v[88:91]
	s_barrier
	v_add_u32_e32 v144, 0x18000, v178
	ds_read_b128 v[28:31], v144
	ds_read_b128 v[32:35], v144 offset:1024
	ds_read_b128 v[40:43], v144 offset:2048
	ds_read_b128 v[44:47], v144 offset:3072
	ds_read_b128 v[200:203], v190 offset:32768
	ds_read_b128 v[204:207], v190 offset:33792
	ds_read_b128 v[208:211], v190 offset:34816
	ds_read_b128 v[212:215], v190 offset:35840
	ds_read_b128 v[216:219], v190 offset:36864
	ds_read_b128 v[220:223], v190 offset:37888
	ds_read_b128 v[224:227], v190 offset:38912
	ds_read_b128 v[228:231], v190 offset:39936
	v_lshl_add_u64 v[176:177], s[88:89], 0, v[160:161]
	s_add_i32 m0, s9, 0x0
	v_lshl_add_u64 v[232:233], s[88:89], 0, v[162:163]
	global_load_lds_dwordx4 v[176:177], off
	s_add_i32 m0, s9, 0x2000
	v_lshl_add_u64 v[234:235], s[82:83], 0, v[160:161]
	global_load_lds_dwordx4 v[232:233], off
	s_add_i32 m0, s9, 0x10000
	v_lshl_add_u64 v[236:237], s[82:83], 0, v[162:163]
	global_load_lds_dwordx4 v[234:235], off
	s_add_i32 m0, s9, 0x12000
	s_add_u32 s88, s88, 0x80
	s_addc_u32 s89, s89, 0
	global_load_lds_dwordx4 v[236:237], off
	s_add_u32 s82, s82, 0x80
	s_addc_u32 s83, s83, 0
	s_waitcnt vmcnt(8)
	s_waitcnt lgkmcnt(0)
	s_barrier
	v_mfma_f32_16x16x32_bf16 v[140:143], v[28:31], v[200:203], v[140:143]
	v_mfma_f32_16x16x32_bf16 v[136:139], v[40:43], v[200:203], v[136:139]
	v_mfma_f32_16x16x32_bf16 v[124:127], v[28:31], v[208:211], v[124:127]
	v_mfma_f32_16x16x32_bf16 v[120:123], v[40:43], v[208:211], v[120:123]
	v_mfma_f32_16x16x32_bf16 v[108:111], v[28:31], v[216:219], v[108:111]
	v_mfma_f32_16x16x32_bf16 v[104:107], v[40:43], v[216:219], v[104:107]
	v_mfma_f32_16x16x32_bf16 v[92:95], v[28:31], v[224:227], v[92:95]
	v_mfma_f32_16x16x32_bf16 v[88:91], v[40:43], v[224:227], v[88:91]
	v_mfma_f32_16x16x32_bf16 v[140:143], v[32:35], v[204:207], v[140:143]
	v_mfma_f32_16x16x32_bf16 v[136:139], v[44:47], v[204:207], v[136:139]
	v_mfma_f32_16x16x32_bf16 v[124:127], v[32:35], v[212:215], v[124:127]
	v_mfma_f32_16x16x32_bf16 v[120:123], v[44:47], v[212:215], v[120:123]
	v_mfma_f32_16x16x32_bf16 v[108:111], v[32:35], v[220:223], v[108:111]
	v_mfma_f32_16x16x32_bf16 v[104:107], v[44:47], v[220:223], v[104:107]
	v_mfma_f32_16x16x32_bf16 v[92:95], v[32:35], v[228:231], v[92:95]
	v_mfma_f32_16x16x32_bf16 v[88:91], v[44:47], v[228:231], v[88:91]
	s_barrier
	v_add_u32_e32 v144, 0x14000, v178
	ds_read_b128 v[28:31], v144
	ds_read_b128 v[32:35], v144 offset:1024
	ds_read_b128 v[40:43], v144 offset:2048
	ds_read_b128 v[44:47], v144 offset:3072
	ds_read_b128 v[200:203], v190 offset:16384
	ds_read_b128 v[204:207], v190 offset:17408
	ds_read_b128 v[208:211], v190 offset:18432
	ds_read_b128 v[212:215], v190 offset:19456
	ds_read_b128 v[216:219], v190 offset:20480
	ds_read_b128 v[220:223], v190 offset:21504
	ds_read_b128 v[224:227], v190 offset:22528
	ds_read_b128 v[228:231], v190 offset:23552
	v_lshl_add_u64 v[176:177], s[88:89], 0, v[160:161]
	s_add_i32 m0, s9, 0x8000
	v_lshl_add_u64 v[232:233], s[88:89], 0, v[162:163]
	global_load_lds_dwordx4 v[176:177], off
	s_add_i32 m0, s9, 0xa000
	v_lshl_add_u64 v[234:235], s[82:83], 0, v[160:161]
	global_load_lds_dwordx4 v[232:233], off
	s_add_i32 m0, s9, 0x18000
	v_lshl_add_u64 v[236:237], s[82:83], 0, v[162:163]
	global_load_lds_dwordx4 v[234:235], off
	s_add_i32 m0, s9, 0x1a000
	s_add_u32 s88, s88, 0x80
	s_addc_u32 s89, s89, 0
	global_load_lds_dwordx4 v[236:237], off
	s_add_u32 s82, s82, 0x80
	s_addc_u32 s83, s83, 0
	s_waitcnt vmcnt(8)
	s_waitcnt lgkmcnt(0)
	s_barrier
	v_mfma_f32_16x16x32_bf16 v[140:143], v[28:31], v[200:203], v[140:143]
	v_mfma_f32_16x16x32_bf16 v[136:139], v[40:43], v[200:203], v[136:139]
	v_mfma_f32_16x16x32_bf16 v[124:127], v[28:31], v[208:211], v[124:127]
	v_mfma_f32_16x16x32_bf16 v[120:123], v[40:43], v[208:211], v[120:123]
	v_mfma_f32_16x16x32_bf16 v[108:111], v[28:31], v[216:219], v[108:111]
	v_mfma_f32_16x16x32_bf16 v[104:107], v[40:43], v[216:219], v[104:107]
	v_mfma_f32_16x16x32_bf16 v[92:95], v[28:31], v[224:227], v[92:95]
	v_mfma_f32_16x16x32_bf16 v[88:91], v[40:43], v[224:227], v[88:91]
	v_mfma_f32_16x16x32_bf16 v[140:143], v[32:35], v[204:207], v[140:143]
	v_mfma_f32_16x16x32_bf16 v[136:139], v[44:47], v[204:207], v[136:139]
	v_mfma_f32_16x16x32_bf16 v[124:127], v[32:35], v[212:215], v[124:127]
	v_mfma_f32_16x16x32_bf16 v[120:123], v[44:47], v[212:215], v[120:123]
	v_mfma_f32_16x16x32_bf16 v[108:111], v[32:35], v[220:223], v[108:111]
	v_mfma_f32_16x16x32_bf16 v[104:107], v[44:47], v[220:223], v[104:107]
	v_mfma_f32_16x16x32_bf16 v[92:95], v[32:35], v[228:231], v[92:95]
	v_mfma_f32_16x16x32_bf16 v[88:91], v[44:47], v[228:231], v[88:91]
	s_barrier
	v_add_u32_e32 v144, 0x1c000, v178
	ds_read_b128 v[28:31], v144
	ds_read_b128 v[32:35], v144 offset:1024
	ds_read_b128 v[40:43], v144 offset:2048
	ds_read_b128 v[44:47], v144 offset:3072
	ds_read_b128 v[200:203], v190 offset:49152
	ds_read_b128 v[204:207], v190 offset:50176
	ds_read_b128 v[208:211], v190 offset:51200
	ds_read_b128 v[212:215], v190 offset:52224
	ds_read_b128 v[216:219], v190 offset:53248
	ds_read_b128 v[220:223], v190 offset:54272
	ds_read_b128 v[224:227], v190 offset:55296
	ds_read_b128 v[228:231], v190 offset:56320
	v_lshl_add_u64 v[176:177], s[88:89], 0, v[160:161]
	s_add_i32 m0, s9, 0x4000
	v_lshl_add_u64 v[232:233], s[88:89], 0, v[162:163]
	global_load_lds_dwordx4 v[176:177], off
	s_add_i32 m0, s9, 0x6000
	v_lshl_add_u64 v[234:235], s[82:83], 0, v[160:161]
	global_load_lds_dwordx4 v[232:233], off
	s_add_i32 m0, s9, 0x14000
	v_lshl_add_u64 v[236:237], s[82:83], 0, v[162:163]
	global_load_lds_dwordx4 v[234:235], off
	s_add_i32 m0, s9, 0x16000
	s_add_u32 s88, s88, 0x80
	s_addc_u32 s89, s89, 0
	global_load_lds_dwordx4 v[236:237], off
	s_add_u32 s82, s82, 0x80
	s_addc_u32 s83, s83, 0
	s_waitcnt vmcnt(8)
	s_waitcnt lgkmcnt(0)
	s_barrier
	v_mfma_f32_16x16x32_bf16 v[140:143], v[28:31], v[200:203], v[140:143]
	v_mfma_f32_16x16x32_bf16 v[136:139], v[40:43], v[200:203], v[136:139]
	v_mfma_f32_16x16x32_bf16 v[124:127], v[28:31], v[208:211], v[124:127]
	v_mfma_f32_16x16x32_bf16 v[120:123], v[40:43], v[208:211], v[120:123]
	v_mfma_f32_16x16x32_bf16 v[108:111], v[28:31], v[216:219], v[108:111]
	v_mfma_f32_16x16x32_bf16 v[104:107], v[40:43], v[216:219], v[104:107]
	v_mfma_f32_16x16x32_bf16 v[92:95], v[28:31], v[224:227], v[92:95]
	v_mfma_f32_16x16x32_bf16 v[88:91], v[40:43], v[224:227], v[88:91]
	v_mfma_f32_16x16x32_bf16 v[140:143], v[32:35], v[204:207], v[140:143]
	v_mfma_f32_16x16x32_bf16 v[136:139], v[44:47], v[204:207], v[136:139]
	v_mfma_f32_16x16x32_bf16 v[124:127], v[32:35], v[212:215], v[124:127]
	v_mfma_f32_16x16x32_bf16 v[120:123], v[44:47], v[212:215], v[120:123]
	v_mfma_f32_16x16x32_bf16 v[108:111], v[32:35], v[220:223], v[108:111]
	v_mfma_f32_16x16x32_bf16 v[104:107], v[44:47], v[220:223], v[104:107]
	v_mfma_f32_16x16x32_bf16 v[92:95], v[32:35], v[228:231], v[92:95]
	v_mfma_f32_16x16x32_bf16 v[88:91], v[44:47], v[228:231], v[88:91]
	s_barrier
	s_add_i32 s55, s55, 1
	s_cmp_lt_u32 s55, 7
	s_cbranch_scc1 .Lq_lout_0_k
	v_add_u32_e32 v144, 0x10000, v178
	ds_read_b128 v[28:31], v144
	ds_read_b128 v[32:35], v144 offset:1024
	ds_read_b128 v[40:43], v144 offset:2048
	ds_read_b128 v[44:47], v144 offset:3072
	ds_read_b128 v[200:203], v190 offset:0
	ds_read_b128 v[204:207], v190 offset:1024
	ds_read_b128 v[208:211], v190 offset:2048
	ds_read_b128 v[212:215], v190 offset:3072
	ds_read_b128 v[216:219], v190 offset:4096
	ds_read_b128 v[220:223], v190 offset:5120
	ds_read_b128 v[224:227], v190 offset:6144
	ds_read_b128 v[228:231], v190 offset:7168
	v_lshl_add_u64 v[176:177], s[88:89], 0, v[160:161]
	s_add_i32 m0, s9, 0xc000
	v_lshl_add_u64 v[232:233], s[88:89], 0, v[162:163]
	global_load_lds_dwordx4 v[176:177], off
	s_add_i32 m0, s9, 0xe000
	v_lshl_add_u64 v[234:235], s[82:83], 0, v[160:161]
	global_load_lds_dwordx4 v[232:233], off
	s_add_i32 m0, s9, 0x1c000
	v_lshl_add_u64 v[236:237], s[82:83], 0, v[162:163]
	global_load_lds_dwordx4 v[234:235], off
	s_add_i32 m0, s9, 0x1e000
	s_add_u32 s88, s88, 0x80
	s_addc_u32 s89, s89, 0
	global_load_lds_dwordx4 v[236:237], off
	s_add_u32 s82, s82, 0x80
	s_addc_u32 s83, s83, 0
	s_waitcnt vmcnt(8)
	s_waitcnt lgkmcnt(0)
	s_barrier
	v_mfma_f32_16x16x32_bf16 v[140:143], v[28:31], v[200:203], v[140:143]
	v_mfma_f32_16x16x32_bf16 v[136:139], v[40:43], v[200:203], v[136:139]
	v_mfma_f32_16x16x32_bf16 v[124:127], v[28:31], v[208:211], v[124:127]
	v_mfma_f32_16x16x32_bf16 v[120:123], v[40:43], v[208:211], v[120:123]
	v_mfma_f32_16x16x32_bf16 v[108:111], v[28:31], v[216:219], v[108:111]
	v_mfma_f32_16x16x32_bf16 v[104:107], v[40:43], v[216:219], v[104:107]
	v_mfma_f32_16x16x32_bf16 v[92:95], v[28:31], v[224:227], v[92:95]
	v_mfma_f32_16x16x32_bf16 v[88:91], v[40:43], v[224:227], v[88:91]
	v_mfma_f32_16x16x32_bf16 v[140:143], v[32:35], v[204:207], v[140:143]
	v_mfma_f32_16x16x32_bf16 v[136:139], v[44:47], v[204:207], v[136:139]
	v_mfma_f32_16x16x32_bf16 v[124:127], v[32:35], v[212:215], v[124:127]
	v_mfma_f32_16x16x32_bf16 v[120:123], v[44:47], v[212:215], v[120:123]
	v_mfma_f32_16x16x32_bf16 v[108:111], v[32:35], v[220:223], v[108:111]
	v_mfma_f32_16x16x32_bf16 v[104:107], v[44:47], v[220:223], v[104:107]
	v_mfma_f32_16x16x32_bf16 v[92:95], v[32:35], v[228:231], v[92:95]
	v_mfma_f32_16x16x32_bf16 v[88:91], v[44:47], v[228:231], v[88:91]
	s_barrier
	v_add_u32_e32 v144, 0x18000, v178
	ds_read_b128 v[28:31], v144
	ds_read_b128 v[32:35], v144 offset:1024
	ds_read_b128 v[40:43], v144 offset:2048
	ds_read_b128 v[44:47], v144 offset:3072
	ds_read_b128 v[200:203], v190 offset:32768
	ds_read_b128 v[204:207], v190 offset:33792
	ds_read_b128 v[208:211], v190 offset:34816
	ds_read_b128 v[212:215], v190 offset:35840
	ds_read_b128 v[216:219], v190 offset:36864
	ds_read_b128 v[220:223], v190 offset:37888
	ds_read_b128 v[224:227], v190 offset:38912
	ds_read_b128 v[228:231], v190 offset:39936
	s_waitcnt vmcnt(4)
	s_waitcnt lgkmcnt(0)
	s_barrier
	v_mfma_f32_16x16x32_bf16 v[140:143], v[28:31], v[200:203], v[140:143]
	v_mfma_f32_16x16x32_bf16 v[136:139], v[40:43], v[200:203], v[136:139]
	v_mfma_f32_16x16x32_bf16 v[124:127], v[28:31], v[208:211], v[124:127]
	v_mfma_f32_16x16x32_bf16 v[120:123], v[40:43], v[208:211], v[120:123]
	v_mfma_f32_16x16x32_bf16 v[108:111], v[28:31], v[216:219], v[108:111]
	v_mfma_f32_16x16x32_bf16 v[104:107], v[40:43], v[216:219], v[104:107]
	v_mfma_f32_16x16x32_bf16 v[92:95], v[28:31], v[224:227], v[92:95]
	v_mfma_f32_16x16x32_bf16 v[88:91], v[40:43], v[224:227], v[88:91]
	v_mfma_f32_16x16x32_bf16 v[140:143], v[32:35], v[204:207], v[140:143]
	v_mfma_f32_16x16x32_bf16 v[136:139], v[44:47], v[204:207], v[136:139]
	v_mfma_f32_16x16x32_bf16 v[124:127], v[32:35], v[212:215], v[124:127]
	v_mfma_f32_16x16x32_bf16 v[120:123], v[44:47], v[212:215], v[120:123]
	v_mfma_f32_16x16x32_bf16 v[108:111], v[32:35], v[220:223], v[108:111]
	v_mfma_f32_16x16x32_bf16 v[104:107], v[44:47], v[220:223], v[104:107]
	v_mfma_f32_16x16x32_bf16 v[92:95], v[32:35], v[228:231], v[92:95]
	v_mfma_f32_16x16x32_bf16 v[88:91], v[44:47], v[228:231], v[88:91]
	s_barrier
	v_add_u32_e32 v144, 0x14000, v178
	ds_read_b128 v[28:31], v144
	ds_read_b128 v[32:35], v144 offset:1024
	ds_read_b128 v[40:43], v144 offset:2048
	ds_read_b128 v[44:47], v144 offset:3072
	ds_read_b128 v[200:203], v190 offset:16384
	ds_read_b128 v[204:207], v190 offset:17408
	ds_read_b128 v[208:211], v190 offset:18432
	ds_read_b128 v[212:215], v190 offset:19456
	ds_read_b128 v[216:219], v190 offset:20480
	ds_read_b128 v[220:223], v190 offset:21504
	ds_read_b128 v[224:227], v190 offset:22528
	ds_read_b128 v[228:231], v190 offset:23552
	s_waitcnt vmcnt(0)
	s_waitcnt lgkmcnt(0)
	s_barrier
	v_mfma_f32_16x16x32_bf16 v[140:143], v[28:31], v[200:203], v[140:143]
	v_mfma_f32_16x16x32_bf16 v[136:139], v[40:43], v[200:203], v[136:139]
	v_mfma_f32_16x16x32_bf16 v[124:127], v[28:31], v[208:211], v[124:127]
	v_mfma_f32_16x16x32_bf16 v[120:123], v[40:43], v[208:211], v[120:123]
	v_mfma_f32_16x16x32_bf16 v[108:111], v[28:31], v[216:219], v[108:111]
	v_mfma_f32_16x16x32_bf16 v[104:107], v[40:43], v[216:219], v[104:107]
	v_mfma_f32_16x16x32_bf16 v[92:95], v[28:31], v[224:227], v[92:95]
	v_mfma_f32_16x16x32_bf16 v[88:91], v[40:43], v[224:227], v[88:91]
	v_mfma_f32_16x16x32_bf16 v[140:143], v[32:35], v[204:207], v[140:143]
	v_mfma_f32_16x16x32_bf16 v[136:139], v[44:47], v[204:207], v[136:139]
	v_mfma_f32_16x16x32_bf16 v[124:127], v[32:35], v[212:215], v[124:127]
	v_mfma_f32_16x16x32_bf16 v[120:123], v[44:47], v[212:215], v[120:123]
	v_mfma_f32_16x16x32_bf16 v[108:111], v[32:35], v[220:223], v[108:111]
	v_mfma_f32_16x16x32_bf16 v[104:107], v[44:47], v[220:223], v[104:107]
	v_mfma_f32_16x16x32_bf16 v[92:95], v[32:35], v[228:231], v[92:95]
	v_mfma_f32_16x16x32_bf16 v[88:91], v[44:47], v[228:231], v[88:91]
	s_barrier
	v_add_u32_e32 v144, 0x1c000, v178
	ds_read_b128 v[28:31], v144
	ds_read_b128 v[32:35], v144 offset:1024
	ds_read_b128 v[40:43], v144 offset:2048
	ds_read_b128 v[44:47], v144 offset:3072
	ds_read_b128 v[200:203], v190 offset:49152
	ds_read_b128 v[204:207], v190 offset:50176
	ds_read_b128 v[208:211], v190 offset:51200
	ds_read_b128 v[212:215], v190 offset:52224
	ds_read_b128 v[216:219], v190 offset:53248
	ds_read_b128 v[220:223], v190 offset:54272
	ds_read_b128 v[224:227], v190 offset:55296
	ds_read_b128 v[228:231], v190 offset:56320
	s_waitcnt lgkmcnt(0)
	s_barrier
	v_mfma_f32_16x16x32_bf16 v[140:143], v[28:31], v[200:203], v[140:143]
	v_mfma_f32_16x16x32_bf16 v[136:139], v[40:43], v[200:203], v[136:139]
	v_mfma_f32_16x16x32_bf16 v[124:127], v[28:31], v[208:211], v[124:127]
	v_mfma_f32_16x16x32_bf16 v[120:123], v[40:43], v[208:211], v[120:123]
	v_mfma_f32_16x16x32_bf16 v[108:111], v[28:31], v[216:219], v[108:111]
	v_mfma_f32_16x16x32_bf16 v[104:107], v[40:43], v[216:219], v[104:107]
	v_mfma_f32_16x16x32_bf16 v[92:95], v[28:31], v[224:227], v[92:95]
	v_mfma_f32_16x16x32_bf16 v[88:91], v[40:43], v[224:227], v[88:91]
	v_mfma_f32_16x16x32_bf16 v[140:143], v[32:35], v[204:207], v[140:143]
	v_mfma_f32_16x16x32_bf16 v[136:139], v[44:47], v[204:207], v[136:139]
	v_mfma_f32_16x16x32_bf16 v[124:127], v[32:35], v[212:215], v[124:127]
	v_mfma_f32_16x16x32_bf16 v[120:123], v[44:47], v[212:215], v[120:123]
	v_mfma_f32_16x16x32_bf16 v[108:111], v[32:35], v[220:223], v[108:111]
	v_mfma_f32_16x16x32_bf16 v[104:107], v[44:47], v[220:223], v[104:107]
	v_mfma_f32_16x16x32_bf16 v[92:95], v[32:35], v[228:231], v[92:95]
	v_mfma_f32_16x16x32_bf16 v[88:91], v[44:47], v[228:231], v[88:91]
	s_barrier
	s_branch .Lq_lout_exit

.Lq_lout_1_k:
	v_add_u32_e32 v144, 0x14000, v178
	ds_read_b128 v[168:171], v144
	ds_read_b128 v[172:175], v144 offset:1024
	ds_read_b128 v[192:195], v144 offset:2048
	ds_read_b128 v[196:199], v144 offset:3072
	ds_read_b128 v[200:203], v190 offset:0
	ds_read_b128 v[204:207], v190 offset:1024
	ds_read_b128 v[208:211], v190 offset:2048
	ds_read_b128 v[212:215], v190 offset:3072
	ds_read_b128 v[216:219], v190 offset:4096
	ds_read_b128 v[220:223], v190 offset:5120
	ds_read_b128 v[224:227], v190 offset:6144
	ds_read_b128 v[228:231], v190 offset:7168
	v_lshl_add_u64 v[176:177], s[88:89], 0, v[160:161]
	s_add_i32 m0, s9, 0xc000
	v_lshl_add_u64 v[232:233], s[88:89], 0, v[162:163]
	global_load_lds_dwordx4 v[176:177], off
	s_add_i32 m0, s9, 0xe000
	v_lshl_add_u64 v[234:235], s[82:83], 0, v[160:161]
	global_load_lds_dwordx4 v[232:233], off
	s_add_i32 m0, s9, 0x18000
	v_lshl_add_u64 v[236:237], s[82:83], 0, v[162:163]
	global_load_lds_dwordx4 v[234:235], off
	s_add_i32 m0, s9, 0x1a000
	s_add_u32 s88, s88, 0x80
	s_addc_u32 s89, s89, 0
	global_load_lds_dwordx4 v[236:237], off
	s_add_u32 s82, s82, 0x80
	s_addc_u32 s83, s83, 0
	s_waitcnt vmcnt(8)
	s_waitcnt lgkmcnt(0)
	s_barrier
	v_mfma_f32_16x16x32_bf16 v[132:135], v[168:171], v[200:203], v[132:135]
	v_mfma_f32_16x16x32_bf16 v[128:131], v[192:195], v[200:203], v[128:131]
	v_mfma_f32_16x16x32_bf16 v[116:119], v[168:171], v[208:211], v[116:119]
	v_mfma_f32_16x16x32_bf16 v[112:115], v[192:195], v[208:211], v[112:115]
	v_mfma_f32_16x16x32_bf16 v[100:103], v[168:171], v[216:219], v[100:103]
	v_mfma_f32_16x16x32_bf16 v[96:99], v[192:195], v[216:219], v[96:99]
	v_mfma_f32_16x16x32_bf16 v[84:87], v[168:171], v[224:227], v[84:87]
	v_mfma_f32_16x16x32_bf16 v[80:83], v[192:195], v[224:227], v[80:83]
	v_mfma_f32_16x16x32_bf16 v[132:135], v[172:175], v[204:207], v[132:135]
	v_mfma_f32_16x16x32_bf16 v[128:131], v[196:199], v[204:207], v[128:131]
	v_mfma_f32_16x16x32_bf16 v[116:119], v[172:175], v[212:215], v[116:119]
	v_mfma_f32_16x16x32_bf16 v[112:115], v[196:199], v[212:215], v[112:115]
	v_mfma_f32_16x16x32_bf16 v[100:103], v[172:175], v[220:223], v[100:103]
	v_mfma_f32_16x16x32_bf16 v[96:99], v[196:199], v[220:223], v[96:99]
	v_mfma_f32_16x16x32_bf16 v[84:87], v[172:175], v[228:231], v[84:87]
	v_mfma_f32_16x16x32_bf16 v[80:83], v[196:199], v[228:231], v[80:83]
	s_barrier
	v_add_u32_e32 v144, 0x1c000, v178
	ds_read_b128 v[168:171], v144
	ds_read_b128 v[172:175], v144 offset:1024
	ds_read_b128 v[192:195], v144 offset:2048
	ds_read_b128 v[196:199], v144 offset:3072
	ds_read_b128 v[200:203], v190 offset:32768
	ds_read_b128 v[204:207], v190 offset:33792
	ds_read_b128 v[208:211], v190 offset:34816
	ds_read_b128 v[212:215], v190 offset:35840
	ds_read_b128 v[216:219], v190 offset:36864
	ds_read_b128 v[220:223], v190 offset:37888
	ds_read_b128 v[224:227], v190 offset:38912
	ds_read_b128 v[228:231], v190 offset:39936
	v_lshl_add_u64 v[176:177], s[88:89], 0, v[160:161]
	s_add_i32 m0, s9, 0x0
	v_lshl_add_u64 v[232:233], s[88:89], 0, v[162:163]
	global_load_lds_dwordx4 v[176:177], off
	s_add_i32 m0, s9, 0x2000
	v_lshl_add_u64 v[234:235], s[82:83], 0, v[160:161]
	global_load_lds_dwordx4 v[232:233], off
	s_add_i32 m0, s9, 0x14000
	v_lshl_add_u64 v[236:237], s[82:83], 0, v[162:163]
	global_load_lds_dwordx4 v[234:235], off
	s_add_i32 m0, s9, 0x16000
	s_add_u32 s88, s88, 0x80
	s_addc_u32 s89, s89, 0
	global_load_lds_dwordx4 v[236:237], off
	s_add_u32 s82, s82, 0x80
	s_addc_u32 s83, s83, 0
	s_waitcnt vmcnt(8)
	s_waitcnt lgkmcnt(0)
	s_barrier
	v_mfma_f32_16x16x32_bf16 v[132:135], v[168:171], v[200:203], v[132:135]
	v_mfma_f32_16x16x32_bf16 v[128:131], v[192:195], v[200:203], v[128:131]
	v_mfma_f32_16x16x32_bf16 v[116:119], v[168:171], v[208:211], v[116:119]
	v_mfma_f32_16x16x32_bf16 v[112:115], v[192:195], v[208:211], v[112:115]
	v_mfma_f32_16x16x32_bf16 v[100:103], v[168:171], v[216:219], v[100:103]
	v_mfma_f32_16x16x32_bf16 v[96:99], v[192:195], v[216:219], v[96:99]
	v_mfma_f32_16x16x32_bf16 v[84:87], v[168:171], v[224:227], v[84:87]
	v_mfma_f32_16x16x32_bf16 v[80:83], v[192:195], v[224:227], v[80:83]
	v_mfma_f32_16x16x32_bf16 v[132:135], v[172:175], v[204:207], v[132:135]
	v_mfma_f32_16x16x32_bf16 v[128:131], v[196:199], v[204:207], v[128:131]
	v_mfma_f32_16x16x32_bf16 v[116:119], v[172:175], v[212:215], v[116:119]
	v_mfma_f32_16x16x32_bf16 v[112:115], v[196:199], v[212:215], v[112:115]
	v_mfma_f32_16x16x32_bf16 v[100:103], v[172:175], v[220:223], v[100:103]
	v_mfma_f32_16x16x32_bf16 v[96:99], v[196:199], v[220:223], v[96:99]
	v_mfma_f32_16x16x32_bf16 v[84:87], v[172:175], v[228:231], v[84:87]
	v_mfma_f32_16x16x32_bf16 v[80:83], v[196:199], v[228:231], v[80:83]
	s_barrier
	v_add_u32_e32 v144, 0x10000, v178
	ds_read_b128 v[168:171], v144
	ds_read_b128 v[172:175], v144 offset:1024
	ds_read_b128 v[192:195], v144 offset:2048
	ds_read_b128 v[196:199], v144 offset:3072
	ds_read_b128 v[200:203], v190 offset:16384
	ds_read_b128 v[204:207], v190 offset:17408
	ds_read_b128 v[208:211], v190 offset:18432
	ds_read_b128 v[212:215], v190 offset:19456
	ds_read_b128 v[216:219], v190 offset:20480
	ds_read_b128 v[220:223], v190 offset:21504
	ds_read_b128 v[224:227], v190 offset:22528
	ds_read_b128 v[228:231], v190 offset:23552
	v_lshl_add_u64 v[176:177], s[88:89], 0, v[160:161]
	s_add_i32 m0, s9, 0x8000
	v_lshl_add_u64 v[232:233], s[88:89], 0, v[162:163]
	global_load_lds_dwordx4 v[176:177], off
	s_add_i32 m0, s9, 0xa000
	v_lshl_add_u64 v[234:235], s[82:83], 0, v[160:161]
	global_load_lds_dwordx4 v[232:233], off
	s_add_i32 m0, s9, 0x1c000
	v_lshl_add_u64 v[236:237], s[82:83], 0, v[162:163]
	global_load_lds_dwordx4 v[234:235], off
	s_add_i32 m0, s9, 0x1e000
	s_add_u32 s88, s88, 0x80
	s_addc_u32 s89, s89, 0
	global_load_lds_dwordx4 v[236:237], off
	s_add_u32 s82, s82, 0x80
	s_addc_u32 s83, s83, 0
	s_waitcnt vmcnt(8)
	s_waitcnt lgkmcnt(0)
	s_barrier
	v_mfma_f32_16x16x32_bf16 v[132:135], v[168:171], v[200:203], v[132:135]
	v_mfma_f32_16x16x32_bf16 v[128:131], v[192:195], v[200:203], v[128:131]
	v_mfma_f32_16x16x32_bf16 v[116:119], v[168:171], v[208:211], v[116:119]
	v_mfma_f32_16x16x32_bf16 v[112:115], v[192:195], v[208:211], v[112:115]
	v_mfma_f32_16x16x32_bf16 v[100:103], v[168:171], v[216:219], v[100:103]
	v_mfma_f32_16x16x32_bf16 v[96:99], v[192:195], v[216:219], v[96:99]
	v_mfma_f32_16x16x32_bf16 v[84:87], v[168:171], v[224:227], v[84:87]
	v_mfma_f32_16x16x32_bf16 v[80:83], v[192:195], v[224:227], v[80:83]
	v_mfma_f32_16x16x32_bf16 v[132:135], v[172:175], v[204:207], v[132:135]
	v_mfma_f32_16x16x32_bf16 v[128:131], v[196:199], v[204:207], v[128:131]
	v_mfma_f32_16x16x32_bf16 v[116:119], v[172:175], v[212:215], v[116:119]
	v_mfma_f32_16x16x32_bf16 v[112:115], v[196:199], v[212:215], v[112:115]
	v_mfma_f32_16x16x32_bf16 v[100:103], v[172:175], v[220:223], v[100:103]
	v_mfma_f32_16x16x32_bf16 v[96:99], v[196:199], v[220:223], v[96:99]
	v_mfma_f32_16x16x32_bf16 v[84:87], v[172:175], v[228:231], v[84:87]
	v_mfma_f32_16x16x32_bf16 v[80:83], v[196:199], v[228:231], v[80:83]
	s_barrier
	v_add_u32_e32 v144, 0x18000, v178
	ds_read_b128 v[168:171], v144
	ds_read_b128 v[172:175], v144 offset:1024
	ds_read_b128 v[192:195], v144 offset:2048
	ds_read_b128 v[196:199], v144 offset:3072
	ds_read_b128 v[200:203], v190 offset:49152
	ds_read_b128 v[204:207], v190 offset:50176
	ds_read_b128 v[208:211], v190 offset:51200
	ds_read_b128 v[212:215], v190 offset:52224
	ds_read_b128 v[216:219], v190 offset:53248
	ds_read_b128 v[220:223], v190 offset:54272
	ds_read_b128 v[224:227], v190 offset:55296
	ds_read_b128 v[228:231], v190 offset:56320
	v_lshl_add_u64 v[176:177], s[88:89], 0, v[160:161]
	s_add_i32 m0, s9, 0x4000
	v_lshl_add_u64 v[232:233], s[88:89], 0, v[162:163]
	global_load_lds_dwordx4 v[176:177], off
	s_add_i32 m0, s9, 0x6000
	v_lshl_add_u64 v[234:235], s[82:83], 0, v[160:161]
	global_load_lds_dwordx4 v[232:233], off
	s_add_i32 m0, s9, 0x10000
	v_lshl_add_u64 v[236:237], s[82:83], 0, v[162:163]
	global_load_lds_dwordx4 v[234:235], off
	s_add_i32 m0, s9, 0x12000
	s_add_u32 s88, s88, 0x80
	s_addc_u32 s89, s89, 0
	global_load_lds_dwordx4 v[236:237], off
	s_add_u32 s82, s82, 0x80
	s_addc_u32 s83, s83, 0
	s_waitcnt vmcnt(8)
	s_waitcnt lgkmcnt(0)
	s_barrier
	v_mfma_f32_16x16x32_bf16 v[132:135], v[168:171], v[200:203], v[132:135]
	v_mfma_f32_16x16x32_bf16 v[128:131], v[192:195], v[200:203], v[128:131]
	v_mfma_f32_16x16x32_bf16 v[116:119], v[168:171], v[208:211], v[116:119]
	v_mfma_f32_16x16x32_bf16 v[112:115], v[192:195], v[208:211], v[112:115]
	v_mfma_f32_16x16x32_bf16 v[100:103], v[168:171], v[216:219], v[100:103]
	v_mfma_f32_16x16x32_bf16 v[96:99], v[192:195], v[216:219], v[96:99]
	v_mfma_f32_16x16x32_bf16 v[84:87], v[168:171], v[224:227], v[84:87]
	v_mfma_f32_16x16x32_bf16 v[80:83], v[192:195], v[224:227], v[80:83]
	v_mfma_f32_16x16x32_bf16 v[132:135], v[172:175], v[204:207], v[132:135]
	v_mfma_f32_16x16x32_bf16 v[128:131], v[196:199], v[204:207], v[128:131]
	v_mfma_f32_16x16x32_bf16 v[116:119], v[172:175], v[212:215], v[116:119]
	v_mfma_f32_16x16x32_bf16 v[112:115], v[196:199], v[212:215], v[112:115]
	v_mfma_f32_16x16x32_bf16 v[100:103], v[172:175], v[220:223], v[100:103]
	v_mfma_f32_16x16x32_bf16 v[96:99], v[196:199], v[220:223], v[96:99]
	v_mfma_f32_16x16x32_bf16 v[84:87], v[172:175], v[228:231], v[84:87]
	v_mfma_f32_16x16x32_bf16 v[80:83], v[196:199], v[228:231], v[80:83]
	s_barrier
	s_add_i32 s55, s55, 1
	s_cmp_lt_u32 s55, 7
	s_cbranch_scc1 .Lq_lout_1_k
	v_add_u32_e32 v144, 0x14000, v178
	ds_read_b128 v[168:171], v144
	ds_read_b128 v[172:175], v144 offset:1024
	ds_read_b128 v[192:195], v144 offset:2048
	ds_read_b128 v[196:199], v144 offset:3072
	ds_read_b128 v[200:203], v190 offset:0
	ds_read_b128 v[204:207], v190 offset:1024
	ds_read_b128 v[208:211], v190 offset:2048
	ds_read_b128 v[212:215], v190 offset:3072
	ds_read_b128 v[216:219], v190 offset:4096
	ds_read_b128 v[220:223], v190 offset:5120
	ds_read_b128 v[224:227], v190 offset:6144
	ds_read_b128 v[228:231], v190 offset:7168
	v_lshl_add_u64 v[176:177], s[88:89], 0, v[160:161]
	s_add_i32 m0, s9, 0xc000
	v_lshl_add_u64 v[232:233], s[88:89], 0, v[162:163]
	global_load_lds_dwordx4 v[176:177], off
	s_add_i32 m0, s9, 0xe000
	v_lshl_add_u64 v[234:235], s[82:83], 0, v[160:161]
	global_load_lds_dwordx4 v[232:233], off
	s_add_i32 m0, s9, 0x18000
	v_lshl_add_u64 v[236:237], s[82:83], 0, v[162:163]
	global_load_lds_dwordx4 v[234:235], off
	s_add_i32 m0, s9, 0x1a000
	s_add_u32 s88, s88, 0x80
	s_addc_u32 s89, s89, 0
	global_load_lds_dwordx4 v[236:237], off
	s_add_u32 s82, s82, 0x80
	s_addc_u32 s83, s83, 0
	s_waitcnt vmcnt(8)
	s_waitcnt lgkmcnt(0)
	s_barrier
	v_mfma_f32_16x16x32_bf16 v[132:135], v[168:171], v[200:203], v[132:135]
	v_mfma_f32_16x16x32_bf16 v[128:131], v[192:195], v[200:203], v[128:131]
	v_mfma_f32_16x16x32_bf16 v[116:119], v[168:171], v[208:211], v[116:119]
	v_mfma_f32_16x16x32_bf16 v[112:115], v[192:195], v[208:211], v[112:115]
	v_mfma_f32_16x16x32_bf16 v[100:103], v[168:171], v[216:219], v[100:103]
	v_mfma_f32_16x16x32_bf16 v[96:99], v[192:195], v[216:219], v[96:99]
	v_mfma_f32_16x16x32_bf16 v[84:87], v[168:171], v[224:227], v[84:87]
	v_mfma_f32_16x16x32_bf16 v[80:83], v[192:195], v[224:227], v[80:83]
	v_mfma_f32_16x16x32_bf16 v[132:135], v[172:175], v[204:207], v[132:135]
	v_mfma_f32_16x16x32_bf16 v[128:131], v[196:199], v[204:207], v[128:131]
	v_mfma_f32_16x16x32_bf16 v[116:119], v[172:175], v[212:215], v[116:119]
	v_mfma_f32_16x16x32_bf16 v[112:115], v[196:199], v[212:215], v[112:115]
	v_mfma_f32_16x16x32_bf16 v[100:103], v[172:175], v[220:223], v[100:103]
	v_mfma_f32_16x16x32_bf16 v[96:99], v[196:199], v[220:223], v[96:99]
	v_mfma_f32_16x16x32_bf16 v[84:87], v[172:175], v[228:231], v[84:87]
	v_mfma_f32_16x16x32_bf16 v[80:83], v[196:199], v[228:231], v[80:83]
	s_barrier
	v_add_u32_e32 v144, 0x1c000, v178
	ds_read_b128 v[168:171], v144
	ds_read_b128 v[172:175], v144 offset:1024
	ds_read_b128 v[192:195], v144 offset:2048
	ds_read_b128 v[196:199], v144 offset:3072
	ds_read_b128 v[200:203], v190 offset:32768
	ds_read_b128 v[204:207], v190 offset:33792
	ds_read_b128 v[208:211], v190 offset:34816
	ds_read_b128 v[212:215], v190 offset:35840
	ds_read_b128 v[216:219], v190 offset:36864
	ds_read_b128 v[220:223], v190 offset:37888
	ds_read_b128 v[224:227], v190 offset:38912
	ds_read_b128 v[228:231], v190 offset:39936
	s_waitcnt vmcnt(4)
	s_waitcnt lgkmcnt(0)
	s_barrier
	v_mfma_f32_16x16x32_bf16 v[132:135], v[168:171], v[200:203], v[132:135]
	v_mfma_f32_16x16x32_bf16 v[128:131], v[192:195], v[200:203], v[128:131]
	v_mfma_f32_16x16x32_bf16 v[116:119], v[168:171], v[208:211], v[116:119]
	v_mfma_f32_16x16x32_bf16 v[112:115], v[192:195], v[208:211], v[112:115]
	v_mfma_f32_16x16x32_bf16 v[100:103], v[168:171], v[216:219], v[100:103]
	v_mfma_f32_16x16x32_bf16 v[96:99], v[192:195], v[216:219], v[96:99]
	v_mfma_f32_16x16x32_bf16 v[84:87], v[168:171], v[224:227], v[84:87]
	v_mfma_f32_16x16x32_bf16 v[80:83], v[192:195], v[224:227], v[80:83]
	v_mfma_f32_16x16x32_bf16 v[132:135], v[172:175], v[204:207], v[132:135]
	v_mfma_f32_16x16x32_bf16 v[128:131], v[196:199], v[204:207], v[128:131]
	v_mfma_f32_16x16x32_bf16 v[116:119], v[172:175], v[212:215], v[116:119]
	v_mfma_f32_16x16x32_bf16 v[112:115], v[196:199], v[212:215], v[112:115]
	v_mfma_f32_16x16x32_bf16 v[100:103], v[172:175], v[220:223], v[100:103]
	v_mfma_f32_16x16x32_bf16 v[96:99], v[196:199], v[220:223], v[96:99]
	v_mfma_f32_16x16x32_bf16 v[84:87], v[172:175], v[228:231], v[84:87]
	v_mfma_f32_16x16x32_bf16 v[80:83], v[196:199], v[228:231], v[80:83]
	s_barrier
	v_add_u32_e32 v144, 0x10000, v178
	ds_read_b128 v[168:171], v144
	ds_read_b128 v[172:175], v144 offset:1024
	ds_read_b128 v[192:195], v144 offset:2048
	ds_read_b128 v[196:199], v144 offset:3072
	ds_read_b128 v[200:203], v190 offset:16384
	ds_read_b128 v[204:207], v190 offset:17408
	ds_read_b128 v[208:211], v190 offset:18432
	ds_read_b128 v[212:215], v190 offset:19456
	ds_read_b128 v[216:219], v190 offset:20480
	ds_read_b128 v[220:223], v190 offset:21504
	ds_read_b128 v[224:227], v190 offset:22528
	ds_read_b128 v[228:231], v190 offset:23552
	s_waitcnt vmcnt(0)
	s_waitcnt lgkmcnt(0)
	s_barrier
	v_mfma_f32_16x16x32_bf16 v[132:135], v[168:171], v[200:203], v[132:135]
	v_mfma_f32_16x16x32_bf16 v[128:131], v[192:195], v[200:203], v[128:131]
	v_mfma_f32_16x16x32_bf16 v[116:119], v[168:171], v[208:211], v[116:119]
	v_mfma_f32_16x16x32_bf16 v[112:115], v[192:195], v[208:211], v[112:115]
	v_mfma_f32_16x16x32_bf16 v[100:103], v[168:171], v[216:219], v[100:103]
	v_mfma_f32_16x16x32_bf16 v[96:99], v[192:195], v[216:219], v[96:99]
	v_mfma_f32_16x16x32_bf16 v[84:87], v[168:171], v[224:227], v[84:87]
	v_mfma_f32_16x16x32_bf16 v[80:83], v[192:195], v[224:227], v[80:83]
	v_mfma_f32_16x16x32_bf16 v[132:135], v[172:175], v[204:207], v[132:135]
	v_mfma_f32_16x16x32_bf16 v[128:131], v[196:199], v[204:207], v[128:131]
	v_mfma_f32_16x16x32_bf16 v[116:119], v[172:175], v[212:215], v[116:119]
	v_mfma_f32_16x16x32_bf16 v[112:115], v[196:199], v[212:215], v[112:115]
	v_mfma_f32_16x16x32_bf16 v[100:103], v[172:175], v[220:223], v[100:103]
	v_mfma_f32_16x16x32_bf16 v[96:99], v[196:199], v[220:223], v[96:99]
	v_mfma_f32_16x16x32_bf16 v[84:87], v[172:175], v[228:231], v[84:87]
	v_mfma_f32_16x16x32_bf16 v[80:83], v[196:199], v[228:231], v[80:83]
	s_barrier
	v_add_u32_e32 v144, 0x18000, v178
	ds_read_b128 v[168:171], v144
	ds_read_b128 v[172:175], v144 offset:1024
	ds_read_b128 v[192:195], v144 offset:2048
	ds_read_b128 v[196:199], v144 offset:3072
	ds_read_b128 v[200:203], v190 offset:49152
	ds_read_b128 v[204:207], v190 offset:50176
	ds_read_b128 v[208:211], v190 offset:51200
	ds_read_b128 v[212:215], v190 offset:52224
	ds_read_b128 v[216:219], v190 offset:53248
	ds_read_b128 v[220:223], v190 offset:54272
	ds_read_b128 v[224:227], v190 offset:55296
	ds_read_b128 v[228:231], v190 offset:56320
	s_waitcnt lgkmcnt(0)
	s_barrier
	v_mfma_f32_16x16x32_bf16 v[132:135], v[168:171], v[200:203], v[132:135]
	v_mfma_f32_16x16x32_bf16 v[128:131], v[192:195], v[200:203], v[128:131]
	v_mfma_f32_16x16x32_bf16 v[116:119], v[168:171], v[208:211], v[116:119]
	v_mfma_f32_16x16x32_bf16 v[112:115], v[192:195], v[208:211], v[112:115]
	v_mfma_f32_16x16x32_bf16 v[100:103], v[168:171], v[216:219], v[100:103]
	v_mfma_f32_16x16x32_bf16 v[96:99], v[192:195], v[216:219], v[96:99]
	v_mfma_f32_16x16x32_bf16 v[84:87], v[168:171], v[224:227], v[84:87]
	v_mfma_f32_16x16x32_bf16 v[80:83], v[192:195], v[224:227], v[80:83]
	v_mfma_f32_16x16x32_bf16 v[132:135], v[172:175], v[204:207], v[132:135]
	v_mfma_f32_16x16x32_bf16 v[128:131], v[196:199], v[204:207], v[128:131]
	v_mfma_f32_16x16x32_bf16 v[116:119], v[172:175], v[212:215], v[116:119]
	v_mfma_f32_16x16x32_bf16 v[112:115], v[196:199], v[212:215], v[112:115]
	v_mfma_f32_16x16x32_bf16 v[100:103], v[172:175], v[220:223], v[100:103]
	v_mfma_f32_16x16x32_bf16 v[96:99], v[196:199], v[220:223], v[96:99]
	v_mfma_f32_16x16x32_bf16 v[84:87], v[172:175], v[228:231], v[84:87]
	v_mfma_f32_16x16x32_bf16 v[80:83], v[196:199], v[228:231], v[80:83]
	s_barrier
	s_branch .Lq_lout_exit

.Lq_lout_2_k:
	v_add_u32_e32 v144, 0x10000, v178
	ds_read_b128 v[28:31], v144
	ds_read_b128 v[32:35], v144 offset:1024
	ds_read_b128 v[40:43], v144 offset:2048
	ds_read_b128 v[44:47], v144 offset:3072
	ds_read_b128 v[200:203], v190 offset:16384
	ds_read_b128 v[204:207], v190 offset:17408
	ds_read_b128 v[208:211], v190 offset:18432
	ds_read_b128 v[212:215], v190 offset:19456
	ds_read_b128 v[216:219], v190 offset:20480
	ds_read_b128 v[220:223], v190 offset:21504
	ds_read_b128 v[224:227], v190 offset:22528
	ds_read_b128 v[228:231], v190 offset:23552
	v_lshl_add_u64 v[176:177], s[88:89], 0, v[160:161]
	s_add_i32 m0, s9, 0x8000
	v_lshl_add_u64 v[232:233], s[88:89], 0, v[162:163]
	global_load_lds_dwordx4 v[176:177], off
	s_add_i32 m0, s9, 0xa000
	v_lshl_add_u64 v[234:235], s[82:83], 0, v[160:161]
	global_load_lds_dwordx4 v[232:233], off
	s_add_i32 m0, s9, 0x1c000
	v_lshl_add_u64 v[236:237], s[82:83], 0, v[162:163]
	global_load_lds_dwordx4 v[234:235], off
	s_add_i32 m0, s9, 0x1e000
	s_add_u32 s88, s88, 0x80
	s_addc_u32 s89, s89, 0
	global_load_lds_dwordx4 v[236:237], off
	s_add_u32 s82, s82, 0x80
	s_addc_u32 s83, s83, 0
	s_waitcnt vmcnt(8)
	s_waitcnt lgkmcnt(0)
	s_barrier
	v_mfma_f32_16x16x32_bf16 v[76:79], v[28:31], v[200:203], v[76:79]
	v_mfma_f32_16x16x32_bf16 v[72:75], v[40:43], v[200:203], v[72:75]
	v_mfma_f32_16x16x32_bf16 v[60:63], v[28:31], v[208:211], v[60:63]
	v_mfma_f32_16x16x32_bf16 v[56:59], v[40:43], v[208:211], v[56:59]
	v_mfma_f32_16x16x32_bf16 v[36:39], v[28:31], v[216:219], v[36:39]
	v_mfma_f32_16x16x32_bf16 v[24:27], v[40:43], v[216:219], v[24:27]
	v_mfma_f32_16x16x32_bf16 v[12:15], v[28:31], v[224:227], v[12:15]
	v_mfma_f32_16x16x32_bf16 v[8:11], v[40:43], v[224:227], v[8:11]
	v_mfma_f32_16x16x32_bf16 v[76:79], v[32:35], v[204:207], v[76:79]
	v_mfma_f32_16x16x32_bf16 v[72:75], v[44:47], v[204:207], v[72:75]
	v_mfma_f32_16x16x32_bf16 v[60:63], v[32:35], v[212:215], v[60:63]
	v_mfma_f32_16x16x32_bf16 v[56:59], v[44:47], v[212:215], v[56:59]
	v_mfma_f32_16x16x32_bf16 v[36:39], v[32:35], v[220:223], v[36:39]
	v_mfma_f32_16x16x32_bf16 v[24:27], v[44:47], v[220:223], v[24:27]
	v_mfma_f32_16x16x32_bf16 v[12:15], v[32:35], v[228:231], v[12:15]
	v_mfma_f32_16x16x32_bf16 v[8:11], v[44:47], v[228:231], v[8:11]
	s_barrier
	v_add_u32_e32 v144, 0x18000, v178
	ds_read_b128 v[28:31], v144
	ds_read_b128 v[32:35], v144 offset:1024
	ds_read_b128 v[40:43], v144 offset:2048
	ds_read_b128 v[44:47], v144 offset:3072
	ds_read_b128 v[200:203], v190 offset:49152
	ds_read_b128 v[204:207], v190 offset:50176
	ds_read_b128 v[208:211], v190 offset:51200
	ds_read_b128 v[212:215], v190 offset:52224
	ds_read_b128 v[216:219], v190 offset:53248
	ds_read_b128 v[220:223], v190 offset:54272
	ds_read_b128 v[224:227], v190 offset:55296
	ds_read_b128 v[228:231], v190 offset:56320
	v_lshl_add_u64 v[176:177], s[88:89], 0, v[160:161]
	s_add_i32 m0, s9, 0x4000
	v_lshl_add_u64 v[232:233], s[88:89], 0, v[162:163]
	global_load_lds_dwordx4 v[176:177], off
	s_add_i32 m0, s9, 0x6000
	v_lshl_add_u64 v[234:235], s[82:83], 0, v[160:161]
	global_load_lds_dwordx4 v[232:233], off
	s_add_i32 m0, s9, 0x10000
	v_lshl_add_u64 v[236:237], s[82:83], 0, v[162:163]
	global_load_lds_dwordx4 v[234:235], off
	s_add_i32 m0, s9, 0x12000
	s_add_u32 s88, s88, 0x80
	s_addc_u32 s89, s89, 0
	global_load_lds_dwordx4 v[236:237], off
	s_add_u32 s82, s82, 0x80
	s_addc_u32 s83, s83, 0
	s_waitcnt vmcnt(8)
	s_waitcnt lgkmcnt(0)
	s_barrier
	v_mfma_f32_16x16x32_bf16 v[76:79], v[28:31], v[200:203], v[76:79]
	v_mfma_f32_16x16x32_bf16 v[72:75], v[40:43], v[200:203], v[72:75]
	v_mfma_f32_16x16x32_bf16 v[60:63], v[28:31], v[208:211], v[60:63]
	v_mfma_f32_16x16x32_bf16 v[56:59], v[40:43], v[208:211], v[56:59]
	v_mfma_f32_16x16x32_bf16 v[36:39], v[28:31], v[216:219], v[36:39]
	v_mfma_f32_16x16x32_bf16 v[24:27], v[40:43], v[216:219], v[24:27]
	v_mfma_f32_16x16x32_bf16 v[12:15], v[28:31], v[224:227], v[12:15]
	v_mfma_f32_16x16x32_bf16 v[8:11], v[40:43], v[224:227], v[8:11]
	v_mfma_f32_16x16x32_bf16 v[76:79], v[32:35], v[204:207], v[76:79]
	v_mfma_f32_16x16x32_bf16 v[72:75], v[44:47], v[204:207], v[72:75]
	v_mfma_f32_16x16x32_bf16 v[60:63], v[32:35], v[212:215], v[60:63]
	v_mfma_f32_16x16x32_bf16 v[56:59], v[44:47], v[212:215], v[56:59]
	v_mfma_f32_16x16x32_bf16 v[36:39], v[32:35], v[220:223], v[36:39]
	v_mfma_f32_16x16x32_bf16 v[24:27], v[44:47], v[220:223], v[24:27]
	v_mfma_f32_16x16x32_bf16 v[12:15], v[32:35], v[228:231], v[12:15]
	v_mfma_f32_16x16x32_bf16 v[8:11], v[44:47], v[228:231], v[8:11]
	s_barrier
	v_add_u32_e32 v144, 0x14000, v178
	ds_read_b128 v[28:31], v144
	ds_read_b128 v[32:35], v144 offset:1024
	ds_read_b128 v[40:43], v144 offset:2048
	ds_read_b128 v[44:47], v144 offset:3072
	ds_read_b128 v[200:203], v190 offset:0
	ds_read_b128 v[204:207], v190 offset:1024
	ds_read_b128 v[208:211], v190 offset:2048
	ds_read_b128 v[212:215], v190 offset:3072
	ds_read_b128 v[216:219], v190 offset:4096
	ds_read_b128 v[220:223], v190 offset:5120
	ds_read_b128 v[224:227], v190 offset:6144
	ds_read_b128 v[228:231], v190 offset:7168
	v_lshl_add_u64 v[176:177], s[88:89], 0, v[160:161]
	s_add_i32 m0, s9, 0xc000
	v_lshl_add_u64 v[232:233], s[88:89], 0, v[162:163]
	global_load_lds_dwordx4 v[176:177], off
	s_add_i32 m0, s9, 0xe000
	v_lshl_add_u64 v[234:235], s[82:83], 0, v[160:161]
	global_load_lds_dwordx4 v[232:233], off
	s_add_i32 m0, s9, 0x18000
	v_lshl_add_u64 v[236:237], s[82:83], 0, v[162:163]
	global_load_lds_dwordx4 v[234:235], off
	s_add_i32 m0, s9, 0x1a000
	s_add_u32 s88, s88, 0x80
	s_addc_u32 s89, s89, 0
	global_load_lds_dwordx4 v[236:237], off
	s_add_u32 s82, s82, 0x80
	s_addc_u32 s83, s83, 0
	s_waitcnt vmcnt(8)
	s_waitcnt lgkmcnt(0)
	s_barrier
	v_mfma_f32_16x16x32_bf16 v[76:79], v[28:31], v[200:203], v[76:79]
	v_mfma_f32_16x16x32_bf16 v[72:75], v[40:43], v[200:203], v[72:75]
	v_mfma_f32_16x16x32_bf16 v[60:63], v[28:31], v[208:211], v[60:63]
	v_mfma_f32_16x16x32_bf16 v[56:59], v[40:43], v[208:211], v[56:59]
	v_mfma_f32_16x16x32_bf16 v[36:39], v[28:31], v[216:219], v[36:39]
	v_mfma_f32_16x16x32_bf16 v[24:27], v[40:43], v[216:219], v[24:27]
	v_mfma_f32_16x16x32_bf16 v[12:15], v[28:31], v[224:227], v[12:15]
	v_mfma_f32_16x16x32_bf16 v[8:11], v[40:43], v[224:227], v[8:11]
	v_mfma_f32_16x16x32_bf16 v[76:79], v[32:35], v[204:207], v[76:79]
	v_mfma_f32_16x16x32_bf16 v[72:75], v[44:47], v[204:207], v[72:75]
	v_mfma_f32_16x16x32_bf16 v[60:63], v[32:35], v[212:215], v[60:63]
	v_mfma_f32_16x16x32_bf16 v[56:59], v[44:47], v[212:215], v[56:59]
	v_mfma_f32_16x16x32_bf16 v[36:39], v[32:35], v[220:223], v[36:39]
	v_mfma_f32_16x16x32_bf16 v[24:27], v[44:47], v[220:223], v[24:27]
	v_mfma_f32_16x16x32_bf16 v[12:15], v[32:35], v[228:231], v[12:15]
	v_mfma_f32_16x16x32_bf16 v[8:11], v[44:47], v[228:231], v[8:11]
	s_barrier
	v_add_u32_e32 v144, 0x1c000, v178
	ds_read_b128 v[28:31], v144
	ds_read_b128 v[32:35], v144 offset:1024
	ds_read_b128 v[40:43], v144 offset:2048
	ds_read_b128 v[44:47], v144 offset:3072
	ds_read_b128 v[200:203], v190 offset:32768
	ds_read_b128 v[204:207], v190 offset:33792
	ds_read_b128 v[208:211], v190 offset:34816
	ds_read_b128 v[212:215], v190 offset:35840
	ds_read_b128 v[216:219], v190 offset:36864
	ds_read_b128 v[220:223], v190 offset:37888
	ds_read_b128 v[224:227], v190 offset:38912
	ds_read_b128 v[228:231], v190 offset:39936
	v_lshl_add_u64 v[176:177], s[88:89], 0, v[160:161]
	s_add_i32 m0, s9, 0x0
	v_lshl_add_u64 v[232:233], s[88:89], 0, v[162:163]
	global_load_lds_dwordx4 v[176:177], off
	s_add_i32 m0, s9, 0x2000
	v_lshl_add_u64 v[234:235], s[82:83], 0, v[160:161]
	global_load_lds_dwordx4 v[232:233], off
	s_add_i32 m0, s9, 0x14000
	v_lshl_add_u64 v[236:237], s[82:83], 0, v[162:163]
	global_load_lds_dwordx4 v[234:235], off
	s_add_i32 m0, s9, 0x16000
	s_add_u32 s88, s88, 0x80
	s_addc_u32 s89, s89, 0
	global_load_lds_dwordx4 v[236:237], off
	s_add_u32 s82, s82, 0x80
	s_addc_u32 s83, s83, 0
	s_waitcnt vmcnt(8)
	s_waitcnt lgkmcnt(0)
	s_barrier
	v_mfma_f32_16x16x32_bf16 v[76:79], v[28:31], v[200:203], v[76:79]
	v_mfma_f32_16x16x32_bf16 v[72:75], v[40:43], v[200:203], v[72:75]
	v_mfma_f32_16x16x32_bf16 v[60:63], v[28:31], v[208:211], v[60:63]
	v_mfma_f32_16x16x32_bf16 v[56:59], v[40:43], v[208:211], v[56:59]
	v_mfma_f32_16x16x32_bf16 v[36:39], v[28:31], v[216:219], v[36:39]
	v_mfma_f32_16x16x32_bf16 v[24:27], v[40:43], v[216:219], v[24:27]
	v_mfma_f32_16x16x32_bf16 v[12:15], v[28:31], v[224:227], v[12:15]
	v_mfma_f32_16x16x32_bf16 v[8:11], v[40:43], v[224:227], v[8:11]
	v_mfma_f32_16x16x32_bf16 v[76:79], v[32:35], v[204:207], v[76:79]
	v_mfma_f32_16x16x32_bf16 v[72:75], v[44:47], v[204:207], v[72:75]
	v_mfma_f32_16x16x32_bf16 v[60:63], v[32:35], v[212:215], v[60:63]
	v_mfma_f32_16x16x32_bf16 v[56:59], v[44:47], v[212:215], v[56:59]
	v_mfma_f32_16x16x32_bf16 v[36:39], v[32:35], v[220:223], v[36:39]
	v_mfma_f32_16x16x32_bf16 v[24:27], v[44:47], v[220:223], v[24:27]
	v_mfma_f32_16x16x32_bf16 v[12:15], v[32:35], v[228:231], v[12:15]
	v_mfma_f32_16x16x32_bf16 v[8:11], v[44:47], v[228:231], v[8:11]
	s_barrier
	s_add_i32 s55, s55, 1
	s_cmp_lt_u32 s55, 7
	s_cbranch_scc1 .Lq_lout_2_k
	v_add_u32_e32 v144, 0x10000, v178
	ds_read_b128 v[28:31], v144
	ds_read_b128 v[32:35], v144 offset:1024
	ds_read_b128 v[40:43], v144 offset:2048
	ds_read_b128 v[44:47], v144 offset:3072
	ds_read_b128 v[200:203], v190 offset:16384
	ds_read_b128 v[204:207], v190 offset:17408
	ds_read_b128 v[208:211], v190 offset:18432
	ds_read_b128 v[212:215], v190 offset:19456
	ds_read_b128 v[216:219], v190 offset:20480
	ds_read_b128 v[220:223], v190 offset:21504
	ds_read_b128 v[224:227], v190 offset:22528
	ds_read_b128 v[228:231], v190 offset:23552
	v_lshl_add_u64 v[176:177], s[88:89], 0, v[160:161]
	s_add_i32 m0, s9, 0x8000
	v_lshl_add_u64 v[232:233], s[88:89], 0, v[162:163]
	global_load_lds_dwordx4 v[176:177], off
	s_add_i32 m0, s9, 0xa000
	v_lshl_add_u64 v[234:235], s[82:83], 0, v[160:161]
	global_load_lds_dwordx4 v[232:233], off
	s_add_i32 m0, s9, 0x1c000
	v_lshl_add_u64 v[236:237], s[82:83], 0, v[162:163]
	global_load_lds_dwordx4 v[234:235], off
	s_add_i32 m0, s9, 0x1e000
	s_add_u32 s88, s88, 0x80
	s_addc_u32 s89, s89, 0
	global_load_lds_dwordx4 v[236:237], off
	s_add_u32 s82, s82, 0x80
	s_addc_u32 s83, s83, 0
	s_waitcnt vmcnt(8)
	s_waitcnt lgkmcnt(0)
	s_barrier
	v_mfma_f32_16x16x32_bf16 v[76:79], v[28:31], v[200:203], v[76:79]
	v_mfma_f32_16x16x32_bf16 v[72:75], v[40:43], v[200:203], v[72:75]
	v_mfma_f32_16x16x32_bf16 v[60:63], v[28:31], v[208:211], v[60:63]
	v_mfma_f32_16x16x32_bf16 v[56:59], v[40:43], v[208:211], v[56:59]
	v_mfma_f32_16x16x32_bf16 v[36:39], v[28:31], v[216:219], v[36:39]
	v_mfma_f32_16x16x32_bf16 v[24:27], v[40:43], v[216:219], v[24:27]
	v_mfma_f32_16x16x32_bf16 v[12:15], v[28:31], v[224:227], v[12:15]
	v_mfma_f32_16x16x32_bf16 v[8:11], v[40:43], v[224:227], v[8:11]
	v_mfma_f32_16x16x32_bf16 v[76:79], v[32:35], v[204:207], v[76:79]
	v_mfma_f32_16x16x32_bf16 v[72:75], v[44:47], v[204:207], v[72:75]
	v_mfma_f32_16x16x32_bf16 v[60:63], v[32:35], v[212:215], v[60:63]
	v_mfma_f32_16x16x32_bf16 v[56:59], v[44:47], v[212:215], v[56:59]
	v_mfma_f32_16x16x32_bf16 v[36:39], v[32:35], v[220:223], v[36:39]
	v_mfma_f32_16x16x32_bf16 v[24:27], v[44:47], v[220:223], v[24:27]
	v_mfma_f32_16x16x32_bf16 v[12:15], v[32:35], v[228:231], v[12:15]
	v_mfma_f32_16x16x32_bf16 v[8:11], v[44:47], v[228:231], v[8:11]
	s_barrier
	v_add_u32_e32 v144, 0x18000, v178
	ds_read_b128 v[28:31], v144
	ds_read_b128 v[32:35], v144 offset:1024
	ds_read_b128 v[40:43], v144 offset:2048
	ds_read_b128 v[44:47], v144 offset:3072
	ds_read_b128 v[200:203], v190 offset:49152
	ds_read_b128 v[204:207], v190 offset:50176
	ds_read_b128 v[208:211], v190 offset:51200
	ds_read_b128 v[212:215], v190 offset:52224
	ds_read_b128 v[216:219], v190 offset:53248
	ds_read_b128 v[220:223], v190 offset:54272
	ds_read_b128 v[224:227], v190 offset:55296
	ds_read_b128 v[228:231], v190 offset:56320
	s_waitcnt vmcnt(4)
	s_waitcnt lgkmcnt(0)
	s_barrier
	v_mfma_f32_16x16x32_bf16 v[76:79], v[28:31], v[200:203], v[76:79]
	v_mfma_f32_16x16x32_bf16 v[72:75], v[40:43], v[200:203], v[72:75]
	v_mfma_f32_16x16x32_bf16 v[60:63], v[28:31], v[208:211], v[60:63]
	v_mfma_f32_16x16x32_bf16 v[56:59], v[40:43], v[208:211], v[56:59]
	v_mfma_f32_16x16x32_bf16 v[36:39], v[28:31], v[216:219], v[36:39]
	v_mfma_f32_16x16x32_bf16 v[24:27], v[40:43], v[216:219], v[24:27]
	v_mfma_f32_16x16x32_bf16 v[12:15], v[28:31], v[224:227], v[12:15]
	v_mfma_f32_16x16x32_bf16 v[8:11], v[40:43], v[224:227], v[8:11]
	v_mfma_f32_16x16x32_bf16 v[76:79], v[32:35], v[204:207], v[76:79]
	v_mfma_f32_16x16x32_bf16 v[72:75], v[44:47], v[204:207], v[72:75]
	v_mfma_f32_16x16x32_bf16 v[60:63], v[32:35], v[212:215], v[60:63]
	v_mfma_f32_16x16x32_bf16 v[56:59], v[44:47], v[212:215], v[56:59]
	v_mfma_f32_16x16x32_bf16 v[36:39], v[32:35], v[220:223], v[36:39]
	v_mfma_f32_16x16x32_bf16 v[24:27], v[44:47], v[220:223], v[24:27]
	v_mfma_f32_16x16x32_bf16 v[12:15], v[32:35], v[228:231], v[12:15]
	v_mfma_f32_16x16x32_bf16 v[8:11], v[44:47], v[228:231], v[8:11]
	s_barrier
	v_add_u32_e32 v144, 0x14000, v178
	ds_read_b128 v[28:31], v144
	ds_read_b128 v[32:35], v144 offset:1024
	ds_read_b128 v[40:43], v144 offset:2048
	ds_read_b128 v[44:47], v144 offset:3072
	ds_read_b128 v[200:203], v190 offset:0
	ds_read_b128 v[204:207], v190 offset:1024
	ds_read_b128 v[208:211], v190 offset:2048
	ds_read_b128 v[212:215], v190 offset:3072
	ds_read_b128 v[216:219], v190 offset:4096
	ds_read_b128 v[220:223], v190 offset:5120
	ds_read_b128 v[224:227], v190 offset:6144
	ds_read_b128 v[228:231], v190 offset:7168
	s_waitcnt vmcnt(0)
	s_waitcnt lgkmcnt(0)
	s_barrier
	v_mfma_f32_16x16x32_bf16 v[76:79], v[28:31], v[200:203], v[76:79]
	v_mfma_f32_16x16x32_bf16 v[72:75], v[40:43], v[200:203], v[72:75]
	v_mfma_f32_16x16x32_bf16 v[60:63], v[28:31], v[208:211], v[60:63]
	v_mfma_f32_16x16x32_bf16 v[56:59], v[40:43], v[208:211], v[56:59]
	v_mfma_f32_16x16x32_bf16 v[36:39], v[28:31], v[216:219], v[36:39]
	v_mfma_f32_16x16x32_bf16 v[24:27], v[40:43], v[216:219], v[24:27]
	v_mfma_f32_16x16x32_bf16 v[12:15], v[28:31], v[224:227], v[12:15]
	v_mfma_f32_16x16x32_bf16 v[8:11], v[40:43], v[224:227], v[8:11]
	v_mfma_f32_16x16x32_bf16 v[76:79], v[32:35], v[204:207], v[76:79]
	v_mfma_f32_16x16x32_bf16 v[72:75], v[44:47], v[204:207], v[72:75]
	v_mfma_f32_16x16x32_bf16 v[60:63], v[32:35], v[212:215], v[60:63]
	v_mfma_f32_16x16x32_bf16 v[56:59], v[44:47], v[212:215], v[56:59]
	v_mfma_f32_16x16x32_bf16 v[36:39], v[32:35], v[220:223], v[36:39]
	v_mfma_f32_16x16x32_bf16 v[24:27], v[44:47], v[220:223], v[24:27]
	v_mfma_f32_16x16x32_bf16 v[12:15], v[32:35], v[228:231], v[12:15]
	v_mfma_f32_16x16x32_bf16 v[8:11], v[44:47], v[228:231], v[8:11]
	s_barrier
	v_add_u32_e32 v144, 0x1c000, v178
	ds_read_b128 v[28:31], v144
	ds_read_b128 v[32:35], v144 offset:1024
	ds_read_b128 v[40:43], v144 offset:2048
	ds_read_b128 v[44:47], v144 offset:3072
	ds_read_b128 v[200:203], v190 offset:32768
	ds_read_b128 v[204:207], v190 offset:33792
	ds_read_b128 v[208:211], v190 offset:34816
	ds_read_b128 v[212:215], v190 offset:35840
	ds_read_b128 v[216:219], v190 offset:36864
	ds_read_b128 v[220:223], v190 offset:37888
	ds_read_b128 v[224:227], v190 offset:38912
	ds_read_b128 v[228:231], v190 offset:39936
	s_waitcnt lgkmcnt(0)
	s_barrier
	v_mfma_f32_16x16x32_bf16 v[76:79], v[28:31], v[200:203], v[76:79]
	v_mfma_f32_16x16x32_bf16 v[72:75], v[40:43], v[200:203], v[72:75]
	v_mfma_f32_16x16x32_bf16 v[60:63], v[28:31], v[208:211], v[60:63]
	v_mfma_f32_16x16x32_bf16 v[56:59], v[40:43], v[208:211], v[56:59]
	v_mfma_f32_16x16x32_bf16 v[36:39], v[28:31], v[216:219], v[36:39]
	v_mfma_f32_16x16x32_bf16 v[24:27], v[40:43], v[216:219], v[24:27]
	v_mfma_f32_16x16x32_bf16 v[12:15], v[28:31], v[224:227], v[12:15]
	v_mfma_f32_16x16x32_bf16 v[8:11], v[40:43], v[224:227], v[8:11]
	v_mfma_f32_16x16x32_bf16 v[76:79], v[32:35], v[204:207], v[76:79]
	v_mfma_f32_16x16x32_bf16 v[72:75], v[44:47], v[204:207], v[72:75]
	v_mfma_f32_16x16x32_bf16 v[60:63], v[32:35], v[212:215], v[60:63]
	v_mfma_f32_16x16x32_bf16 v[56:59], v[44:47], v[212:215], v[56:59]
	v_mfma_f32_16x16x32_bf16 v[36:39], v[32:35], v[220:223], v[36:39]
	v_mfma_f32_16x16x32_bf16 v[24:27], v[44:47], v[220:223], v[24:27]
	v_mfma_f32_16x16x32_bf16 v[12:15], v[32:35], v[228:231], v[12:15]
	v_mfma_f32_16x16x32_bf16 v[8:11], v[44:47], v[228:231], v[8:11]
	s_barrier
	s_branch .Lq_lout_exit

.Lq_lout_3_k:
	v_add_u32_e32 v144, 0x14000, v178
	ds_read_b128 v[168:171], v144
	ds_read_b128 v[172:175], v144 offset:1024
	ds_read_b128 v[192:195], v144 offset:2048
	ds_read_b128 v[196:199], v144 offset:3072
	ds_read_b128 v[200:203], v190 offset:16384
	ds_read_b128 v[204:207], v190 offset:17408
	ds_read_b128 v[208:211], v190 offset:18432
	ds_read_b128 v[212:215], v190 offset:19456
	ds_read_b128 v[216:219], v190 offset:20480
	ds_read_b128 v[220:223], v190 offset:21504
	ds_read_b128 v[224:227], v190 offset:22528
	ds_read_b128 v[228:231], v190 offset:23552
	v_lshl_add_u64 v[176:177], s[88:89], 0, v[160:161]
	s_add_i32 m0, s9, 0x8000
	v_lshl_add_u64 v[232:233], s[88:89], 0, v[162:163]
	global_load_lds_dwordx4 v[176:177], off
	s_add_i32 m0, s9, 0xa000
	v_lshl_add_u64 v[234:235], s[82:83], 0, v[160:161]
	global_load_lds_dwordx4 v[232:233], off
	s_add_i32 m0, s9, 0x18000
	v_lshl_add_u64 v[236:237], s[82:83], 0, v[162:163]
	global_load_lds_dwordx4 v[234:235], off
	s_add_i32 m0, s9, 0x1a000
	s_add_u32 s88, s88, 0x80
	s_addc_u32 s89, s89, 0
	global_load_lds_dwordx4 v[236:237], off
	s_add_u32 s82, s82, 0x80
	s_addc_u32 s83, s83, 0
	s_waitcnt vmcnt(8)
	s_waitcnt lgkmcnt(0)
	s_barrier
	v_mfma_f32_16x16x32_bf16 v[20:23], v[168:171], v[216:219], v[20:23]
	v_mfma_f32_16x16x32_bf16 v[16:19], v[192:195], v[216:219], v[16:19]
	v_mfma_f32_16x16x32_bf16 v[4:7], v[168:171], v[224:227], v[4:7]
	v_mfma_f32_16x16x32_bf16 v[0:3], v[192:195], v[224:227], v[0:3]
	v_mfma_f32_16x16x32_bf16 v[68:71], v[168:171], v[200:203], v[68:71]
	v_mfma_f32_16x16x32_bf16 v[64:67], v[192:195], v[200:203], v[64:67]
	v_mfma_f32_16x16x32_bf16 v[52:55], v[168:171], v[208:211], v[52:55]
	v_mfma_f32_16x16x32_bf16 v[48:51], v[192:195], v[208:211], v[48:51]
	v_mfma_f32_16x16x32_bf16 v[20:23], v[172:175], v[220:223], v[20:23]
	v_mfma_f32_16x16x32_bf16 v[16:19], v[196:199], v[220:223], v[16:19]
	v_mfma_f32_16x16x32_bf16 v[4:7], v[172:175], v[228:231], v[4:7]
	v_mfma_f32_16x16x32_bf16 v[0:3], v[196:199], v[228:231], v[0:3]
	v_mfma_f32_16x16x32_bf16 v[68:71], v[172:175], v[204:207], v[68:71]
	v_mfma_f32_16x16x32_bf16 v[64:67], v[196:199], v[204:207], v[64:67]
	v_mfma_f32_16x16x32_bf16 v[52:55], v[172:175], v[212:215], v[52:55]
	v_mfma_f32_16x16x32_bf16 v[48:51], v[196:199], v[212:215], v[48:51]
	s_barrier
	v_add_u32_e32 v144, 0x1c000, v178
	ds_read_b128 v[168:171], v144
	ds_read_b128 v[172:175], v144 offset:1024
	ds_read_b128 v[192:195], v144 offset:2048
	ds_read_b128 v[196:199], v144 offset:3072
	ds_read_b128 v[200:203], v190 offset:49152
	ds_read_b128 v[204:207], v190 offset:50176
	ds_read_b128 v[208:211], v190 offset:51200
	ds_read_b128 v[212:215], v190 offset:52224
	ds_read_b128 v[216:219], v190 offset:53248
	ds_read_b128 v[220:223], v190 offset:54272
	ds_read_b128 v[224:227], v190 offset:55296
	ds_read_b128 v[228:231], v190 offset:56320
	v_lshl_add_u64 v[176:177], s[88:89], 0, v[160:161]
	s_add_i32 m0, s9, 0x4000
	v_lshl_add_u64 v[232:233], s[88:89], 0, v[162:163]
	global_load_lds_dwordx4 v[176:177], off
	s_add_i32 m0, s9, 0x6000
	v_lshl_add_u64 v[234:235], s[82:83], 0, v[160:161]
	global_load_lds_dwordx4 v[232:233], off
	s_add_i32 m0, s9, 0x14000
	v_lshl_add_u64 v[236:237], s[82:83], 0, v[162:163]
	global_load_lds_dwordx4 v[234:235], off
	s_add_i32 m0, s9, 0x16000
	s_add_u32 s88, s88, 0x80
	s_addc_u32 s89, s89, 0
	global_load_lds_dwordx4 v[236:237], off
	s_add_u32 s82, s82, 0x80
	s_addc_u32 s83, s83, 0
	s_waitcnt vmcnt(8)
	s_waitcnt lgkmcnt(0)
	s_barrier
	v_mfma_f32_16x16x32_bf16 v[20:23], v[168:171], v[216:219], v[20:23]
	v_mfma_f32_16x16x32_bf16 v[16:19], v[192:195], v[216:219], v[16:19]
	v_mfma_f32_16x16x32_bf16 v[4:7], v[168:171], v[224:227], v[4:7]
	v_mfma_f32_16x16x32_bf16 v[0:3], v[192:195], v[224:227], v[0:3]
	v_mfma_f32_16x16x32_bf16 v[68:71], v[168:171], v[200:203], v[68:71]
	v_mfma_f32_16x16x32_bf16 v[64:67], v[192:195], v[200:203], v[64:67]
	v_mfma_f32_16x16x32_bf16 v[52:55], v[168:171], v[208:211], v[52:55]
	v_mfma_f32_16x16x32_bf16 v[48:51], v[192:195], v[208:211], v[48:51]
	v_mfma_f32_16x16x32_bf16 v[20:23], v[172:175], v[220:223], v[20:23]
	v_mfma_f32_16x16x32_bf16 v[16:19], v[196:199], v[220:223], v[16:19]
	v_mfma_f32_16x16x32_bf16 v[4:7], v[172:175], v[228:231], v[4:7]
	v_mfma_f32_16x16x32_bf16 v[0:3], v[196:199], v[228:231], v[0:3]
	v_mfma_f32_16x16x32_bf16 v[68:71], v[172:175], v[204:207], v[68:71]
	v_mfma_f32_16x16x32_bf16 v[64:67], v[196:199], v[204:207], v[64:67]
	v_mfma_f32_16x16x32_bf16 v[52:55], v[172:175], v[212:215], v[52:55]
	v_mfma_f32_16x16x32_bf16 v[48:51], v[196:199], v[212:215], v[48:51]
	s_barrier
	v_add_u32_e32 v144, 0x10000, v178
	ds_read_b128 v[168:171], v144
	ds_read_b128 v[172:175], v144 offset:1024
	ds_read_b128 v[192:195], v144 offset:2048
	ds_read_b128 v[196:199], v144 offset:3072
	ds_read_b128 v[200:203], v190 offset:0
	ds_read_b128 v[204:207], v190 offset:1024
	ds_read_b128 v[208:211], v190 offset:2048
	ds_read_b128 v[212:215], v190 offset:3072
	ds_read_b128 v[216:219], v190 offset:4096
	ds_read_b128 v[220:223], v190 offset:5120
	ds_read_b128 v[224:227], v190 offset:6144
	ds_read_b128 v[228:231], v190 offset:7168
	v_lshl_add_u64 v[176:177], s[88:89], 0, v[160:161]
	s_add_i32 m0, s9, 0xc000
	v_lshl_add_u64 v[232:233], s[88:89], 0, v[162:163]
	global_load_lds_dwordx4 v[176:177], off
	s_add_i32 m0, s9, 0xe000
	v_lshl_add_u64 v[234:235], s[82:83], 0, v[160:161]
	global_load_lds_dwordx4 v[232:233], off
	s_add_i32 m0, s9, 0x1c000
	v_lshl_add_u64 v[236:237], s[82:83], 0, v[162:163]
	global_load_lds_dwordx4 v[234:235], off
	s_add_i32 m0, s9, 0x1e000
	s_add_u32 s88, s88, 0x80
	s_addc_u32 s89, s89, 0
	global_load_lds_dwordx4 v[236:237], off
	s_add_u32 s82, s82, 0x80
	s_addc_u32 s83, s83, 0
	s_waitcnt vmcnt(8)
	s_waitcnt lgkmcnt(0)
	s_barrier
	v_mfma_f32_16x16x32_bf16 v[20:23], v[168:171], v[216:219], v[20:23]
	v_mfma_f32_16x16x32_bf16 v[16:19], v[192:195], v[216:219], v[16:19]
	v_mfma_f32_16x16x32_bf16 v[4:7], v[168:171], v[224:227], v[4:7]
	v_mfma_f32_16x16x32_bf16 v[0:3], v[192:195], v[224:227], v[0:3]
	v_mfma_f32_16x16x32_bf16 v[68:71], v[168:171], v[200:203], v[68:71]
	v_mfma_f32_16x16x32_bf16 v[64:67], v[192:195], v[200:203], v[64:67]
	v_mfma_f32_16x16x32_bf16 v[52:55], v[168:171], v[208:211], v[52:55]
	v_mfma_f32_16x16x32_bf16 v[48:51], v[192:195], v[208:211], v[48:51]
	v_mfma_f32_16x16x32_bf16 v[20:23], v[172:175], v[220:223], v[20:23]
	v_mfma_f32_16x16x32_bf16 v[16:19], v[196:199], v[220:223], v[16:19]
	v_mfma_f32_16x16x32_bf16 v[4:7], v[172:175], v[228:231], v[4:7]
	v_mfma_f32_16x16x32_bf16 v[0:3], v[196:199], v[228:231], v[0:3]
	v_mfma_f32_16x16x32_bf16 v[68:71], v[172:175], v[204:207], v[68:71]
	v_mfma_f32_16x16x32_bf16 v[64:67], v[196:199], v[204:207], v[64:67]
	v_mfma_f32_16x16x32_bf16 v[52:55], v[172:175], v[212:215], v[52:55]
	v_mfma_f32_16x16x32_bf16 v[48:51], v[196:199], v[212:215], v[48:51]
	s_barrier
	v_add_u32_e32 v144, 0x18000, v178
	ds_read_b128 v[168:171], v144
	ds_read_b128 v[172:175], v144 offset:1024
	ds_read_b128 v[192:195], v144 offset:2048
	ds_read_b128 v[196:199], v144 offset:3072
	ds_read_b128 v[200:203], v190 offset:32768
	ds_read_b128 v[204:207], v190 offset:33792
	ds_read_b128 v[208:211], v190 offset:34816
	ds_read_b128 v[212:215], v190 offset:35840
	ds_read_b128 v[216:219], v190 offset:36864
	ds_read_b128 v[220:223], v190 offset:37888
	ds_read_b128 v[224:227], v190 offset:38912
	ds_read_b128 v[228:231], v190 offset:39936
	v_lshl_add_u64 v[176:177], s[88:89], 0, v[160:161]
	s_add_i32 m0, s9, 0x0
	v_lshl_add_u64 v[232:233], s[88:89], 0, v[162:163]
	global_load_lds_dwordx4 v[176:177], off
	s_add_i32 m0, s9, 0x2000
	v_lshl_add_u64 v[234:235], s[82:83], 0, v[160:161]
	global_load_lds_dwordx4 v[232:233], off
	s_add_i32 m0, s9, 0x10000
	v_lshl_add_u64 v[236:237], s[82:83], 0, v[162:163]
	global_load_lds_dwordx4 v[234:235], off
	s_add_i32 m0, s9, 0x12000
	s_add_u32 s88, s88, 0x80
	s_addc_u32 s89, s89, 0
	global_load_lds_dwordx4 v[236:237], off
	s_add_u32 s82, s82, 0x80
	s_addc_u32 s83, s83, 0
	s_waitcnt vmcnt(8)
	s_waitcnt lgkmcnt(0)
	s_barrier
	v_mfma_f32_16x16x32_bf16 v[20:23], v[168:171], v[216:219], v[20:23]
	v_mfma_f32_16x16x32_bf16 v[16:19], v[192:195], v[216:219], v[16:19]
	v_mfma_f32_16x16x32_bf16 v[4:7], v[168:171], v[224:227], v[4:7]
	v_mfma_f32_16x16x32_bf16 v[0:3], v[192:195], v[224:227], v[0:3]
	v_mfma_f32_16x16x32_bf16 v[68:71], v[168:171], v[200:203], v[68:71]
	v_mfma_f32_16x16x32_bf16 v[64:67], v[192:195], v[200:203], v[64:67]
	v_mfma_f32_16x16x32_bf16 v[52:55], v[168:171], v[208:211], v[52:55]
	v_mfma_f32_16x16x32_bf16 v[48:51], v[192:195], v[208:211], v[48:51]
	v_mfma_f32_16x16x32_bf16 v[20:23], v[172:175], v[220:223], v[20:23]
	v_mfma_f32_16x16x32_bf16 v[16:19], v[196:199], v[220:223], v[16:19]
	v_mfma_f32_16x16x32_bf16 v[4:7], v[172:175], v[228:231], v[4:7]
	v_mfma_f32_16x16x32_bf16 v[0:3], v[196:199], v[228:231], v[0:3]
	v_mfma_f32_16x16x32_bf16 v[68:71], v[172:175], v[204:207], v[68:71]
	v_mfma_f32_16x16x32_bf16 v[64:67], v[196:199], v[204:207], v[64:67]
	v_mfma_f32_16x16x32_bf16 v[52:55], v[172:175], v[212:215], v[52:55]
	v_mfma_f32_16x16x32_bf16 v[48:51], v[196:199], v[212:215], v[48:51]
	s_barrier
	s_add_i32 s55, s55, 1
	s_cmp_lt_u32 s55, 7
	s_cbranch_scc1 .Lq_lout_3_k
	v_add_u32_e32 v144, 0x14000, v178
	ds_read_b128 v[168:171], v144
	ds_read_b128 v[172:175], v144 offset:1024
	ds_read_b128 v[192:195], v144 offset:2048
	ds_read_b128 v[196:199], v144 offset:3072
	ds_read_b128 v[200:203], v190 offset:16384
	ds_read_b128 v[204:207], v190 offset:17408
	ds_read_b128 v[208:211], v190 offset:18432
	ds_read_b128 v[212:215], v190 offset:19456
	ds_read_b128 v[216:219], v190 offset:20480
	ds_read_b128 v[220:223], v190 offset:21504
	ds_read_b128 v[224:227], v190 offset:22528
	ds_read_b128 v[228:231], v190 offset:23552
	v_lshl_add_u64 v[176:177], s[88:89], 0, v[160:161]
	s_add_i32 m0, s9, 0x8000
	v_lshl_add_u64 v[232:233], s[88:89], 0, v[162:163]
	global_load_lds_dwordx4 v[176:177], off
	s_add_i32 m0, s9, 0xa000
	v_lshl_add_u64 v[234:235], s[82:83], 0, v[160:161]
	global_load_lds_dwordx4 v[232:233], off
	s_add_i32 m0, s9, 0x18000
	v_lshl_add_u64 v[236:237], s[82:83], 0, v[162:163]
	global_load_lds_dwordx4 v[234:235], off
	s_add_i32 m0, s9, 0x1a000
	s_add_u32 s88, s88, 0x80
	s_addc_u32 s89, s89, 0
	global_load_lds_dwordx4 v[236:237], off
	s_add_u32 s82, s82, 0x80
	s_addc_u32 s83, s83, 0
	s_waitcnt vmcnt(8)
	s_waitcnt lgkmcnt(0)
	s_barrier
	v_mfma_f32_16x16x32_bf16 v[20:23], v[168:171], v[216:219], v[20:23]
	v_mfma_f32_16x16x32_bf16 v[16:19], v[192:195], v[216:219], v[16:19]
	v_mfma_f32_16x16x32_bf16 v[4:7], v[168:171], v[224:227], v[4:7]
	v_mfma_f32_16x16x32_bf16 v[0:3], v[192:195], v[224:227], v[0:3]
	v_mfma_f32_16x16x32_bf16 v[68:71], v[168:171], v[200:203], v[68:71]
	v_mfma_f32_16x16x32_bf16 v[64:67], v[192:195], v[200:203], v[64:67]
	v_mfma_f32_16x16x32_bf16 v[52:55], v[168:171], v[208:211], v[52:55]
	v_mfma_f32_16x16x32_bf16 v[48:51], v[192:195], v[208:211], v[48:51]
	v_mfma_f32_16x16x32_bf16 v[20:23], v[172:175], v[220:223], v[20:23]
	v_mfma_f32_16x16x32_bf16 v[16:19], v[196:199], v[220:223], v[16:19]
	v_mfma_f32_16x16x32_bf16 v[4:7], v[172:175], v[228:231], v[4:7]
	v_mfma_f32_16x16x32_bf16 v[0:3], v[196:199], v[228:231], v[0:3]
	v_mfma_f32_16x16x32_bf16 v[68:71], v[172:175], v[204:207], v[68:71]
	v_mfma_f32_16x16x32_bf16 v[64:67], v[196:199], v[204:207], v[64:67]
	v_mfma_f32_16x16x32_bf16 v[52:55], v[172:175], v[212:215], v[52:55]
	v_mfma_f32_16x16x32_bf16 v[48:51], v[196:199], v[212:215], v[48:51]
	s_barrier
	v_add_u32_e32 v144, 0x1c000, v178
	ds_read_b128 v[168:171], v144
	ds_read_b128 v[172:175], v144 offset:1024
	ds_read_b128 v[192:195], v144 offset:2048
	ds_read_b128 v[196:199], v144 offset:3072
	ds_read_b128 v[200:203], v190 offset:49152
	ds_read_b128 v[204:207], v190 offset:50176
	ds_read_b128 v[208:211], v190 offset:51200
	ds_read_b128 v[212:215], v190 offset:52224
	ds_read_b128 v[216:219], v190 offset:53248
	ds_read_b128 v[220:223], v190 offset:54272
	ds_read_b128 v[224:227], v190 offset:55296
	ds_read_b128 v[228:231], v190 offset:56320
	s_waitcnt vmcnt(4)
	s_waitcnt lgkmcnt(0)
	s_barrier
	v_mfma_f32_16x16x32_bf16 v[20:23], v[168:171], v[216:219], v[20:23]
	v_mfma_f32_16x16x32_bf16 v[16:19], v[192:195], v[216:219], v[16:19]
	v_mfma_f32_16x16x32_bf16 v[4:7], v[168:171], v[224:227], v[4:7]
	v_mfma_f32_16x16x32_bf16 v[0:3], v[192:195], v[224:227], v[0:3]
	v_mfma_f32_16x16x32_bf16 v[68:71], v[168:171], v[200:203], v[68:71]
	v_mfma_f32_16x16x32_bf16 v[64:67], v[192:195], v[200:203], v[64:67]
	v_mfma_f32_16x16x32_bf16 v[52:55], v[168:171], v[208:211], v[52:55]
	v_mfma_f32_16x16x32_bf16 v[48:51], v[192:195], v[208:211], v[48:51]
	v_mfma_f32_16x16x32_bf16 v[20:23], v[172:175], v[220:223], v[20:23]
	v_mfma_f32_16x16x32_bf16 v[16:19], v[196:199], v[220:223], v[16:19]
	v_mfma_f32_16x16x32_bf16 v[4:7], v[172:175], v[228:231], v[4:7]
	v_mfma_f32_16x16x32_bf16 v[0:3], v[196:199], v[228:231], v[0:3]
	v_mfma_f32_16x16x32_bf16 v[68:71], v[172:175], v[204:207], v[68:71]
	v_mfma_f32_16x16x32_bf16 v[64:67], v[196:199], v[204:207], v[64:67]
	v_mfma_f32_16x16x32_bf16 v[52:55], v[172:175], v[212:215], v[52:55]
	v_mfma_f32_16x16x32_bf16 v[48:51], v[196:199], v[212:215], v[48:51]
	s_barrier
	v_add_u32_e32 v144, 0x10000, v178
	ds_read_b128 v[168:171], v144
	ds_read_b128 v[172:175], v144 offset:1024
	ds_read_b128 v[192:195], v144 offset:2048
	ds_read_b128 v[196:199], v144 offset:3072
	ds_read_b128 v[200:203], v190 offset:0
	ds_read_b128 v[204:207], v190 offset:1024
	ds_read_b128 v[208:211], v190 offset:2048
	ds_read_b128 v[212:215], v190 offset:3072
	ds_read_b128 v[216:219], v190 offset:4096
	ds_read_b128 v[220:223], v190 offset:5120
	ds_read_b128 v[224:227], v190 offset:6144
	ds_read_b128 v[228:231], v190 offset:7168
	s_waitcnt vmcnt(0)
	s_waitcnt lgkmcnt(0)
	s_barrier
	v_mfma_f32_16x16x32_bf16 v[20:23], v[168:171], v[216:219], v[20:23]
	v_mfma_f32_16x16x32_bf16 v[16:19], v[192:195], v[216:219], v[16:19]
	v_mfma_f32_16x16x32_bf16 v[4:7], v[168:171], v[224:227], v[4:7]
	v_mfma_f32_16x16x32_bf16 v[0:3], v[192:195], v[224:227], v[0:3]
	v_mfma_f32_16x16x32_bf16 v[68:71], v[168:171], v[200:203], v[68:71]
	v_mfma_f32_16x16x32_bf16 v[64:67], v[192:195], v[200:203], v[64:67]
	v_mfma_f32_16x16x32_bf16 v[52:55], v[168:171], v[208:211], v[52:55]
	v_mfma_f32_16x16x32_bf16 v[48:51], v[192:195], v[208:211], v[48:51]
	v_mfma_f32_16x16x32_bf16 v[20:23], v[172:175], v[220:223], v[20:23]
	v_mfma_f32_16x16x32_bf16 v[16:19], v[196:199], v[220:223], v[16:19]
	v_mfma_f32_16x16x32_bf16 v[4:7], v[172:175], v[228:231], v[4:7]
	v_mfma_f32_16x16x32_bf16 v[0:3], v[196:199], v[228:231], v[0:3]
	v_mfma_f32_16x16x32_bf16 v[68:71], v[172:175], v[204:207], v[68:71]
	v_mfma_f32_16x16x32_bf16 v[64:67], v[196:199], v[204:207], v[64:67]
	v_mfma_f32_16x16x32_bf16 v[52:55], v[172:175], v[212:215], v[52:55]
	v_mfma_f32_16x16x32_bf16 v[48:51], v[196:199], v[212:215], v[48:51]
	s_barrier
	v_add_u32_e32 v144, 0x18000, v178
	ds_read_b128 v[168:171], v144
	ds_read_b128 v[172:175], v144 offset:1024
	ds_read_b128 v[192:195], v144 offset:2048
	ds_read_b128 v[196:199], v144 offset:3072
	ds_read_b128 v[200:203], v190 offset:32768
	ds_read_b128 v[204:207], v190 offset:33792
	ds_read_b128 v[208:211], v190 offset:34816
	ds_read_b128 v[212:215], v190 offset:35840
	ds_read_b128 v[216:219], v190 offset:36864
	ds_read_b128 v[220:223], v190 offset:37888
	ds_read_b128 v[224:227], v190 offset:38912
	ds_read_b128 v[228:231], v190 offset:39936
	s_waitcnt lgkmcnt(0)
	s_barrier
	v_mfma_f32_16x16x32_bf16 v[20:23], v[168:171], v[216:219], v[20:23]
	v_mfma_f32_16x16x32_bf16 v[16:19], v[192:195], v[216:219], v[16:19]
	v_mfma_f32_16x16x32_bf16 v[4:7], v[168:171], v[224:227], v[4:7]
	v_mfma_f32_16x16x32_bf16 v[0:3], v[192:195], v[224:227], v[0:3]
	v_mfma_f32_16x16x32_bf16 v[68:71], v[168:171], v[200:203], v[68:71]
	v_mfma_f32_16x16x32_bf16 v[64:67], v[192:195], v[200:203], v[64:67]
	v_mfma_f32_16x16x32_bf16 v[52:55], v[168:171], v[208:211], v[52:55]
	v_mfma_f32_16x16x32_bf16 v[48:51], v[192:195], v[208:211], v[48:51]
	v_mfma_f32_16x16x32_bf16 v[20:23], v[172:175], v[220:223], v[20:23]
	v_mfma_f32_16x16x32_bf16 v[16:19], v[196:199], v[220:223], v[16:19]
	v_mfma_f32_16x16x32_bf16 v[4:7], v[172:175], v[228:231], v[4:7]
	v_mfma_f32_16x16x32_bf16 v[0:3], v[196:199], v[228:231], v[0:3]
	v_mfma_f32_16x16x32_bf16 v[68:71], v[172:175], v[204:207], v[68:71]
	v_mfma_f32_16x16x32_bf16 v[64:67], v[196:199], v[204:207], v[64:67]
	v_mfma_f32_16x16x32_bf16 v[52:55], v[172:175], v[212:215], v[52:55]
	v_mfma_f32_16x16x32_bf16 v[48:51], v[196:199], v[212:215], v[48:51]
	s_barrier
	s_branch .Lq_lout_exit

.Lq_abi_0_k:
	v_add_u32_e32 v142, 0x10000, v160
	ds_read_b128 v[138:141], v142
	ds_read_b128 v[164:167], v142 offset:1024
	ds_read_b128 v[168:171], v142 offset:2048
	ds_read_b128 v[172:175], v142 offset:3072
	ds_read_b128 v[202:205], v162 offset:0
	ds_read_b128 v[206:209], v162 offset:1024
	ds_read_b128 v[210:213], v162 offset:2048
	ds_read_b128 v[214:217], v162 offset:3072
	ds_read_b128 v[218:221], v162 offset:4096
	ds_read_b128 v[222:225], v162 offset:5120
	ds_read_b128 v[226:229], v162 offset:6144
	ds_read_b128 v[230:233], v162 offset:7168
	v_lshl_add_u64 v[234:235], s[74:75], 0, v[128:129]
	s_add_i32 m0, s5, 0xc000
	v_lshl_add_u64 v[236:237], s[74:75], 0, v[130:131]
	global_load_lds_dwordx4 v[234:235], off
	s_add_i32 m0, s5, 0xe000
	v_lshl_add_u64 v[238:239], s[2:3], 0, v[144:145]
	global_load_lds_dwordx4 v[236:237], off
	s_add_i32 m0, s5, 0x1c000
	v_lshl_add_u64 v[240:241], s[2:3], 0, v[132:133]
	global_load_lds_dwordx4 v[238:239], off
	s_add_i32 m0, s5, 0x1e000
	s_add_u32 s74, s74, 0x80
	s_addc_u32 s75, s75, 0
	global_load_lds_dwordx4 v[240:241], off
	s_add_u32 s2, s2, 0x80
	s_addc_u32 s3, s3, 0
	s_waitcnt vmcnt(8)
	s_waitcnt lgkmcnt(0)
	s_barrier
	v_mfma_f32_16x16x32_bf16 v[124:127], v[138:141], v[202:205], v[124:127]
	v_mfma_f32_16x16x32_bf16 v[120:123], v[168:171], v[202:205], v[120:123]
	v_mfma_f32_16x16x32_bf16 v[108:111], v[138:141], v[210:213], v[108:111]
	v_mfma_f32_16x16x32_bf16 v[104:107], v[168:171], v[210:213], v[104:107]
	v_mfma_f32_16x16x32_bf16 v[92:95], v[138:141], v[218:221], v[92:95]
	v_mfma_f32_16x16x32_bf16 v[88:91], v[168:171], v[218:221], v[88:91]
	v_mfma_f32_16x16x32_bf16 v[76:79], v[138:141], v[226:229], v[76:79]
	v_mfma_f32_16x16x32_bf16 v[72:75], v[168:171], v[226:229], v[72:75]
	v_mfma_f32_16x16x32_bf16 v[124:127], v[164:167], v[206:209], v[124:127]
	v_mfma_f32_16x16x32_bf16 v[120:123], v[172:175], v[206:209], v[120:123]
	v_mfma_f32_16x16x32_bf16 v[108:111], v[164:167], v[214:217], v[108:111]
	v_mfma_f32_16x16x32_bf16 v[104:107], v[172:175], v[214:217], v[104:107]
	v_mfma_f32_16x16x32_bf16 v[92:95], v[164:167], v[222:225], v[92:95]
	v_mfma_f32_16x16x32_bf16 v[88:91], v[172:175], v[222:225], v[88:91]
	v_mfma_f32_16x16x32_bf16 v[76:79], v[164:167], v[230:233], v[76:79]
	v_mfma_f32_16x16x32_bf16 v[72:75], v[172:175], v[230:233], v[72:75]
	s_barrier
	v_add_u32_e32 v142, 0x18000, v160
	ds_read_b128 v[138:141], v142
	ds_read_b128 v[164:167], v142 offset:1024
	ds_read_b128 v[168:171], v142 offset:2048
	ds_read_b128 v[172:175], v142 offset:3072
	ds_read_b128 v[202:205], v162 offset:32768
	ds_read_b128 v[206:209], v162 offset:33792
	ds_read_b128 v[210:213], v162 offset:34816
	ds_read_b128 v[214:217], v162 offset:35840
	ds_read_b128 v[218:221], v162 offset:36864
	ds_read_b128 v[222:225], v162 offset:37888
	ds_read_b128 v[226:229], v162 offset:38912
	ds_read_b128 v[230:233], v162 offset:39936
	v_lshl_add_u64 v[234:235], s[74:75], 0, v[128:129]
	s_add_i32 m0, s5, 0x0
	v_lshl_add_u64 v[236:237], s[74:75], 0, v[130:131]
	global_load_lds_dwordx4 v[234:235], off
	s_add_i32 m0, s5, 0x2000
	v_lshl_add_u64 v[238:239], s[2:3], 0, v[144:145]
	global_load_lds_dwordx4 v[236:237], off
	s_add_i32 m0, s5, 0x10000
	v_lshl_add_u64 v[240:241], s[2:3], 0, v[132:133]
	global_load_lds_dwordx4 v[238:239], off
	s_add_i32 m0, s5, 0x12000
	s_add_u32 s74, s74, 0x80
	s_addc_u32 s75, s75, 0
	global_load_lds_dwordx4 v[240:241], off
	s_add_u32 s2, s2, 0x80
	s_addc_u32 s3, s3, 0
	s_waitcnt vmcnt(8)
	s_waitcnt lgkmcnt(0)
	s_barrier
	v_mfma_f32_16x16x32_bf16 v[124:127], v[138:141], v[202:205], v[124:127]
	v_mfma_f32_16x16x32_bf16 v[120:123], v[168:171], v[202:205], v[120:123]
	v_mfma_f32_16x16x32_bf16 v[108:111], v[138:141], v[210:213], v[108:111]
	v_mfma_f32_16x16x32_bf16 v[104:107], v[168:171], v[210:213], v[104:107]
	v_mfma_f32_16x16x32_bf16 v[92:95], v[138:141], v[218:221], v[92:95]
	v_mfma_f32_16x16x32_bf16 v[88:91], v[168:171], v[218:221], v[88:91]
	v_mfma_f32_16x16x32_bf16 v[76:79], v[138:141], v[226:229], v[76:79]
	v_mfma_f32_16x16x32_bf16 v[72:75], v[168:171], v[226:229], v[72:75]
	v_mfma_f32_16x16x32_bf16 v[124:127], v[164:167], v[206:209], v[124:127]
	v_mfma_f32_16x16x32_bf16 v[120:123], v[172:175], v[206:209], v[120:123]
	v_mfma_f32_16x16x32_bf16 v[108:111], v[164:167], v[214:217], v[108:111]
	v_mfma_f32_16x16x32_bf16 v[104:107], v[172:175], v[214:217], v[104:107]
	v_mfma_f32_16x16x32_bf16 v[92:95], v[164:167], v[222:225], v[92:95]
	v_mfma_f32_16x16x32_bf16 v[88:91], v[172:175], v[222:225], v[88:91]
	v_mfma_f32_16x16x32_bf16 v[76:79], v[164:167], v[230:233], v[76:79]
	v_mfma_f32_16x16x32_bf16 v[72:75], v[172:175], v[230:233], v[72:75]
	s_barrier
	v_add_u32_e32 v142, 0x14000, v160
	ds_read_b128 v[138:141], v142
	ds_read_b128 v[164:167], v142 offset:1024
	ds_read_b128 v[168:171], v142 offset:2048
	ds_read_b128 v[172:175], v142 offset:3072
	ds_read_b128 v[202:205], v162 offset:16384
	ds_read_b128 v[206:209], v162 offset:17408
	ds_read_b128 v[210:213], v162 offset:18432
	ds_read_b128 v[214:217], v162 offset:19456
	ds_read_b128 v[218:221], v162 offset:20480
	ds_read_b128 v[222:225], v162 offset:21504
	ds_read_b128 v[226:229], v162 offset:22528
	ds_read_b128 v[230:233], v162 offset:23552
	v_lshl_add_u64 v[234:235], s[74:75], 0, v[128:129]
	s_add_i32 m0, s5, 0x8000
	v_lshl_add_u64 v[236:237], s[74:75], 0, v[130:131]
	global_load_lds_dwordx4 v[234:235], off
	s_add_i32 m0, s5, 0xa000
	v_lshl_add_u64 v[238:239], s[2:3], 0, v[144:145]
	global_load_lds_dwordx4 v[236:237], off
	s_add_i32 m0, s5, 0x18000
	v_lshl_add_u64 v[240:241], s[2:3], 0, v[132:133]
	global_load_lds_dwordx4 v[238:239], off
	s_add_i32 m0, s5, 0x1a000
	s_add_u32 s74, s74, 0x80
	s_addc_u32 s75, s75, 0
	global_load_lds_dwordx4 v[240:241], off
	s_add_u32 s2, s2, 0x80
	s_addc_u32 s3, s3, 0
	s_waitcnt vmcnt(8)
	s_waitcnt lgkmcnt(0)
	s_barrier
	v_mfma_f32_16x16x32_bf16 v[124:127], v[138:141], v[202:205], v[124:127]
	v_mfma_f32_16x16x32_bf16 v[120:123], v[168:171], v[202:205], v[120:123]
	v_mfma_f32_16x16x32_bf16 v[108:111], v[138:141], v[210:213], v[108:111]
	v_mfma_f32_16x16x32_bf16 v[104:107], v[168:171], v[210:213], v[104:107]
	v_mfma_f32_16x16x32_bf16 v[92:95], v[138:141], v[218:221], v[92:95]
	v_mfma_f32_16x16x32_bf16 v[88:91], v[168:171], v[218:221], v[88:91]
	v_mfma_f32_16x16x32_bf16 v[76:79], v[138:141], v[226:229], v[76:79]
	v_mfma_f32_16x16x32_bf16 v[72:75], v[168:171], v[226:229], v[72:75]
	v_mfma_f32_16x16x32_bf16 v[124:127], v[164:167], v[206:209], v[124:127]
	v_mfma_f32_16x16x32_bf16 v[120:123], v[172:175], v[206:209], v[120:123]
	v_mfma_f32_16x16x32_bf16 v[108:111], v[164:167], v[214:217], v[108:111]
	v_mfma_f32_16x16x32_bf16 v[104:107], v[172:175], v[214:217], v[104:107]
	v_mfma_f32_16x16x32_bf16 v[92:95], v[164:167], v[222:225], v[92:95]
	v_mfma_f32_16x16x32_bf16 v[88:91], v[172:175], v[222:225], v[88:91]
	v_mfma_f32_16x16x32_bf16 v[76:79], v[164:167], v[230:233], v[76:79]
	v_mfma_f32_16x16x32_bf16 v[72:75], v[172:175], v[230:233], v[72:75]
	s_barrier
	v_add_u32_e32 v142, 0x1c000, v160
	ds_read_b128 v[138:141], v142
	ds_read_b128 v[164:167], v142 offset:1024
	ds_read_b128 v[168:171], v142 offset:2048
	ds_read_b128 v[172:175], v142 offset:3072
	ds_read_b128 v[202:205], v162 offset:49152
	ds_read_b128 v[206:209], v162 offset:50176
	ds_read_b128 v[210:213], v162 offset:51200
	ds_read_b128 v[214:217], v162 offset:52224
	ds_read_b128 v[218:221], v162 offset:53248
	ds_read_b128 v[222:225], v162 offset:54272
	ds_read_b128 v[226:229], v162 offset:55296
	ds_read_b128 v[230:233], v162 offset:56320
	v_lshl_add_u64 v[234:235], s[74:75], 0, v[128:129]
	s_add_i32 m0, s5, 0x4000
	v_lshl_add_u64 v[236:237], s[74:75], 0, v[130:131]
	global_load_lds_dwordx4 v[234:235], off
	s_add_i32 m0, s5, 0x6000
	v_lshl_add_u64 v[238:239], s[2:3], 0, v[144:145]
	global_load_lds_dwordx4 v[236:237], off
	s_add_i32 m0, s5, 0x14000
	v_lshl_add_u64 v[240:241], s[2:3], 0, v[132:133]
	global_load_lds_dwordx4 v[238:239], off
	s_add_i32 m0, s5, 0x16000
	s_add_u32 s74, s74, 0x80
	s_addc_u32 s75, s75, 0
	global_load_lds_dwordx4 v[240:241], off
	s_add_u32 s2, s2, 0x80
	s_addc_u32 s3, s3, 0
	s_waitcnt vmcnt(8)
	s_waitcnt lgkmcnt(0)
	s_barrier
	v_mfma_f32_16x16x32_bf16 v[124:127], v[138:141], v[202:205], v[124:127]
	v_mfma_f32_16x16x32_bf16 v[120:123], v[168:171], v[202:205], v[120:123]
	v_mfma_f32_16x16x32_bf16 v[108:111], v[138:141], v[210:213], v[108:111]
	v_mfma_f32_16x16x32_bf16 v[104:107], v[168:171], v[210:213], v[104:107]
	v_mfma_f32_16x16x32_bf16 v[92:95], v[138:141], v[218:221], v[92:95]
	v_mfma_f32_16x16x32_bf16 v[88:91], v[168:171], v[218:221], v[88:91]
	v_mfma_f32_16x16x32_bf16 v[76:79], v[138:141], v[226:229], v[76:79]
	v_mfma_f32_16x16x32_bf16 v[72:75], v[168:171], v[226:229], v[72:75]
	v_mfma_f32_16x16x32_bf16 v[124:127], v[164:167], v[206:209], v[124:127]
	v_mfma_f32_16x16x32_bf16 v[120:123], v[172:175], v[206:209], v[120:123]
	v_mfma_f32_16x16x32_bf16 v[108:111], v[164:167], v[214:217], v[108:111]
	v_mfma_f32_16x16x32_bf16 v[104:107], v[172:175], v[214:217], v[104:107]
	v_mfma_f32_16x16x32_bf16 v[92:95], v[164:167], v[222:225], v[92:95]
	v_mfma_f32_16x16x32_bf16 v[88:91], v[172:175], v[222:225], v[88:91]
	v_mfma_f32_16x16x32_bf16 v[76:79], v[164:167], v[230:233], v[76:79]
	v_mfma_f32_16x16x32_bf16 v[72:75], v[172:175], v[230:233], v[72:75]
	s_barrier
	s_add_i32 s8, s8, 1
	s_cmp_lt_u32 s8, 7
	s_cbranch_scc1 .Lq_abi_0_k
	v_add_u32_e32 v142, 0x10000, v160
	ds_read_b128 v[138:141], v142
	ds_read_b128 v[164:167], v142 offset:1024
	ds_read_b128 v[168:171], v142 offset:2048
	ds_read_b128 v[172:175], v142 offset:3072
	ds_read_b128 v[202:205], v162 offset:0
	ds_read_b128 v[206:209], v162 offset:1024
	ds_read_b128 v[210:213], v162 offset:2048
	ds_read_b128 v[214:217], v162 offset:3072
	ds_read_b128 v[218:221], v162 offset:4096
	ds_read_b128 v[222:225], v162 offset:5120
	ds_read_b128 v[226:229], v162 offset:6144
	ds_read_b128 v[230:233], v162 offset:7168
	v_lshl_add_u64 v[234:235], s[74:75], 0, v[128:129]
	s_add_i32 m0, s5, 0xc000
	v_lshl_add_u64 v[236:237], s[74:75], 0, v[130:131]
	global_load_lds_dwordx4 v[234:235], off
	s_add_i32 m0, s5, 0xe000
	v_lshl_add_u64 v[238:239], s[2:3], 0, v[144:145]
	global_load_lds_dwordx4 v[236:237], off
	s_add_i32 m0, s5, 0x1c000
	v_lshl_add_u64 v[240:241], s[2:3], 0, v[132:133]
	global_load_lds_dwordx4 v[238:239], off
	s_add_i32 m0, s5, 0x1e000
	s_add_u32 s74, s74, 0x80
	s_addc_u32 s75, s75, 0
	global_load_lds_dwordx4 v[240:241], off
	s_add_u32 s2, s2, 0x80
	s_addc_u32 s3, s3, 0
	s_waitcnt vmcnt(8)
	s_waitcnt lgkmcnt(0)
	s_barrier
	v_mfma_f32_16x16x32_bf16 v[124:127], v[138:141], v[202:205], v[124:127]
	v_mfma_f32_16x16x32_bf16 v[120:123], v[168:171], v[202:205], v[120:123]
	v_mfma_f32_16x16x32_bf16 v[108:111], v[138:141], v[210:213], v[108:111]
	v_mfma_f32_16x16x32_bf16 v[104:107], v[168:171], v[210:213], v[104:107]
	v_mfma_f32_16x16x32_bf16 v[92:95], v[138:141], v[218:221], v[92:95]
	v_mfma_f32_16x16x32_bf16 v[88:91], v[168:171], v[218:221], v[88:91]
	v_mfma_f32_16x16x32_bf16 v[76:79], v[138:141], v[226:229], v[76:79]
	v_mfma_f32_16x16x32_bf16 v[72:75], v[168:171], v[226:229], v[72:75]
	v_mfma_f32_16x16x32_bf16 v[124:127], v[164:167], v[206:209], v[124:127]
	v_mfma_f32_16x16x32_bf16 v[120:123], v[172:175], v[206:209], v[120:123]
	v_mfma_f32_16x16x32_bf16 v[108:111], v[164:167], v[214:217], v[108:111]
	v_mfma_f32_16x16x32_bf16 v[104:107], v[172:175], v[214:217], v[104:107]
	v_mfma_f32_16x16x32_bf16 v[92:95], v[164:167], v[222:225], v[92:95]
	v_mfma_f32_16x16x32_bf16 v[88:91], v[172:175], v[222:225], v[88:91]
	v_mfma_f32_16x16x32_bf16 v[76:79], v[164:167], v[230:233], v[76:79]
	v_mfma_f32_16x16x32_bf16 v[72:75], v[172:175], v[230:233], v[72:75]
	s_barrier
	v_add_u32_e32 v142, 0x18000, v160
	ds_read_b128 v[138:141], v142
	ds_read_b128 v[164:167], v142 offset:1024
	ds_read_b128 v[168:171], v142 offset:2048
	ds_read_b128 v[172:175], v142 offset:3072
	ds_read_b128 v[202:205], v162 offset:32768
	ds_read_b128 v[206:209], v162 offset:33792
	ds_read_b128 v[210:213], v162 offset:34816
	ds_read_b128 v[214:217], v162 offset:35840
	ds_read_b128 v[218:221], v162 offset:36864
	ds_read_b128 v[222:225], v162 offset:37888
	ds_read_b128 v[226:229], v162 offset:38912
	ds_read_b128 v[230:233], v162 offset:39936
	s_waitcnt vmcnt(4)
	s_waitcnt lgkmcnt(0)
	s_barrier
	v_mfma_f32_16x16x32_bf16 v[124:127], v[138:141], v[202:205], v[124:127]
	v_mfma_f32_16x16x32_bf16 v[120:123], v[168:171], v[202:205], v[120:123]
	v_mfma_f32_16x16x32_bf16 v[108:111], v[138:141], v[210:213], v[108:111]
	v_mfma_f32_16x16x32_bf16 v[104:107], v[168:171], v[210:213], v[104:107]
	v_mfma_f32_16x16x32_bf16 v[92:95], v[138:141], v[218:221], v[92:95]
	v_mfma_f32_16x16x32_bf16 v[88:91], v[168:171], v[218:221], v[88:91]
	v_mfma_f32_16x16x32_bf16 v[76:79], v[138:141], v[226:229], v[76:79]
	v_mfma_f32_16x16x32_bf16 v[72:75], v[168:171], v[226:229], v[72:75]
	v_mfma_f32_16x16x32_bf16 v[124:127], v[164:167], v[206:209], v[124:127]
	v_mfma_f32_16x16x32_bf16 v[120:123], v[172:175], v[206:209], v[120:123]
	v_mfma_f32_16x16x32_bf16 v[108:111], v[164:167], v[214:217], v[108:111]
	v_mfma_f32_16x16x32_bf16 v[104:107], v[172:175], v[214:217], v[104:107]
	v_mfma_f32_16x16x32_bf16 v[92:95], v[164:167], v[222:225], v[92:95]
	v_mfma_f32_16x16x32_bf16 v[88:91], v[172:175], v[222:225], v[88:91]
	v_mfma_f32_16x16x32_bf16 v[76:79], v[164:167], v[230:233], v[76:79]
	v_mfma_f32_16x16x32_bf16 v[72:75], v[172:175], v[230:233], v[72:75]
	s_barrier
	v_add_u32_e32 v142, 0x14000, v160
	ds_read_b128 v[138:141], v142
	ds_read_b128 v[164:167], v142 offset:1024
	ds_read_b128 v[168:171], v142 offset:2048
	ds_read_b128 v[172:175], v142 offset:3072
	ds_read_b128 v[202:205], v162 offset:16384
	ds_read_b128 v[206:209], v162 offset:17408
	ds_read_b128 v[210:213], v162 offset:18432
	ds_read_b128 v[214:217], v162 offset:19456
	ds_read_b128 v[218:221], v162 offset:20480
	ds_read_b128 v[222:225], v162 offset:21504
	ds_read_b128 v[226:229], v162 offset:22528
	ds_read_b128 v[230:233], v162 offset:23552
	s_waitcnt vmcnt(0)
	s_waitcnt lgkmcnt(0)
	s_barrier
	v_mfma_f32_16x16x32_bf16 v[124:127], v[138:141], v[202:205], v[124:127]
	v_mfma_f32_16x16x32_bf16 v[120:123], v[168:171], v[202:205], v[120:123]
	v_mfma_f32_16x16x32_bf16 v[108:111], v[138:141], v[210:213], v[108:111]
	v_mfma_f32_16x16x32_bf16 v[104:107], v[168:171], v[210:213], v[104:107]
	v_mfma_f32_16x16x32_bf16 v[92:95], v[138:141], v[218:221], v[92:95]
	v_mfma_f32_16x16x32_bf16 v[88:91], v[168:171], v[218:221], v[88:91]
	v_mfma_f32_16x16x32_bf16 v[76:79], v[138:141], v[226:229], v[76:79]
	v_mfma_f32_16x16x32_bf16 v[72:75], v[168:171], v[226:229], v[72:75]
	v_mfma_f32_16x16x32_bf16 v[124:127], v[164:167], v[206:209], v[124:127]
	v_mfma_f32_16x16x32_bf16 v[120:123], v[172:175], v[206:209], v[120:123]
	v_mfma_f32_16x16x32_bf16 v[108:111], v[164:167], v[214:217], v[108:111]
	v_mfma_f32_16x16x32_bf16 v[104:107], v[172:175], v[214:217], v[104:107]
	v_mfma_f32_16x16x32_bf16 v[92:95], v[164:167], v[222:225], v[92:95]
	v_mfma_f32_16x16x32_bf16 v[88:91], v[172:175], v[222:225], v[88:91]
	v_mfma_f32_16x16x32_bf16 v[76:79], v[164:167], v[230:233], v[76:79]
	v_mfma_f32_16x16x32_bf16 v[72:75], v[172:175], v[230:233], v[72:75]
	s_barrier
	v_add_u32_e32 v142, 0x1c000, v160
	ds_read_b128 v[138:141], v142
	ds_read_b128 v[164:167], v142 offset:1024
	ds_read_b128 v[168:171], v142 offset:2048
	ds_read_b128 v[172:175], v142 offset:3072
	ds_read_b128 v[202:205], v162 offset:49152
	ds_read_b128 v[206:209], v162 offset:50176
	ds_read_b128 v[210:213], v162 offset:51200
	ds_read_b128 v[214:217], v162 offset:52224
	ds_read_b128 v[218:221], v162 offset:53248
	ds_read_b128 v[222:225], v162 offset:54272
	ds_read_b128 v[226:229], v162 offset:55296
	ds_read_b128 v[230:233], v162 offset:56320
	s_waitcnt lgkmcnt(0)
	s_barrier
	v_mfma_f32_16x16x32_bf16 v[124:127], v[138:141], v[202:205], v[124:127]
	v_mfma_f32_16x16x32_bf16 v[120:123], v[168:171], v[202:205], v[120:123]
	v_mfma_f32_16x16x32_bf16 v[108:111], v[138:141], v[210:213], v[108:111]
	v_mfma_f32_16x16x32_bf16 v[104:107], v[168:171], v[210:213], v[104:107]
	v_mfma_f32_16x16x32_bf16 v[92:95], v[138:141], v[218:221], v[92:95]
	v_mfma_f32_16x16x32_bf16 v[88:91], v[168:171], v[218:221], v[88:91]
	v_mfma_f32_16x16x32_bf16 v[76:79], v[138:141], v[226:229], v[76:79]
	v_mfma_f32_16x16x32_bf16 v[72:75], v[168:171], v[226:229], v[72:75]
	v_mfma_f32_16x16x32_bf16 v[124:127], v[164:167], v[206:209], v[124:127]
	v_mfma_f32_16x16x32_bf16 v[120:123], v[172:175], v[206:209], v[120:123]
	v_mfma_f32_16x16x32_bf16 v[108:111], v[164:167], v[214:217], v[108:111]
	v_mfma_f32_16x16x32_bf16 v[104:107], v[172:175], v[214:217], v[104:107]
	v_mfma_f32_16x16x32_bf16 v[92:95], v[164:167], v[222:225], v[92:95]
	v_mfma_f32_16x16x32_bf16 v[88:91], v[172:175], v[222:225], v[88:91]
	v_mfma_f32_16x16x32_bf16 v[76:79], v[164:167], v[230:233], v[76:79]
	v_mfma_f32_16x16x32_bf16 v[72:75], v[172:175], v[230:233], v[72:75]
	s_barrier
	s_branch .Lq_abi_exit

.Lq_abi_1_k:
	v_add_u32_e32 v142, 0x14000, v160
	ds_read_b128 v[176:179], v142
	ds_read_b128 v[190:193], v142 offset:1024
	ds_read_b128 v[194:197], v142 offset:2048
	ds_read_b128 v[198:201], v142 offset:3072
	ds_read_b128 v[202:205], v162 offset:0
	ds_read_b128 v[206:209], v162 offset:1024
	ds_read_b128 v[210:213], v162 offset:2048
	ds_read_b128 v[214:217], v162 offset:3072
	ds_read_b128 v[218:221], v162 offset:4096
	ds_read_b128 v[222:225], v162 offset:5120
	ds_read_b128 v[226:229], v162 offset:6144
	ds_read_b128 v[230:233], v162 offset:7168
	v_lshl_add_u64 v[234:235], s[74:75], 0, v[128:129]
	s_add_i32 m0, s5, 0xc000
	v_lshl_add_u64 v[236:237], s[74:75], 0, v[130:131]
	global_load_lds_dwordx4 v[234:235], off
	s_add_i32 m0, s5, 0xe000
	v_lshl_add_u64 v[238:239], s[2:3], 0, v[144:145]
	global_load_lds_dwordx4 v[236:237], off
	s_add_i32 m0, s5, 0x18000
	v_lshl_add_u64 v[240:241], s[2:3], 0, v[132:133]
	global_load_lds_dwordx4 v[238:239], off
	s_add_i32 m0, s5, 0x1a000
	s_add_u32 s74, s74, 0x80
	s_addc_u32 s75, s75, 0
	global_load_lds_dwordx4 v[240:241], off
	s_add_u32 s2, s2, 0x80
	s_addc_u32 s3, s3, 0
	s_waitcnt vmcnt(8)
	s_waitcnt lgkmcnt(0)
	s_barrier
	v_mfma_f32_16x16x32_bf16 v[116:119], v[176:179], v[202:205], v[116:119]
	v_mfma_f32_16x16x32_bf16 v[112:115], v[194:197], v[202:205], v[112:115]
	v_mfma_f32_16x16x32_bf16 v[100:103], v[176:179], v[210:213], v[100:103]
	v_mfma_f32_16x16x32_bf16 v[96:99], v[194:197], v[210:213], v[96:99]
	v_mfma_f32_16x16x32_bf16 v[84:87], v[176:179], v[218:221], v[84:87]
	v_mfma_f32_16x16x32_bf16 v[80:83], v[194:197], v[218:221], v[80:83]
	v_mfma_f32_16x16x32_bf16 v[68:71], v[176:179], v[226:229], v[68:71]
	v_mfma_f32_16x16x32_bf16 v[64:67], v[194:197], v[226:229], v[64:67]
	v_mfma_f32_16x16x32_bf16 v[116:119], v[190:193], v[206:209], v[116:119]
	v_mfma_f32_16x16x32_bf16 v[112:115], v[198:201], v[206:209], v[112:115]
	v_mfma_f32_16x16x32_bf16 v[100:103], v[190:193], v[214:217], v[100:103]
	v_mfma_f32_16x16x32_bf16 v[96:99], v[198:201], v[214:217], v[96:99]
	v_mfma_f32_16x16x32_bf16 v[84:87], v[190:193], v[222:225], v[84:87]
	v_mfma_f32_16x16x32_bf16 v[80:83], v[198:201], v[222:225], v[80:83]
	v_mfma_f32_16x16x32_bf16 v[68:71], v[190:193], v[230:233], v[68:71]
	v_mfma_f32_16x16x32_bf16 v[64:67], v[198:201], v[230:233], v[64:67]
	s_barrier
	v_add_u32_e32 v142, 0x1c000, v160
	ds_read_b128 v[176:179], v142
	ds_read_b128 v[190:193], v142 offset:1024
	ds_read_b128 v[194:197], v142 offset:2048
	ds_read_b128 v[198:201], v142 offset:3072
	ds_read_b128 v[202:205], v162 offset:32768
	ds_read_b128 v[206:209], v162 offset:33792
	ds_read_b128 v[210:213], v162 offset:34816
	ds_read_b128 v[214:217], v162 offset:35840
	ds_read_b128 v[218:221], v162 offset:36864
	ds_read_b128 v[222:225], v162 offset:37888
	ds_read_b128 v[226:229], v162 offset:38912
	ds_read_b128 v[230:233], v162 offset:39936
	v_lshl_add_u64 v[234:235], s[74:75], 0, v[128:129]
	s_add_i32 m0, s5, 0x0
	v_lshl_add_u64 v[236:237], s[74:75], 0, v[130:131]
	global_load_lds_dwordx4 v[234:235], off
	s_add_i32 m0, s5, 0x2000
	v_lshl_add_u64 v[238:239], s[2:3], 0, v[144:145]
	global_load_lds_dwordx4 v[236:237], off
	s_add_i32 m0, s5, 0x14000
	v_lshl_add_u64 v[240:241], s[2:3], 0, v[132:133]
	global_load_lds_dwordx4 v[238:239], off
	s_add_i32 m0, s5, 0x16000
	s_add_u32 s74, s74, 0x80
	s_addc_u32 s75, s75, 0
	global_load_lds_dwordx4 v[240:241], off
	s_add_u32 s2, s2, 0x80
	s_addc_u32 s3, s3, 0
	s_waitcnt vmcnt(8)
	s_waitcnt lgkmcnt(0)
	s_barrier
	v_mfma_f32_16x16x32_bf16 v[116:119], v[176:179], v[202:205], v[116:119]
	v_mfma_f32_16x16x32_bf16 v[112:115], v[194:197], v[202:205], v[112:115]
	v_mfma_f32_16x16x32_bf16 v[100:103], v[176:179], v[210:213], v[100:103]
	v_mfma_f32_16x16x32_bf16 v[96:99], v[194:197], v[210:213], v[96:99]
	v_mfma_f32_16x16x32_bf16 v[84:87], v[176:179], v[218:221], v[84:87]
	v_mfma_f32_16x16x32_bf16 v[80:83], v[194:197], v[218:221], v[80:83]
	v_mfma_f32_16x16x32_bf16 v[68:71], v[176:179], v[226:229], v[68:71]
	v_mfma_f32_16x16x32_bf16 v[64:67], v[194:197], v[226:229], v[64:67]
	v_mfma_f32_16x16x32_bf16 v[116:119], v[190:193], v[206:209], v[116:119]
	v_mfma_f32_16x16x32_bf16 v[112:115], v[198:201], v[206:209], v[112:115]
	v_mfma_f32_16x16x32_bf16 v[100:103], v[190:193], v[214:217], v[100:103]
	v_mfma_f32_16x16x32_bf16 v[96:99], v[198:201], v[214:217], v[96:99]
	v_mfma_f32_16x16x32_bf16 v[84:87], v[190:193], v[222:225], v[84:87]
	v_mfma_f32_16x16x32_bf16 v[80:83], v[198:201], v[222:225], v[80:83]
	v_mfma_f32_16x16x32_bf16 v[68:71], v[190:193], v[230:233], v[68:71]
	v_mfma_f32_16x16x32_bf16 v[64:67], v[198:201], v[230:233], v[64:67]
	s_barrier
	v_add_u32_e32 v142, 0x10000, v160
	ds_read_b128 v[176:179], v142
	ds_read_b128 v[190:193], v142 offset:1024
	ds_read_b128 v[194:197], v142 offset:2048
	ds_read_b128 v[198:201], v142 offset:3072
	ds_read_b128 v[202:205], v162 offset:16384
	ds_read_b128 v[206:209], v162 offset:17408
	ds_read_b128 v[210:213], v162 offset:18432
	ds_read_b128 v[214:217], v162 offset:19456
	ds_read_b128 v[218:221], v162 offset:20480
	ds_read_b128 v[222:225], v162 offset:21504
	ds_read_b128 v[226:229], v162 offset:22528
	ds_read_b128 v[230:233], v162 offset:23552
	v_lshl_add_u64 v[234:235], s[74:75], 0, v[128:129]
	s_add_i32 m0, s5, 0x8000
	v_lshl_add_u64 v[236:237], s[74:75], 0, v[130:131]
	global_load_lds_dwordx4 v[234:235], off
	s_add_i32 m0, s5, 0xa000
	v_lshl_add_u64 v[238:239], s[2:3], 0, v[144:145]
	global_load_lds_dwordx4 v[236:237], off
	s_add_i32 m0, s5, 0x1c000
	v_lshl_add_u64 v[240:241], s[2:3], 0, v[132:133]
	global_load_lds_dwordx4 v[238:239], off
	s_add_i32 m0, s5, 0x1e000
	s_add_u32 s74, s74, 0x80
	s_addc_u32 s75, s75, 0
	global_load_lds_dwordx4 v[240:241], off
	s_add_u32 s2, s2, 0x80
	s_addc_u32 s3, s3, 0
	s_waitcnt vmcnt(8)
	s_waitcnt lgkmcnt(0)
	s_barrier
	v_mfma_f32_16x16x32_bf16 v[116:119], v[176:179], v[202:205], v[116:119]
	v_mfma_f32_16x16x32_bf16 v[112:115], v[194:197], v[202:205], v[112:115]
	v_mfma_f32_16x16x32_bf16 v[100:103], v[176:179], v[210:213], v[100:103]
	v_mfma_f32_16x16x32_bf16 v[96:99], v[194:197], v[210:213], v[96:99]
	v_mfma_f32_16x16x32_bf16 v[84:87], v[176:179], v[218:221], v[84:87]
	v_mfma_f32_16x16x32_bf16 v[80:83], v[194:197], v[218:221], v[80:83]
	v_mfma_f32_16x16x32_bf16 v[68:71], v[176:179], v[226:229], v[68:71]
	v_mfma_f32_16x16x32_bf16 v[64:67], v[194:197], v[226:229], v[64:67]
	v_mfma_f32_16x16x32_bf16 v[116:119], v[190:193], v[206:209], v[116:119]
	v_mfma_f32_16x16x32_bf16 v[112:115], v[198:201], v[206:209], v[112:115]
	v_mfma_f32_16x16x32_bf16 v[100:103], v[190:193], v[214:217], v[100:103]
	v_mfma_f32_16x16x32_bf16 v[96:99], v[198:201], v[214:217], v[96:99]
	v_mfma_f32_16x16x32_bf16 v[84:87], v[190:193], v[222:225], v[84:87]
	v_mfma_f32_16x16x32_bf16 v[80:83], v[198:201], v[222:225], v[80:83]
	v_mfma_f32_16x16x32_bf16 v[68:71], v[190:193], v[230:233], v[68:71]
	v_mfma_f32_16x16x32_bf16 v[64:67], v[198:201], v[230:233], v[64:67]
	s_barrier
	v_add_u32_e32 v142, 0x18000, v160
	ds_read_b128 v[176:179], v142
	ds_read_b128 v[190:193], v142 offset:1024
	ds_read_b128 v[194:197], v142 offset:2048
	ds_read_b128 v[198:201], v142 offset:3072
	ds_read_b128 v[202:205], v162 offset:49152
	ds_read_b128 v[206:209], v162 offset:50176
	ds_read_b128 v[210:213], v162 offset:51200
	ds_read_b128 v[214:217], v162 offset:52224
	ds_read_b128 v[218:221], v162 offset:53248
	ds_read_b128 v[222:225], v162 offset:54272
	ds_read_b128 v[226:229], v162 offset:55296
	ds_read_b128 v[230:233], v162 offset:56320
	v_lshl_add_u64 v[234:235], s[74:75], 0, v[128:129]
	s_add_i32 m0, s5, 0x4000
	v_lshl_add_u64 v[236:237], s[74:75], 0, v[130:131]
	global_load_lds_dwordx4 v[234:235], off
	s_add_i32 m0, s5, 0x6000
	v_lshl_add_u64 v[238:239], s[2:3], 0, v[144:145]
	global_load_lds_dwordx4 v[236:237], off
	s_add_i32 m0, s5, 0x10000
	v_lshl_add_u64 v[240:241], s[2:3], 0, v[132:133]
	global_load_lds_dwordx4 v[238:239], off
	s_add_i32 m0, s5, 0x12000
	s_add_u32 s74, s74, 0x80
	s_addc_u32 s75, s75, 0
	global_load_lds_dwordx4 v[240:241], off
	s_add_u32 s2, s2, 0x80
	s_addc_u32 s3, s3, 0
	s_waitcnt vmcnt(8)
	s_waitcnt lgkmcnt(0)
	s_barrier
	v_mfma_f32_16x16x32_bf16 v[116:119], v[176:179], v[202:205], v[116:119]
	v_mfma_f32_16x16x32_bf16 v[112:115], v[194:197], v[202:205], v[112:115]
	v_mfma_f32_16x16x32_bf16 v[100:103], v[176:179], v[210:213], v[100:103]
	v_mfma_f32_16x16x32_bf16 v[96:99], v[194:197], v[210:213], v[96:99]
	v_mfma_f32_16x16x32_bf16 v[84:87], v[176:179], v[218:221], v[84:87]
	v_mfma_f32_16x16x32_bf16 v[80:83], v[194:197], v[218:221], v[80:83]
	v_mfma_f32_16x16x32_bf16 v[68:71], v[176:179], v[226:229], v[68:71]
	v_mfma_f32_16x16x32_bf16 v[64:67], v[194:197], v[226:229], v[64:67]
	v_mfma_f32_16x16x32_bf16 v[116:119], v[190:193], v[206:209], v[116:119]
	v_mfma_f32_16x16x32_bf16 v[112:115], v[198:201], v[206:209], v[112:115]
	v_mfma_f32_16x16x32_bf16 v[100:103], v[190:193], v[214:217], v[100:103]
	v_mfma_f32_16x16x32_bf16 v[96:99], v[198:201], v[214:217], v[96:99]
	v_mfma_f32_16x16x32_bf16 v[84:87], v[190:193], v[222:225], v[84:87]
	v_mfma_f32_16x16x32_bf16 v[80:83], v[198:201], v[222:225], v[80:83]
	v_mfma_f32_16x16x32_bf16 v[68:71], v[190:193], v[230:233], v[68:71]
	v_mfma_f32_16x16x32_bf16 v[64:67], v[198:201], v[230:233], v[64:67]
	s_barrier
	s_add_i32 s8, s8, 1
	s_cmp_lt_u32 s8, 7
	s_cbranch_scc1 .Lq_abi_1_k
	v_add_u32_e32 v142, 0x14000, v160
	ds_read_b128 v[176:179], v142
	ds_read_b128 v[190:193], v142 offset:1024
	ds_read_b128 v[194:197], v142 offset:2048
	ds_read_b128 v[198:201], v142 offset:3072
	ds_read_b128 v[202:205], v162 offset:0
	ds_read_b128 v[206:209], v162 offset:1024
	ds_read_b128 v[210:213], v162 offset:2048
	ds_read_b128 v[214:217], v162 offset:3072
	ds_read_b128 v[218:221], v162 offset:4096
	ds_read_b128 v[222:225], v162 offset:5120
	ds_read_b128 v[226:229], v162 offset:6144
	ds_read_b128 v[230:233], v162 offset:7168
	v_lshl_add_u64 v[234:235], s[74:75], 0, v[128:129]
	s_add_i32 m0, s5, 0xc000
	v_lshl_add_u64 v[236:237], s[74:75], 0, v[130:131]
	global_load_lds_dwordx4 v[234:235], off
	s_add_i32 m0, s5, 0xe000
	v_lshl_add_u64 v[238:239], s[2:3], 0, v[144:145]
	global_load_lds_dwordx4 v[236:237], off
	s_add_i32 m0, s5, 0x18000
	v_lshl_add_u64 v[240:241], s[2:3], 0, v[132:133]
	global_load_lds_dwordx4 v[238:239], off
	s_add_i32 m0, s5, 0x1a000
	s_add_u32 s74, s74, 0x80
	s_addc_u32 s75, s75, 0
	global_load_lds_dwordx4 v[240:241], off
	s_add_u32 s2, s2, 0x80
	s_addc_u32 s3, s3, 0
	s_waitcnt vmcnt(8)
	s_waitcnt lgkmcnt(0)
	s_barrier
	v_mfma_f32_16x16x32_bf16 v[116:119], v[176:179], v[202:205], v[116:119]
	v_mfma_f32_16x16x32_bf16 v[112:115], v[194:197], v[202:205], v[112:115]
	v_mfma_f32_16x16x32_bf16 v[100:103], v[176:179], v[210:213], v[100:103]
	v_mfma_f32_16x16x32_bf16 v[96:99], v[194:197], v[210:213], v[96:99]
	v_mfma_f32_16x16x32_bf16 v[84:87], v[176:179], v[218:221], v[84:87]
	v_mfma_f32_16x16x32_bf16 v[80:83], v[194:197], v[218:221], v[80:83]
	v_mfma_f32_16x16x32_bf16 v[68:71], v[176:179], v[226:229], v[68:71]
	v_mfma_f32_16x16x32_bf16 v[64:67], v[194:197], v[226:229], v[64:67]
	v_mfma_f32_16x16x32_bf16 v[116:119], v[190:193], v[206:209], v[116:119]
	v_mfma_f32_16x16x32_bf16 v[112:115], v[198:201], v[206:209], v[112:115]
	v_mfma_f32_16x16x32_bf16 v[100:103], v[190:193], v[214:217], v[100:103]
	v_mfma_f32_16x16x32_bf16 v[96:99], v[198:201], v[214:217], v[96:99]
	v_mfma_f32_16x16x32_bf16 v[84:87], v[190:193], v[222:225], v[84:87]
	v_mfma_f32_16x16x32_bf16 v[80:83], v[198:201], v[222:225], v[80:83]
	v_mfma_f32_16x16x32_bf16 v[68:71], v[190:193], v[230:233], v[68:71]
	v_mfma_f32_16x16x32_bf16 v[64:67], v[198:201], v[230:233], v[64:67]
	s_barrier
	v_add_u32_e32 v142, 0x1c000, v160
	ds_read_b128 v[176:179], v142
	ds_read_b128 v[190:193], v142 offset:1024
	ds_read_b128 v[194:197], v142 offset:2048
	ds_read_b128 v[198:201], v142 offset:3072
	ds_read_b128 v[202:205], v162 offset:32768
	ds_read_b128 v[206:209], v162 offset:33792
	ds_read_b128 v[210:213], v162 offset:34816
	ds_read_b128 v[214:217], v162 offset:35840
	ds_read_b128 v[218:221], v162 offset:36864
	ds_read_b128 v[222:225], v162 offset:37888
	ds_read_b128 v[226:229], v162 offset:38912
	ds_read_b128 v[230:233], v162 offset:39936
	s_waitcnt vmcnt(4)
	s_waitcnt lgkmcnt(0)
	s_barrier
	v_mfma_f32_16x16x32_bf16 v[116:119], v[176:179], v[202:205], v[116:119]
	v_mfma_f32_16x16x32_bf16 v[112:115], v[194:197], v[202:205], v[112:115]
	v_mfma_f32_16x16x32_bf16 v[100:103], v[176:179], v[210:213], v[100:103]
	v_mfma_f32_16x16x32_bf16 v[96:99], v[194:197], v[210:213], v[96:99]
	v_mfma_f32_16x16x32_bf16 v[84:87], v[176:179], v[218:221], v[84:87]
	v_mfma_f32_16x16x32_bf16 v[80:83], v[194:197], v[218:221], v[80:83]
	v_mfma_f32_16x16x32_bf16 v[68:71], v[176:179], v[226:229], v[68:71]
	v_mfma_f32_16x16x32_bf16 v[64:67], v[194:197], v[226:229], v[64:67]
	v_mfma_f32_16x16x32_bf16 v[116:119], v[190:193], v[206:209], v[116:119]
	v_mfma_f32_16x16x32_bf16 v[112:115], v[198:201], v[206:209], v[112:115]
	v_mfma_f32_16x16x32_bf16 v[100:103], v[190:193], v[214:217], v[100:103]
	v_mfma_f32_16x16x32_bf16 v[96:99], v[198:201], v[214:217], v[96:99]
	v_mfma_f32_16x16x32_bf16 v[84:87], v[190:193], v[222:225], v[84:87]
	v_mfma_f32_16x16x32_bf16 v[80:83], v[198:201], v[222:225], v[80:83]
	v_mfma_f32_16x16x32_bf16 v[68:71], v[190:193], v[230:233], v[68:71]
	v_mfma_f32_16x16x32_bf16 v[64:67], v[198:201], v[230:233], v[64:67]
	s_barrier
	v_add_u32_e32 v142, 0x10000, v160
	ds_read_b128 v[176:179], v142
	ds_read_b128 v[190:193], v142 offset:1024
	ds_read_b128 v[194:197], v142 offset:2048
	ds_read_b128 v[198:201], v142 offset:3072
	ds_read_b128 v[202:205], v162 offset:16384
	ds_read_b128 v[206:209], v162 offset:17408
	ds_read_b128 v[210:213], v162 offset:18432
	ds_read_b128 v[214:217], v162 offset:19456
	ds_read_b128 v[218:221], v162 offset:20480
	ds_read_b128 v[222:225], v162 offset:21504
	ds_read_b128 v[226:229], v162 offset:22528
	ds_read_b128 v[230:233], v162 offset:23552
	s_waitcnt vmcnt(0)
	s_waitcnt lgkmcnt(0)
	s_barrier
	v_mfma_f32_16x16x32_bf16 v[116:119], v[176:179], v[202:205], v[116:119]
	v_mfma_f32_16x16x32_bf16 v[112:115], v[194:197], v[202:205], v[112:115]
	v_mfma_f32_16x16x32_bf16 v[100:103], v[176:179], v[210:213], v[100:103]
	v_mfma_f32_16x16x32_bf16 v[96:99], v[194:197], v[210:213], v[96:99]
	v_mfma_f32_16x16x32_bf16 v[84:87], v[176:179], v[218:221], v[84:87]
	v_mfma_f32_16x16x32_bf16 v[80:83], v[194:197], v[218:221], v[80:83]
	v_mfma_f32_16x16x32_bf16 v[68:71], v[176:179], v[226:229], v[68:71]
	v_mfma_f32_16x16x32_bf16 v[64:67], v[194:197], v[226:229], v[64:67]
	v_mfma_f32_16x16x32_bf16 v[116:119], v[190:193], v[206:209], v[116:119]
	v_mfma_f32_16x16x32_bf16 v[112:115], v[198:201], v[206:209], v[112:115]
	v_mfma_f32_16x16x32_bf16 v[100:103], v[190:193], v[214:217], v[100:103]
	v_mfma_f32_16x16x32_bf16 v[96:99], v[198:201], v[214:217], v[96:99]
	v_mfma_f32_16x16x32_bf16 v[84:87], v[190:193], v[222:225], v[84:87]
	v_mfma_f32_16x16x32_bf16 v[80:83], v[198:201], v[222:225], v[80:83]
	v_mfma_f32_16x16x32_bf16 v[68:71], v[190:193], v[230:233], v[68:71]
	v_mfma_f32_16x16x32_bf16 v[64:67], v[198:201], v[230:233], v[64:67]
	s_barrier
	v_add_u32_e32 v142, 0x18000, v160
	ds_read_b128 v[176:179], v142
	ds_read_b128 v[190:193], v142 offset:1024
	ds_read_b128 v[194:197], v142 offset:2048
	ds_read_b128 v[198:201], v142 offset:3072
	ds_read_b128 v[202:205], v162 offset:49152
	ds_read_b128 v[206:209], v162 offset:50176
	ds_read_b128 v[210:213], v162 offset:51200
	ds_read_b128 v[214:217], v162 offset:52224
	ds_read_b128 v[218:221], v162 offset:53248
	ds_read_b128 v[222:225], v162 offset:54272
	ds_read_b128 v[226:229], v162 offset:55296
	ds_read_b128 v[230:233], v162 offset:56320
	s_waitcnt lgkmcnt(0)
	s_barrier
	v_mfma_f32_16x16x32_bf16 v[116:119], v[176:179], v[202:205], v[116:119]
	v_mfma_f32_16x16x32_bf16 v[112:115], v[194:197], v[202:205], v[112:115]
	v_mfma_f32_16x16x32_bf16 v[100:103], v[176:179], v[210:213], v[100:103]
	v_mfma_f32_16x16x32_bf16 v[96:99], v[194:197], v[210:213], v[96:99]
	v_mfma_f32_16x16x32_bf16 v[84:87], v[176:179], v[218:221], v[84:87]
	v_mfma_f32_16x16x32_bf16 v[80:83], v[194:197], v[218:221], v[80:83]
	v_mfma_f32_16x16x32_bf16 v[68:71], v[176:179], v[226:229], v[68:71]
	v_mfma_f32_16x16x32_bf16 v[64:67], v[194:197], v[226:229], v[64:67]
	v_mfma_f32_16x16x32_bf16 v[116:119], v[190:193], v[206:209], v[116:119]
	v_mfma_f32_16x16x32_bf16 v[112:115], v[198:201], v[206:209], v[112:115]
	v_mfma_f32_16x16x32_bf16 v[100:103], v[190:193], v[214:217], v[100:103]
	v_mfma_f32_16x16x32_bf16 v[96:99], v[198:201], v[214:217], v[96:99]
	v_mfma_f32_16x16x32_bf16 v[84:87], v[190:193], v[222:225], v[84:87]
	v_mfma_f32_16x16x32_bf16 v[80:83], v[198:201], v[222:225], v[80:83]
	v_mfma_f32_16x16x32_bf16 v[68:71], v[190:193], v[230:233], v[68:71]
	v_mfma_f32_16x16x32_bf16 v[64:67], v[198:201], v[230:233], v[64:67]
	s_barrier
	s_branch .Lq_abi_exit

.Lq_abi_2_k:
	v_add_u32_e32 v142, 0x10000, v160
	ds_read_b128 v[138:141], v142
	ds_read_b128 v[164:167], v142 offset:1024
	ds_read_b128 v[168:171], v142 offset:2048
	ds_read_b128 v[172:175], v142 offset:3072
	ds_read_b128 v[202:205], v162 offset:16384
	ds_read_b128 v[206:209], v162 offset:17408
	ds_read_b128 v[210:213], v162 offset:18432
	ds_read_b128 v[214:217], v162 offset:19456
	ds_read_b128 v[218:221], v162 offset:20480
	ds_read_b128 v[222:225], v162 offset:21504
	ds_read_b128 v[226:229], v162 offset:22528
	ds_read_b128 v[230:233], v162 offset:23552
	v_lshl_add_u64 v[234:235], s[74:75], 0, v[128:129]
	s_add_i32 m0, s5, 0x8000
	v_lshl_add_u64 v[236:237], s[74:75], 0, v[130:131]
	global_load_lds_dwordx4 v[234:235], off
	s_add_i32 m0, s5, 0xa000
	v_lshl_add_u64 v[238:239], s[2:3], 0, v[144:145]
	global_load_lds_dwordx4 v[236:237], off
	s_add_i32 m0, s5, 0x1c000
	v_lshl_add_u64 v[240:241], s[2:3], 0, v[132:133]
	global_load_lds_dwordx4 v[238:239], off
	s_add_i32 m0, s5, 0x1e000
	s_add_u32 s74, s74, 0x80
	s_addc_u32 s75, s75, 0
	global_load_lds_dwordx4 v[240:241], off
	s_add_u32 s2, s2, 0x80
	s_addc_u32 s3, s3, 0
	s_waitcnt vmcnt(8)
	s_waitcnt lgkmcnt(0)
	s_barrier
	v_mfma_f32_16x16x32_bf16 v[60:63], v[138:141], v[202:205], v[60:63]
	v_mfma_f32_16x16x32_bf16 v[56:59], v[168:171], v[202:205], v[56:59]
	v_mfma_f32_16x16x32_bf16 v[44:47], v[138:141], v[210:213], v[44:47]
	v_mfma_f32_16x16x32_bf16 v[40:43], v[168:171], v[210:213], v[40:43]
	v_mfma_f32_16x16x32_bf16 v[28:31], v[138:141], v[218:221], v[28:31]
	v_mfma_f32_16x16x32_bf16 v[24:27], v[168:171], v[218:221], v[24:27]
	v_mfma_f32_16x16x32_bf16 v[12:15], v[138:141], v[226:229], v[12:15]
	v_mfma_f32_16x16x32_bf16 v[8:11], v[168:171], v[226:229], v[8:11]
	v_mfma_f32_16x16x32_bf16 v[60:63], v[164:167], v[206:209], v[60:63]
	v_mfma_f32_16x16x32_bf16 v[56:59], v[172:175], v[206:209], v[56:59]
	v_mfma_f32_16x16x32_bf16 v[44:47], v[164:167], v[214:217], v[44:47]
	v_mfma_f32_16x16x32_bf16 v[40:43], v[172:175], v[214:217], v[40:43]
	v_mfma_f32_16x16x32_bf16 v[28:31], v[164:167], v[222:225], v[28:31]
	v_mfma_f32_16x16x32_bf16 v[24:27], v[172:175], v[222:225], v[24:27]
	v_mfma_f32_16x16x32_bf16 v[12:15], v[164:167], v[230:233], v[12:15]
	v_mfma_f32_16x16x32_bf16 v[8:11], v[172:175], v[230:233], v[8:11]
	s_barrier
	v_add_u32_e32 v142, 0x18000, v160
	ds_read_b128 v[138:141], v142
	ds_read_b128 v[164:167], v142 offset:1024
	ds_read_b128 v[168:171], v142 offset:2048
	ds_read_b128 v[172:175], v142 offset:3072
	ds_read_b128 v[202:205], v162 offset:49152
	ds_read_b128 v[206:209], v162 offset:50176
	ds_read_b128 v[210:213], v162 offset:51200
	ds_read_b128 v[214:217], v162 offset:52224
	ds_read_b128 v[218:221], v162 offset:53248
	ds_read_b128 v[222:225], v162 offset:54272
	ds_read_b128 v[226:229], v162 offset:55296
	ds_read_b128 v[230:233], v162 offset:56320
	v_lshl_add_u64 v[234:235], s[74:75], 0, v[128:129]
	s_add_i32 m0, s5, 0x4000
	v_lshl_add_u64 v[236:237], s[74:75], 0, v[130:131]
	global_load_lds_dwordx4 v[234:235], off
	s_add_i32 m0, s5, 0x6000
	v_lshl_add_u64 v[238:239], s[2:3], 0, v[144:145]
	global_load_lds_dwordx4 v[236:237], off
	s_add_i32 m0, s5, 0x10000
	v_lshl_add_u64 v[240:241], s[2:3], 0, v[132:133]
	global_load_lds_dwordx4 v[238:239], off
	s_add_i32 m0, s5, 0x12000
	s_add_u32 s74, s74, 0x80
	s_addc_u32 s75, s75, 0
	global_load_lds_dwordx4 v[240:241], off
	s_add_u32 s2, s2, 0x80
	s_addc_u32 s3, s3, 0
	s_waitcnt vmcnt(8)
	s_waitcnt lgkmcnt(0)
	s_barrier
	v_mfma_f32_16x16x32_bf16 v[60:63], v[138:141], v[202:205], v[60:63]
	v_mfma_f32_16x16x32_bf16 v[56:59], v[168:171], v[202:205], v[56:59]
	v_mfma_f32_16x16x32_bf16 v[44:47], v[138:141], v[210:213], v[44:47]
	v_mfma_f32_16x16x32_bf16 v[40:43], v[168:171], v[210:213], v[40:43]
	v_mfma_f32_16x16x32_bf16 v[28:31], v[138:141], v[218:221], v[28:31]
	v_mfma_f32_16x16x32_bf16 v[24:27], v[168:171], v[218:221], v[24:27]
	v_mfma_f32_16x16x32_bf16 v[12:15], v[138:141], v[226:229], v[12:15]
	v_mfma_f32_16x16x32_bf16 v[8:11], v[168:171], v[226:229], v[8:11]
	v_mfma_f32_16x16x32_bf16 v[60:63], v[164:167], v[206:209], v[60:63]
	v_mfma_f32_16x16x32_bf16 v[56:59], v[172:175], v[206:209], v[56:59]
	v_mfma_f32_16x16x32_bf16 v[44:47], v[164:167], v[214:217], v[44:47]
	v_mfma_f32_16x16x32_bf16 v[40:43], v[172:175], v[214:217], v[40:43]
	v_mfma_f32_16x16x32_bf16 v[28:31], v[164:167], v[222:225], v[28:31]
	v_mfma_f32_16x16x32_bf16 v[24:27], v[172:175], v[222:225], v[24:27]
	v_mfma_f32_16x16x32_bf16 v[12:15], v[164:167], v[230:233], v[12:15]
	v_mfma_f32_16x16x32_bf16 v[8:11], v[172:175], v[230:233], v[8:11]
	s_barrier
	v_add_u32_e32 v142, 0x14000, v160
	ds_read_b128 v[138:141], v142
	ds_read_b128 v[164:167], v142 offset:1024
	ds_read_b128 v[168:171], v142 offset:2048
	ds_read_b128 v[172:175], v142 offset:3072
	ds_read_b128 v[202:205], v162 offset:0
	ds_read_b128 v[206:209], v162 offset:1024
	ds_read_b128 v[210:213], v162 offset:2048
	ds_read_b128 v[214:217], v162 offset:3072
	ds_read_b128 v[218:221], v162 offset:4096
	ds_read_b128 v[222:225], v162 offset:5120
	ds_read_b128 v[226:229], v162 offset:6144
	ds_read_b128 v[230:233], v162 offset:7168
	v_lshl_add_u64 v[234:235], s[74:75], 0, v[128:129]
	s_add_i32 m0, s5, 0xc000
	v_lshl_add_u64 v[236:237], s[74:75], 0, v[130:131]
	global_load_lds_dwordx4 v[234:235], off
	s_add_i32 m0, s5, 0xe000
	v_lshl_add_u64 v[238:239], s[2:3], 0, v[144:145]
	global_load_lds_dwordx4 v[236:237], off
	s_add_i32 m0, s5, 0x18000
	v_lshl_add_u64 v[240:241], s[2:3], 0, v[132:133]
	global_load_lds_dwordx4 v[238:239], off
	s_add_i32 m0, s5, 0x1a000
	s_add_u32 s74, s74, 0x80
	s_addc_u32 s75, s75, 0
	global_load_lds_dwordx4 v[240:241], off
	s_add_u32 s2, s2, 0x80
	s_addc_u32 s3, s3, 0
	s_waitcnt vmcnt(8)
	s_waitcnt lgkmcnt(0)
	s_barrier
	v_mfma_f32_16x16x32_bf16 v[60:63], v[138:141], v[202:205], v[60:63]
	v_mfma_f32_16x16x32_bf16 v[56:59], v[168:171], v[202:205], v[56:59]
	v_mfma_f32_16x16x32_bf16 v[44:47], v[138:141], v[210:213], v[44:47]
	v_mfma_f32_16x16x32_bf16 v[40:43], v[168:171], v[210:213], v[40:43]
	v_mfma_f32_16x16x32_bf16 v[28:31], v[138:141], v[218:221], v[28:31]
	v_mfma_f32_16x16x32_bf16 v[24:27], v[168:171], v[218:221], v[24:27]
	v_mfma_f32_16x16x32_bf16 v[12:15], v[138:141], v[226:229], v[12:15]
	v_mfma_f32_16x16x32_bf16 v[8:11], v[168:171], v[226:229], v[8:11]
	v_mfma_f32_16x16x32_bf16 v[60:63], v[164:167], v[206:209], v[60:63]
	v_mfma_f32_16x16x32_bf16 v[56:59], v[172:175], v[206:209], v[56:59]
	v_mfma_f32_16x16x32_bf16 v[44:47], v[164:167], v[214:217], v[44:47]
	v_mfma_f32_16x16x32_bf16 v[40:43], v[172:175], v[214:217], v[40:43]
	v_mfma_f32_16x16x32_bf16 v[28:31], v[164:167], v[222:225], v[28:31]
	v_mfma_f32_16x16x32_bf16 v[24:27], v[172:175], v[222:225], v[24:27]
	v_mfma_f32_16x16x32_bf16 v[12:15], v[164:167], v[230:233], v[12:15]
	v_mfma_f32_16x16x32_bf16 v[8:11], v[172:175], v[230:233], v[8:11]
	s_barrier
	v_add_u32_e32 v142, 0x1c000, v160
	ds_read_b128 v[138:141], v142
	ds_read_b128 v[164:167], v142 offset:1024
	ds_read_b128 v[168:171], v142 offset:2048
	ds_read_b128 v[172:175], v142 offset:3072
	ds_read_b128 v[202:205], v162 offset:32768
	ds_read_b128 v[206:209], v162 offset:33792
	ds_read_b128 v[210:213], v162 offset:34816
	ds_read_b128 v[214:217], v162 offset:35840
	ds_read_b128 v[218:221], v162 offset:36864
	ds_read_b128 v[222:225], v162 offset:37888
	ds_read_b128 v[226:229], v162 offset:38912
	ds_read_b128 v[230:233], v162 offset:39936
	v_lshl_add_u64 v[234:235], s[74:75], 0, v[128:129]
	s_add_i32 m0, s5, 0x0
	v_lshl_add_u64 v[236:237], s[74:75], 0, v[130:131]
	global_load_lds_dwordx4 v[234:235], off
	s_add_i32 m0, s5, 0x2000
	v_lshl_add_u64 v[238:239], s[2:3], 0, v[144:145]
	global_load_lds_dwordx4 v[236:237], off
	s_add_i32 m0, s5, 0x14000
	v_lshl_add_u64 v[240:241], s[2:3], 0, v[132:133]
	global_load_lds_dwordx4 v[238:239], off
	s_add_i32 m0, s5, 0x16000
	s_add_u32 s74, s74, 0x80
	s_addc_u32 s75, s75, 0
	global_load_lds_dwordx4 v[240:241], off
	s_add_u32 s2, s2, 0x80
	s_addc_u32 s3, s3, 0
	s_waitcnt vmcnt(8)
	s_waitcnt lgkmcnt(0)
	s_barrier
	v_mfma_f32_16x16x32_bf16 v[60:63], v[138:141], v[202:205], v[60:63]
	v_mfma_f32_16x16x32_bf16 v[56:59], v[168:171], v[202:205], v[56:59]
	v_mfma_f32_16x16x32_bf16 v[44:47], v[138:141], v[210:213], v[44:47]
	v_mfma_f32_16x16x32_bf16 v[40:43], v[168:171], v[210:213], v[40:43]
	v_mfma_f32_16x16x32_bf16 v[28:31], v[138:141], v[218:221], v[28:31]
	v_mfma_f32_16x16x32_bf16 v[24:27], v[168:171], v[218:221], v[24:27]
	v_mfma_f32_16x16x32_bf16 v[12:15], v[138:141], v[226:229], v[12:15]
	v_mfma_f32_16x16x32_bf16 v[8:11], v[168:171], v[226:229], v[8:11]
	v_mfma_f32_16x16x32_bf16 v[60:63], v[164:167], v[206:209], v[60:63]
	v_mfma_f32_16x16x32_bf16 v[56:59], v[172:175], v[206:209], v[56:59]
	v_mfma_f32_16x16x32_bf16 v[44:47], v[164:167], v[214:217], v[44:47]
	v_mfma_f32_16x16x32_bf16 v[40:43], v[172:175], v[214:217], v[40:43]
	v_mfma_f32_16x16x32_bf16 v[28:31], v[164:167], v[222:225], v[28:31]
	v_mfma_f32_16x16x32_bf16 v[24:27], v[172:175], v[222:225], v[24:27]
	v_mfma_f32_16x16x32_bf16 v[12:15], v[164:167], v[230:233], v[12:15]
	v_mfma_f32_16x16x32_bf16 v[8:11], v[172:175], v[230:233], v[8:11]
	s_barrier
	s_add_i32 s8, s8, 1
	s_cmp_lt_u32 s8, 7
	s_cbranch_scc1 .Lq_abi_2_k
	v_add_u32_e32 v142, 0x10000, v160
	ds_read_b128 v[138:141], v142
	ds_read_b128 v[164:167], v142 offset:1024
	ds_read_b128 v[168:171], v142 offset:2048
	ds_read_b128 v[172:175], v142 offset:3072
	ds_read_b128 v[202:205], v162 offset:16384
	ds_read_b128 v[206:209], v162 offset:17408
	ds_read_b128 v[210:213], v162 offset:18432
	ds_read_b128 v[214:217], v162 offset:19456
	ds_read_b128 v[218:221], v162 offset:20480
	ds_read_b128 v[222:225], v162 offset:21504
	ds_read_b128 v[226:229], v162 offset:22528
	ds_read_b128 v[230:233], v162 offset:23552
	v_lshl_add_u64 v[234:235], s[74:75], 0, v[128:129]
	s_add_i32 m0, s5, 0x8000
	v_lshl_add_u64 v[236:237], s[74:75], 0, v[130:131]
	global_load_lds_dwordx4 v[234:235], off
	s_add_i32 m0, s5, 0xa000
	v_lshl_add_u64 v[238:239], s[2:3], 0, v[144:145]
	global_load_lds_dwordx4 v[236:237], off
	s_add_i32 m0, s5, 0x1c000
	v_lshl_add_u64 v[240:241], s[2:3], 0, v[132:133]
	global_load_lds_dwordx4 v[238:239], off
	s_add_i32 m0, s5, 0x1e000
	s_add_u32 s74, s74, 0x80
	s_addc_u32 s75, s75, 0
	global_load_lds_dwordx4 v[240:241], off
	s_add_u32 s2, s2, 0x80
	s_addc_u32 s3, s3, 0
	s_waitcnt vmcnt(8)
	s_waitcnt lgkmcnt(0)
	s_barrier
	v_mfma_f32_16x16x32_bf16 v[60:63], v[138:141], v[202:205], v[60:63]
	v_mfma_f32_16x16x32_bf16 v[56:59], v[168:171], v[202:205], v[56:59]
	v_mfma_f32_16x16x32_bf16 v[44:47], v[138:141], v[210:213], v[44:47]
	v_mfma_f32_16x16x32_bf16 v[40:43], v[168:171], v[210:213], v[40:43]
	v_mfma_f32_16x16x32_bf16 v[28:31], v[138:141], v[218:221], v[28:31]
	v_mfma_f32_16x16x32_bf16 v[24:27], v[168:171], v[218:221], v[24:27]
	v_mfma_f32_16x16x32_bf16 v[12:15], v[138:141], v[226:229], v[12:15]
	v_mfma_f32_16x16x32_bf16 v[8:11], v[168:171], v[226:229], v[8:11]
	v_mfma_f32_16x16x32_bf16 v[60:63], v[164:167], v[206:209], v[60:63]
	v_mfma_f32_16x16x32_bf16 v[56:59], v[172:175], v[206:209], v[56:59]
	v_mfma_f32_16x16x32_bf16 v[44:47], v[164:167], v[214:217], v[44:47]
	v_mfma_f32_16x16x32_bf16 v[40:43], v[172:175], v[214:217], v[40:43]
	v_mfma_f32_16x16x32_bf16 v[28:31], v[164:167], v[222:225], v[28:31]
	v_mfma_f32_16x16x32_bf16 v[24:27], v[172:175], v[222:225], v[24:27]
	v_mfma_f32_16x16x32_bf16 v[12:15], v[164:167], v[230:233], v[12:15]
	v_mfma_f32_16x16x32_bf16 v[8:11], v[172:175], v[230:233], v[8:11]
	s_barrier
	v_add_u32_e32 v142, 0x18000, v160
	ds_read_b128 v[138:141], v142
	ds_read_b128 v[164:167], v142 offset:1024
	ds_read_b128 v[168:171], v142 offset:2048
	ds_read_b128 v[172:175], v142 offset:3072
	ds_read_b128 v[202:205], v162 offset:49152
	ds_read_b128 v[206:209], v162 offset:50176
	ds_read_b128 v[210:213], v162 offset:51200
	ds_read_b128 v[214:217], v162 offset:52224
	ds_read_b128 v[218:221], v162 offset:53248
	ds_read_b128 v[222:225], v162 offset:54272
	ds_read_b128 v[226:229], v162 offset:55296
	ds_read_b128 v[230:233], v162 offset:56320
	s_waitcnt vmcnt(4)
	s_waitcnt lgkmcnt(0)
	s_barrier
	v_mfma_f32_16x16x32_bf16 v[60:63], v[138:141], v[202:205], v[60:63]
	v_mfma_f32_16x16x32_bf16 v[56:59], v[168:171], v[202:205], v[56:59]
	v_mfma_f32_16x16x32_bf16 v[44:47], v[138:141], v[210:213], v[44:47]
	v_mfma_f32_16x16x32_bf16 v[40:43], v[168:171], v[210:213], v[40:43]
	v_mfma_f32_16x16x32_bf16 v[28:31], v[138:141], v[218:221], v[28:31]
	v_mfma_f32_16x16x32_bf16 v[24:27], v[168:171], v[218:221], v[24:27]
	v_mfma_f32_16x16x32_bf16 v[12:15], v[138:141], v[226:229], v[12:15]
	v_mfma_f32_16x16x32_bf16 v[8:11], v[168:171], v[226:229], v[8:11]
	v_mfma_f32_16x16x32_bf16 v[60:63], v[164:167], v[206:209], v[60:63]
	v_mfma_f32_16x16x32_bf16 v[56:59], v[172:175], v[206:209], v[56:59]
	v_mfma_f32_16x16x32_bf16 v[44:47], v[164:167], v[214:217], v[44:47]
	v_mfma_f32_16x16x32_bf16 v[40:43], v[172:175], v[214:217], v[40:43]
	v_mfma_f32_16x16x32_bf16 v[28:31], v[164:167], v[222:225], v[28:31]
	v_mfma_f32_16x16x32_bf16 v[24:27], v[172:175], v[222:225], v[24:27]
	v_mfma_f32_16x16x32_bf16 v[12:15], v[164:167], v[230:233], v[12:15]
	v_mfma_f32_16x16x32_bf16 v[8:11], v[172:175], v[230:233], v[8:11]
	s_barrier
	v_add_u32_e32 v142, 0x14000, v160
	ds_read_b128 v[138:141], v142
	ds_read_b128 v[164:167], v142 offset:1024
	ds_read_b128 v[168:171], v142 offset:2048
	ds_read_b128 v[172:175], v142 offset:3072
	ds_read_b128 v[202:205], v162 offset:0
	ds_read_b128 v[206:209], v162 offset:1024
	ds_read_b128 v[210:213], v162 offset:2048
	ds_read_b128 v[214:217], v162 offset:3072
	ds_read_b128 v[218:221], v162 offset:4096
	ds_read_b128 v[222:225], v162 offset:5120
	ds_read_b128 v[226:229], v162 offset:6144
	ds_read_b128 v[230:233], v162 offset:7168
	s_waitcnt vmcnt(0)
	s_waitcnt lgkmcnt(0)
	s_barrier
	v_mfma_f32_16x16x32_bf16 v[60:63], v[138:141], v[202:205], v[60:63]
	v_mfma_f32_16x16x32_bf16 v[56:59], v[168:171], v[202:205], v[56:59]
	v_mfma_f32_16x16x32_bf16 v[44:47], v[138:141], v[210:213], v[44:47]
	v_mfma_f32_16x16x32_bf16 v[40:43], v[168:171], v[210:213], v[40:43]
	v_mfma_f32_16x16x32_bf16 v[28:31], v[138:141], v[218:221], v[28:31]
	v_mfma_f32_16x16x32_bf16 v[24:27], v[168:171], v[218:221], v[24:27]
	v_mfma_f32_16x16x32_bf16 v[12:15], v[138:141], v[226:229], v[12:15]
	v_mfma_f32_16x16x32_bf16 v[8:11], v[168:171], v[226:229], v[8:11]
	v_mfma_f32_16x16x32_bf16 v[60:63], v[164:167], v[206:209], v[60:63]
	v_mfma_f32_16x16x32_bf16 v[56:59], v[172:175], v[206:209], v[56:59]
	v_mfma_f32_16x16x32_bf16 v[44:47], v[164:167], v[214:217], v[44:47]
	v_mfma_f32_16x16x32_bf16 v[40:43], v[172:175], v[214:217], v[40:43]
	v_mfma_f32_16x16x32_bf16 v[28:31], v[164:167], v[222:225], v[28:31]
	v_mfma_f32_16x16x32_bf16 v[24:27], v[172:175], v[222:225], v[24:27]
	v_mfma_f32_16x16x32_bf16 v[12:15], v[164:167], v[230:233], v[12:15]
	v_mfma_f32_16x16x32_bf16 v[8:11], v[172:175], v[230:233], v[8:11]
	s_barrier
	v_add_u32_e32 v142, 0x1c000, v160
	ds_read_b128 v[138:141], v142
	ds_read_b128 v[164:167], v142 offset:1024
	ds_read_b128 v[168:171], v142 offset:2048
	ds_read_b128 v[172:175], v142 offset:3072
	ds_read_b128 v[202:205], v162 offset:32768
	ds_read_b128 v[206:209], v162 offset:33792
	ds_read_b128 v[210:213], v162 offset:34816
	ds_read_b128 v[214:217], v162 offset:35840
	ds_read_b128 v[218:221], v162 offset:36864
	ds_read_b128 v[222:225], v162 offset:37888
	ds_read_b128 v[226:229], v162 offset:38912
	ds_read_b128 v[230:233], v162 offset:39936
	s_waitcnt lgkmcnt(0)
	s_barrier
	v_mfma_f32_16x16x32_bf16 v[60:63], v[138:141], v[202:205], v[60:63]
	v_mfma_f32_16x16x32_bf16 v[56:59], v[168:171], v[202:205], v[56:59]
	v_mfma_f32_16x16x32_bf16 v[44:47], v[138:141], v[210:213], v[44:47]
	v_mfma_f32_16x16x32_bf16 v[40:43], v[168:171], v[210:213], v[40:43]
	v_mfma_f32_16x16x32_bf16 v[28:31], v[138:141], v[218:221], v[28:31]
	v_mfma_f32_16x16x32_bf16 v[24:27], v[168:171], v[218:221], v[24:27]
	v_mfma_f32_16x16x32_bf16 v[12:15], v[138:141], v[226:229], v[12:15]
	v_mfma_f32_16x16x32_bf16 v[8:11], v[168:171], v[226:229], v[8:11]
	v_mfma_f32_16x16x32_bf16 v[60:63], v[164:167], v[206:209], v[60:63]
	v_mfma_f32_16x16x32_bf16 v[56:59], v[172:175], v[206:209], v[56:59]
	v_mfma_f32_16x16x32_bf16 v[44:47], v[164:167], v[214:217], v[44:47]
	v_mfma_f32_16x16x32_bf16 v[40:43], v[172:175], v[214:217], v[40:43]
	v_mfma_f32_16x16x32_bf16 v[28:31], v[164:167], v[222:225], v[28:31]
	v_mfma_f32_16x16x32_bf16 v[24:27], v[172:175], v[222:225], v[24:27]
	v_mfma_f32_16x16x32_bf16 v[12:15], v[164:167], v[230:233], v[12:15]
	v_mfma_f32_16x16x32_bf16 v[8:11], v[172:175], v[230:233], v[8:11]
	s_barrier
	s_branch .Lq_abi_exit

.Lq_abi_3_k:
	v_add_u32_e32 v142, 0x14000, v160
	ds_read_b128 v[176:179], v142
	ds_read_b128 v[190:193], v142 offset:1024
	ds_read_b128 v[194:197], v142 offset:2048
	ds_read_b128 v[198:201], v142 offset:3072
	ds_read_b128 v[202:205], v162 offset:16384
	ds_read_b128 v[206:209], v162 offset:17408
	ds_read_b128 v[210:213], v162 offset:18432
	ds_read_b128 v[214:217], v162 offset:19456
	ds_read_b128 v[218:221], v162 offset:20480
	ds_read_b128 v[222:225], v162 offset:21504
	ds_read_b128 v[226:229], v162 offset:22528
	ds_read_b128 v[230:233], v162 offset:23552
	v_lshl_add_u64 v[234:235], s[74:75], 0, v[128:129]
	s_add_i32 m0, s5, 0x8000
	v_lshl_add_u64 v[236:237], s[74:75], 0, v[130:131]
	global_load_lds_dwordx4 v[234:235], off
	s_add_i32 m0, s5, 0xa000
	v_lshl_add_u64 v[238:239], s[2:3], 0, v[144:145]
	global_load_lds_dwordx4 v[236:237], off
	s_add_i32 m0, s5, 0x18000
	v_lshl_add_u64 v[240:241], s[2:3], 0, v[132:133]
	global_load_lds_dwordx4 v[238:239], off
	s_add_i32 m0, s5, 0x1a000
	s_add_u32 s74, s74, 0x80
	s_addc_u32 s75, s75, 0
	global_load_lds_dwordx4 v[240:241], off
	s_add_u32 s2, s2, 0x80
	s_addc_u32 s3, s3, 0
	s_waitcnt vmcnt(8)
	s_waitcnt lgkmcnt(0)
	s_barrier
	v_mfma_f32_16x16x32_bf16 v[52:55], v[176:179], v[202:205], v[52:55]
	v_mfma_f32_16x16x32_bf16 v[48:51], v[194:197], v[202:205], v[48:51]
	v_mfma_f32_16x16x32_bf16 v[36:39], v[176:179], v[210:213], v[36:39]
	v_mfma_f32_16x16x32_bf16 v[32:35], v[194:197], v[210:213], v[32:35]
	v_mfma_f32_16x16x32_bf16 v[20:23], v[176:179], v[218:221], v[20:23]
	v_mfma_f32_16x16x32_bf16 v[16:19], v[194:197], v[218:221], v[16:19]
	v_mfma_f32_16x16x32_bf16 v[4:7], v[176:179], v[226:229], v[4:7]
	v_mfma_f32_16x16x32_bf16 v[0:3], v[194:197], v[226:229], v[0:3]
	v_mfma_f32_16x16x32_bf16 v[52:55], v[190:193], v[206:209], v[52:55]
	v_mfma_f32_16x16x32_bf16 v[48:51], v[198:201], v[206:209], v[48:51]
	v_mfma_f32_16x16x32_bf16 v[36:39], v[190:193], v[214:217], v[36:39]
	v_mfma_f32_16x16x32_bf16 v[32:35], v[198:201], v[214:217], v[32:35]
	v_mfma_f32_16x16x32_bf16 v[20:23], v[190:193], v[222:225], v[20:23]
	v_mfma_f32_16x16x32_bf16 v[16:19], v[198:201], v[222:225], v[16:19]
	v_mfma_f32_16x16x32_bf16 v[4:7], v[190:193], v[230:233], v[4:7]
	v_mfma_f32_16x16x32_bf16 v[0:3], v[198:201], v[230:233], v[0:3]
	s_barrier
	v_add_u32_e32 v142, 0x1c000, v160
	ds_read_b128 v[176:179], v142
	ds_read_b128 v[190:193], v142 offset:1024
	ds_read_b128 v[194:197], v142 offset:2048
	ds_read_b128 v[198:201], v142 offset:3072
	ds_read_b128 v[202:205], v162 offset:49152
	ds_read_b128 v[206:209], v162 offset:50176
	ds_read_b128 v[210:213], v162 offset:51200
	ds_read_b128 v[214:217], v162 offset:52224
	ds_read_b128 v[218:221], v162 offset:53248
	ds_read_b128 v[222:225], v162 offset:54272
	ds_read_b128 v[226:229], v162 offset:55296
	ds_read_b128 v[230:233], v162 offset:56320
	v_lshl_add_u64 v[234:235], s[74:75], 0, v[128:129]
	s_add_i32 m0, s5, 0x4000
	v_lshl_add_u64 v[236:237], s[74:75], 0, v[130:131]
	global_load_lds_dwordx4 v[234:235], off
	s_add_i32 m0, s5, 0x6000
	v_lshl_add_u64 v[238:239], s[2:3], 0, v[144:145]
	global_load_lds_dwordx4 v[236:237], off
	s_add_i32 m0, s5, 0x14000
	v_lshl_add_u64 v[240:241], s[2:3], 0, v[132:133]
	global_load_lds_dwordx4 v[238:239], off
	s_add_i32 m0, s5, 0x16000
	s_add_u32 s74, s74, 0x80
	s_addc_u32 s75, s75, 0
	global_load_lds_dwordx4 v[240:241], off
	s_add_u32 s2, s2, 0x80
	s_addc_u32 s3, s3, 0
	s_waitcnt vmcnt(8)
	s_waitcnt lgkmcnt(0)
	s_barrier
	v_mfma_f32_16x16x32_bf16 v[52:55], v[176:179], v[202:205], v[52:55]
	v_mfma_f32_16x16x32_bf16 v[48:51], v[194:197], v[202:205], v[48:51]
	v_mfma_f32_16x16x32_bf16 v[36:39], v[176:179], v[210:213], v[36:39]
	v_mfma_f32_16x16x32_bf16 v[32:35], v[194:197], v[210:213], v[32:35]
	v_mfma_f32_16x16x32_bf16 v[20:23], v[176:179], v[218:221], v[20:23]
	v_mfma_f32_16x16x32_bf16 v[16:19], v[194:197], v[218:221], v[16:19]
	v_mfma_f32_16x16x32_bf16 v[4:7], v[176:179], v[226:229], v[4:7]
	v_mfma_f32_16x16x32_bf16 v[0:3], v[194:197], v[226:229], v[0:3]
	v_mfma_f32_16x16x32_bf16 v[52:55], v[190:193], v[206:209], v[52:55]
	v_mfma_f32_16x16x32_bf16 v[48:51], v[198:201], v[206:209], v[48:51]
	v_mfma_f32_16x16x32_bf16 v[36:39], v[190:193], v[214:217], v[36:39]
	v_mfma_f32_16x16x32_bf16 v[32:35], v[198:201], v[214:217], v[32:35]
	v_mfma_f32_16x16x32_bf16 v[20:23], v[190:193], v[222:225], v[20:23]
	v_mfma_f32_16x16x32_bf16 v[16:19], v[198:201], v[222:225], v[16:19]
	v_mfma_f32_16x16x32_bf16 v[4:7], v[190:193], v[230:233], v[4:7]
	v_mfma_f32_16x16x32_bf16 v[0:3], v[198:201], v[230:233], v[0:3]
	s_barrier
	v_add_u32_e32 v142, 0x10000, v160
	ds_read_b128 v[176:179], v142
	ds_read_b128 v[190:193], v142 offset:1024
	ds_read_b128 v[194:197], v142 offset:2048
	ds_read_b128 v[198:201], v142 offset:3072
	ds_read_b128 v[202:205], v162 offset:0
	ds_read_b128 v[206:209], v162 offset:1024
	ds_read_b128 v[210:213], v162 offset:2048
	ds_read_b128 v[214:217], v162 offset:3072
	ds_read_b128 v[218:221], v162 offset:4096
	ds_read_b128 v[222:225], v162 offset:5120
	ds_read_b128 v[226:229], v162 offset:6144
	ds_read_b128 v[230:233], v162 offset:7168
	v_lshl_add_u64 v[234:235], s[74:75], 0, v[128:129]
	s_add_i32 m0, s5, 0xc000
	v_lshl_add_u64 v[236:237], s[74:75], 0, v[130:131]
	global_load_lds_dwordx4 v[234:235], off
	s_add_i32 m0, s5, 0xe000
	v_lshl_add_u64 v[238:239], s[2:3], 0, v[144:145]
	global_load_lds_dwordx4 v[236:237], off
	s_add_i32 m0, s5, 0x1c000
	v_lshl_add_u64 v[240:241], s[2:3], 0, v[132:133]
	global_load_lds_dwordx4 v[238:239], off
	s_add_i32 m0, s5, 0x1e000
	s_add_u32 s74, s74, 0x80
	s_addc_u32 s75, s75, 0
	global_load_lds_dwordx4 v[240:241], off
	s_add_u32 s2, s2, 0x80
	s_addc_u32 s3, s3, 0
	s_waitcnt vmcnt(8)
	s_waitcnt lgkmcnt(0)
	s_barrier
	v_mfma_f32_16x16x32_bf16 v[52:55], v[176:179], v[202:205], v[52:55]
	v_mfma_f32_16x16x32_bf16 v[48:51], v[194:197], v[202:205], v[48:51]
	v_mfma_f32_16x16x32_bf16 v[36:39], v[176:179], v[210:213], v[36:39]
	v_mfma_f32_16x16x32_bf16 v[32:35], v[194:197], v[210:213], v[32:35]
	v_mfma_f32_16x16x32_bf16 v[20:23], v[176:179], v[218:221], v[20:23]
	v_mfma_f32_16x16x32_bf16 v[16:19], v[194:197], v[218:221], v[16:19]
	v_mfma_f32_16x16x32_bf16 v[4:7], v[176:179], v[226:229], v[4:7]
	v_mfma_f32_16x16x32_bf16 v[0:3], v[194:197], v[226:229], v[0:3]
	v_mfma_f32_16x16x32_bf16 v[52:55], v[190:193], v[206:209], v[52:55]
	v_mfma_f32_16x16x32_bf16 v[48:51], v[198:201], v[206:209], v[48:51]
	v_mfma_f32_16x16x32_bf16 v[36:39], v[190:193], v[214:217], v[36:39]
	v_mfma_f32_16x16x32_bf16 v[32:35], v[198:201], v[214:217], v[32:35]
	v_mfma_f32_16x16x32_bf16 v[20:23], v[190:193], v[222:225], v[20:23]
	v_mfma_f32_16x16x32_bf16 v[16:19], v[198:201], v[222:225], v[16:19]
	v_mfma_f32_16x16x32_bf16 v[4:7], v[190:193], v[230:233], v[4:7]
	v_mfma_f32_16x16x32_bf16 v[0:3], v[198:201], v[230:233], v[0:3]
	s_barrier
	v_add_u32_e32 v142, 0x18000, v160
	ds_read_b128 v[176:179], v142
	ds_read_b128 v[190:193], v142 offset:1024
	ds_read_b128 v[194:197], v142 offset:2048
	ds_read_b128 v[198:201], v142 offset:3072
	ds_read_b128 v[202:205], v162 offset:32768
	ds_read_b128 v[206:209], v162 offset:33792
	ds_read_b128 v[210:213], v162 offset:34816
	ds_read_b128 v[214:217], v162 offset:35840
	ds_read_b128 v[218:221], v162 offset:36864
	ds_read_b128 v[222:225], v162 offset:37888
	ds_read_b128 v[226:229], v162 offset:38912
	ds_read_b128 v[230:233], v162 offset:39936
	v_lshl_add_u64 v[234:235], s[74:75], 0, v[128:129]
	s_add_i32 m0, s5, 0x0
	v_lshl_add_u64 v[236:237], s[74:75], 0, v[130:131]
	global_load_lds_dwordx4 v[234:235], off
	s_add_i32 m0, s5, 0x2000
	v_lshl_add_u64 v[238:239], s[2:3], 0, v[144:145]
	global_load_lds_dwordx4 v[236:237], off
	s_add_i32 m0, s5, 0x10000
	v_lshl_add_u64 v[240:241], s[2:3], 0, v[132:133]
	global_load_lds_dwordx4 v[238:239], off
	s_add_i32 m0, s5, 0x12000
	s_add_u32 s74, s74, 0x80
	s_addc_u32 s75, s75, 0
	global_load_lds_dwordx4 v[240:241], off
	s_add_u32 s2, s2, 0x80
	s_addc_u32 s3, s3, 0
	s_waitcnt vmcnt(8)
	s_waitcnt lgkmcnt(0)
	s_barrier
	v_mfma_f32_16x16x32_bf16 v[52:55], v[176:179], v[202:205], v[52:55]
	v_mfma_f32_16x16x32_bf16 v[48:51], v[194:197], v[202:205], v[48:51]
	v_mfma_f32_16x16x32_bf16 v[36:39], v[176:179], v[210:213], v[36:39]
	v_mfma_f32_16x16x32_bf16 v[32:35], v[194:197], v[210:213], v[32:35]
	v_mfma_f32_16x16x32_bf16 v[20:23], v[176:179], v[218:221], v[20:23]
	v_mfma_f32_16x16x32_bf16 v[16:19], v[194:197], v[218:221], v[16:19]
	v_mfma_f32_16x16x32_bf16 v[4:7], v[176:179], v[226:229], v[4:7]
	v_mfma_f32_16x16x32_bf16 v[0:3], v[194:197], v[226:229], v[0:3]
	v_mfma_f32_16x16x32_bf16 v[52:55], v[190:193], v[206:209], v[52:55]
	v_mfma_f32_16x16x32_bf16 v[48:51], v[198:201], v[206:209], v[48:51]
	v_mfma_f32_16x16x32_bf16 v[36:39], v[190:193], v[214:217], v[36:39]
	v_mfma_f32_16x16x32_bf16 v[32:35], v[198:201], v[214:217], v[32:35]
	v_mfma_f32_16x16x32_bf16 v[20:23], v[190:193], v[222:225], v[20:23]
	v_mfma_f32_16x16x32_bf16 v[16:19], v[198:201], v[222:225], v[16:19]
	v_mfma_f32_16x16x32_bf16 v[4:7], v[190:193], v[230:233], v[4:7]
	v_mfma_f32_16x16x32_bf16 v[0:3], v[198:201], v[230:233], v[0:3]
	s_barrier
	s_add_i32 s8, s8, 1
	s_cmp_lt_u32 s8, 7
	s_cbranch_scc1 .Lq_abi_3_k
	v_add_u32_e32 v142, 0x14000, v160
	ds_read_b128 v[176:179], v142
	ds_read_b128 v[190:193], v142 offset:1024
	ds_read_b128 v[194:197], v142 offset:2048
	ds_read_b128 v[198:201], v142 offset:3072
	ds_read_b128 v[202:205], v162 offset:16384
	ds_read_b128 v[206:209], v162 offset:17408
	ds_read_b128 v[210:213], v162 offset:18432
	ds_read_b128 v[214:217], v162 offset:19456
	ds_read_b128 v[218:221], v162 offset:20480
	ds_read_b128 v[222:225], v162 offset:21504
	ds_read_b128 v[226:229], v162 offset:22528
	ds_read_b128 v[230:233], v162 offset:23552
	v_lshl_add_u64 v[234:235], s[74:75], 0, v[128:129]
	s_add_i32 m0, s5, 0x8000
	v_lshl_add_u64 v[236:237], s[74:75], 0, v[130:131]
	global_load_lds_dwordx4 v[234:235], off
	s_add_i32 m0, s5, 0xa000
	v_lshl_add_u64 v[238:239], s[2:3], 0, v[144:145]
	global_load_lds_dwordx4 v[236:237], off
	s_add_i32 m0, s5, 0x18000
	v_lshl_add_u64 v[240:241], s[2:3], 0, v[132:133]
	global_load_lds_dwordx4 v[238:239], off
	s_add_i32 m0, s5, 0x1a000
	s_add_u32 s74, s74, 0x80
	s_addc_u32 s75, s75, 0
	global_load_lds_dwordx4 v[240:241], off
	s_add_u32 s2, s2, 0x80
	s_addc_u32 s3, s3, 0
	s_waitcnt vmcnt(8)
	s_waitcnt lgkmcnt(0)
	s_barrier
	v_mfma_f32_16x16x32_bf16 v[52:55], v[176:179], v[202:205], v[52:55]
	v_mfma_f32_16x16x32_bf16 v[48:51], v[194:197], v[202:205], v[48:51]
	v_mfma_f32_16x16x32_bf16 v[36:39], v[176:179], v[210:213], v[36:39]
	v_mfma_f32_16x16x32_bf16 v[32:35], v[194:197], v[210:213], v[32:35]
	v_mfma_f32_16x16x32_bf16 v[20:23], v[176:179], v[218:221], v[20:23]
	v_mfma_f32_16x16x32_bf16 v[16:19], v[194:197], v[218:221], v[16:19]
	v_mfma_f32_16x16x32_bf16 v[4:7], v[176:179], v[226:229], v[4:7]
	v_mfma_f32_16x16x32_bf16 v[0:3], v[194:197], v[226:229], v[0:3]
	v_mfma_f32_16x16x32_bf16 v[52:55], v[190:193], v[206:209], v[52:55]
	v_mfma_f32_16x16x32_bf16 v[48:51], v[198:201], v[206:209], v[48:51]
	v_mfma_f32_16x16x32_bf16 v[36:39], v[190:193], v[214:217], v[36:39]
	v_mfma_f32_16x16x32_bf16 v[32:35], v[198:201], v[214:217], v[32:35]
	v_mfma_f32_16x16x32_bf16 v[20:23], v[190:193], v[222:225], v[20:23]
	v_mfma_f32_16x16x32_bf16 v[16:19], v[198:201], v[222:225], v[16:19]
	v_mfma_f32_16x16x32_bf16 v[4:7], v[190:193], v[230:233], v[4:7]
	v_mfma_f32_16x16x32_bf16 v[0:3], v[198:201], v[230:233], v[0:3]
	s_barrier
	v_add_u32_e32 v142, 0x1c000, v160
	ds_read_b128 v[176:179], v142
	ds_read_b128 v[190:193], v142 offset:1024
	ds_read_b128 v[194:197], v142 offset:2048
	ds_read_b128 v[198:201], v142 offset:3072
	ds_read_b128 v[202:205], v162 offset:49152
	ds_read_b128 v[206:209], v162 offset:50176
	ds_read_b128 v[210:213], v162 offset:51200
	ds_read_b128 v[214:217], v162 offset:52224
	ds_read_b128 v[218:221], v162 offset:53248
	ds_read_b128 v[222:225], v162 offset:54272
	ds_read_b128 v[226:229], v162 offset:55296
	ds_read_b128 v[230:233], v162 offset:56320
	s_waitcnt vmcnt(4)
	s_waitcnt lgkmcnt(0)
	s_barrier
	v_mfma_f32_16x16x32_bf16 v[52:55], v[176:179], v[202:205], v[52:55]
	v_mfma_f32_16x16x32_bf16 v[48:51], v[194:197], v[202:205], v[48:51]
	v_mfma_f32_16x16x32_bf16 v[36:39], v[176:179], v[210:213], v[36:39]
	v_mfma_f32_16x16x32_bf16 v[32:35], v[194:197], v[210:213], v[32:35]
	v_mfma_f32_16x16x32_bf16 v[20:23], v[176:179], v[218:221], v[20:23]
	v_mfma_f32_16x16x32_bf16 v[16:19], v[194:197], v[218:221], v[16:19]
	v_mfma_f32_16x16x32_bf16 v[4:7], v[176:179], v[226:229], v[4:7]
	v_mfma_f32_16x16x32_bf16 v[0:3], v[194:197], v[226:229], v[0:3]
	v_mfma_f32_16x16x32_bf16 v[52:55], v[190:193], v[206:209], v[52:55]
	v_mfma_f32_16x16x32_bf16 v[48:51], v[198:201], v[206:209], v[48:51]
	v_mfma_f32_16x16x32_bf16 v[36:39], v[190:193], v[214:217], v[36:39]
	v_mfma_f32_16x16x32_bf16 v[32:35], v[198:201], v[214:217], v[32:35]
	v_mfma_f32_16x16x32_bf16 v[20:23], v[190:193], v[222:225], v[20:23]
	v_mfma_f32_16x16x32_bf16 v[16:19], v[198:201], v[222:225], v[16:19]
	v_mfma_f32_16x16x32_bf16 v[4:7], v[190:193], v[230:233], v[4:7]
	v_mfma_f32_16x16x32_bf16 v[0:3], v[198:201], v[230:233], v[0:3]
	s_barrier
	v_add_u32_e32 v142, 0x10000, v160
	ds_read_b128 v[176:179], v142
	ds_read_b128 v[190:193], v142 offset:1024
	ds_read_b128 v[194:197], v142 offset:2048
	ds_read_b128 v[198:201], v142 offset:3072
	ds_read_b128 v[202:205], v162 offset:0
	ds_read_b128 v[206:209], v162 offset:1024
	ds_read_b128 v[210:213], v162 offset:2048
	ds_read_b128 v[214:217], v162 offset:3072
	ds_read_b128 v[218:221], v162 offset:4096
	ds_read_b128 v[222:225], v162 offset:5120
	ds_read_b128 v[226:229], v162 offset:6144
	ds_read_b128 v[230:233], v162 offset:7168
	s_waitcnt vmcnt(0)
	s_waitcnt lgkmcnt(0)
	s_barrier
	v_mfma_f32_16x16x32_bf16 v[52:55], v[176:179], v[202:205], v[52:55]
	v_mfma_f32_16x16x32_bf16 v[48:51], v[194:197], v[202:205], v[48:51]
	v_mfma_f32_16x16x32_bf16 v[36:39], v[176:179], v[210:213], v[36:39]
	v_mfma_f32_16x16x32_bf16 v[32:35], v[194:197], v[210:213], v[32:35]
	v_mfma_f32_16x16x32_bf16 v[20:23], v[176:179], v[218:221], v[20:23]
	v_mfma_f32_16x16x32_bf16 v[16:19], v[194:197], v[218:221], v[16:19]
	v_mfma_f32_16x16x32_bf16 v[4:7], v[176:179], v[226:229], v[4:7]
	v_mfma_f32_16x16x32_bf16 v[0:3], v[194:197], v[226:229], v[0:3]
	v_mfma_f32_16x16x32_bf16 v[52:55], v[190:193], v[206:209], v[52:55]
	v_mfma_f32_16x16x32_bf16 v[48:51], v[198:201], v[206:209], v[48:51]
	v_mfma_f32_16x16x32_bf16 v[36:39], v[190:193], v[214:217], v[36:39]
	v_mfma_f32_16x16x32_bf16 v[32:35], v[198:201], v[214:217], v[32:35]
	v_mfma_f32_16x16x32_bf16 v[20:23], v[190:193], v[222:225], v[20:23]
	v_mfma_f32_16x16x32_bf16 v[16:19], v[198:201], v[222:225], v[16:19]
	v_mfma_f32_16x16x32_bf16 v[4:7], v[190:193], v[230:233], v[4:7]
	v_mfma_f32_16x16x32_bf16 v[0:3], v[198:201], v[230:233], v[0:3]
	s_barrier
	v_add_u32_e32 v142, 0x18000, v160
	ds_read_b128 v[176:179], v142
	ds_read_b128 v[190:193], v142 offset:1024
	ds_read_b128 v[194:197], v142 offset:2048
	ds_read_b128 v[198:201], v142 offset:3072
	ds_read_b128 v[202:205], v162 offset:32768
	ds_read_b128 v[206:209], v162 offset:33792
	ds_read_b128 v[210:213], v162 offset:34816
	ds_read_b128 v[214:217], v162 offset:35840
	ds_read_b128 v[218:221], v162 offset:36864
	ds_read_b128 v[222:225], v162 offset:37888
	ds_read_b128 v[226:229], v162 offset:38912
	ds_read_b128 v[230:233], v162 offset:39936
	s_waitcnt lgkmcnt(0)
	s_barrier
	v_mfma_f32_16x16x32_bf16 v[52:55], v[176:179], v[202:205], v[52:55]
	v_mfma_f32_16x16x32_bf16 v[48:51], v[194:197], v[202:205], v[48:51]
	v_mfma_f32_16x16x32_bf16 v[36:39], v[176:179], v[210:213], v[36:39]
	v_mfma_f32_16x16x32_bf16 v[32:35], v[194:197], v[210:213], v[32:35]
	v_mfma_f32_16x16x32_bf16 v[20:23], v[176:179], v[218:221], v[20:23]
	v_mfma_f32_16x16x32_bf16 v[16:19], v[194:197], v[218:221], v[16:19]
	v_mfma_f32_16x16x32_bf16 v[4:7], v[176:179], v[226:229], v[4:7]
	v_mfma_f32_16x16x32_bf16 v[0:3], v[194:197], v[226:229], v[0:3]
	v_mfma_f32_16x16x32_bf16 v[52:55], v[190:193], v[206:209], v[52:55]
	v_mfma_f32_16x16x32_bf16 v[48:51], v[198:201], v[206:209], v[48:51]
	v_mfma_f32_16x16x32_bf16 v[36:39], v[190:193], v[214:217], v[36:39]
	v_mfma_f32_16x16x32_bf16 v[32:35], v[198:201], v[214:217], v[32:35]
	v_mfma_f32_16x16x32_bf16 v[20:23], v[190:193], v[222:225], v[20:23]
	v_mfma_f32_16x16x32_bf16 v[16:19], v[198:201], v[222:225], v[16:19]
	v_mfma_f32_16x16x32_bf16 v[4:7], v[190:193], v[230:233], v[4:7]
	v_mfma_f32_16x16x32_bf16 v[0:3], v[198:201], v[230:233], v[0:3]
	s_barrier
	s_branch .Lq_abi_exit

.Lq_smp_0_k:
	v_add_u32_e32 v161, 0x10000, v38
	ds_read_b128 v[40:43], v161
	ds_read_b128 v[48:51], v161 offset:1024
	ds_read_b128 v[162:165], v161 offset:2048
	ds_read_b128 v[166:169], v161 offset:3072
	ds_read_b128 v[198:201], v39 offset:0
	ds_read_b128 v[202:205], v39 offset:1024
	ds_read_b128 v[206:209], v39 offset:2048
	ds_read_b128 v[210:213], v39 offset:3072
	ds_read_b128 v[214:217], v39 offset:4096
	ds_read_b128 v[218:221], v39 offset:5120
	ds_read_b128 v[222:225], v39 offset:6144
	ds_read_b128 v[226:229], v39 offset:7168
	v_lshl_add_u64 v[178:179], s[14:15], 0, v[144:145]
	s_add_i32 m0, s1, 0xc000
	v_lshl_add_u64 v[230:231], s[14:15], 0, v[28:29]
	global_load_lds_dwordx4 v[178:179], off
	s_add_i32 m0, s1, 0xe000
	v_lshl_add_u64 v[232:233], s[2:3], 0, v[144:145]
	global_load_lds_dwordx4 v[230:231], off
	s_add_i32 m0, s1, 0x1c000
	v_lshl_add_u64 v[234:235], s[2:3], 0, v[28:29]
	global_load_lds_dwordx4 v[232:233], off
	s_add_i32 m0, s1, 0x1e000
	s_add_u32 s14, s14, 0x80
	s_addc_u32 s15, s15, 0
	global_load_lds_dwordx4 v[234:235], off
	s_add_u32 s2, s2, 0x80
	s_addc_u32 s3, s3, 0
	s_waitcnt vmcnt(8)
	s_waitcnt lgkmcnt(0)
	s_barrier
	v_mfma_f32_16x16x32_bf16 v[140:143], v[40:43], v[198:201], v[140:143]
	v_mfma_f32_16x16x32_bf16 v[136:139], v[162:165], v[198:201], v[136:139]
	v_mfma_f32_16x16x32_bf16 v[124:127], v[40:43], v[206:209], v[124:127]
	v_mfma_f32_16x16x32_bf16 v[120:123], v[162:165], v[206:209], v[120:123]
	v_mfma_f32_16x16x32_bf16 v[108:111], v[40:43], v[214:217], v[108:111]
	v_mfma_f32_16x16x32_bf16 v[104:107], v[162:165], v[214:217], v[104:107]
	v_mfma_f32_16x16x32_bf16 v[92:95], v[40:43], v[222:225], v[92:95]
	v_mfma_f32_16x16x32_bf16 v[88:91], v[162:165], v[222:225], v[88:91]
	v_mfma_f32_16x16x32_bf16 v[140:143], v[48:51], v[202:205], v[140:143]
	v_mfma_f32_16x16x32_bf16 v[136:139], v[166:169], v[202:205], v[136:139]
	v_mfma_f32_16x16x32_bf16 v[124:127], v[48:51], v[210:213], v[124:127]
	v_mfma_f32_16x16x32_bf16 v[120:123], v[166:169], v[210:213], v[120:123]
	v_mfma_f32_16x16x32_bf16 v[108:111], v[48:51], v[218:221], v[108:111]
	v_mfma_f32_16x16x32_bf16 v[104:107], v[166:169], v[218:221], v[104:107]
	v_mfma_f32_16x16x32_bf16 v[92:95], v[48:51], v[226:229], v[92:95]
	v_mfma_f32_16x16x32_bf16 v[88:91], v[166:169], v[226:229], v[88:91]
	s_barrier
	v_add_u32_e32 v161, 0x18000, v38
	ds_read_b128 v[40:43], v161
	ds_read_b128 v[48:51], v161 offset:1024
	ds_read_b128 v[162:165], v161 offset:2048
	ds_read_b128 v[166:169], v161 offset:3072
	ds_read_b128 v[198:201], v39 offset:32768
	ds_read_b128 v[202:205], v39 offset:33792
	ds_read_b128 v[206:209], v39 offset:34816
	ds_read_b128 v[210:213], v39 offset:35840
	ds_read_b128 v[214:217], v39 offset:36864
	ds_read_b128 v[218:221], v39 offset:37888
	ds_read_b128 v[222:225], v39 offset:38912
	ds_read_b128 v[226:229], v39 offset:39936
	v_lshl_add_u64 v[178:179], s[14:15], 0, v[144:145]
	s_add_i32 m0, s1, 0x0
	v_lshl_add_u64 v[230:231], s[14:15], 0, v[28:29]
	global_load_lds_dwordx4 v[178:179], off
	s_add_i32 m0, s1, 0x2000
	v_lshl_add_u64 v[232:233], s[2:3], 0, v[144:145]
	global_load_lds_dwordx4 v[230:231], off
	s_add_i32 m0, s1, 0x10000
	v_lshl_add_u64 v[234:235], s[2:3], 0, v[28:29]
	global_load_lds_dwordx4 v[232:233], off
	s_add_i32 m0, s1, 0x12000
	s_add_u32 s14, s14, 0x80
	s_addc_u32 s15, s15, 0
	global_load_lds_dwordx4 v[234:235], off
	s_add_u32 s2, s2, 0x80
	s_addc_u32 s3, s3, 0
	s_waitcnt vmcnt(8)
	s_waitcnt lgkmcnt(0)
	s_barrier
	v_mfma_f32_16x16x32_bf16 v[140:143], v[40:43], v[198:201], v[140:143]
	v_mfma_f32_16x16x32_bf16 v[136:139], v[162:165], v[198:201], v[136:139]
	v_mfma_f32_16x16x32_bf16 v[124:127], v[40:43], v[206:209], v[124:127]
	v_mfma_f32_16x16x32_bf16 v[120:123], v[162:165], v[206:209], v[120:123]
	v_mfma_f32_16x16x32_bf16 v[108:111], v[40:43], v[214:217], v[108:111]
	v_mfma_f32_16x16x32_bf16 v[104:107], v[162:165], v[214:217], v[104:107]
	v_mfma_f32_16x16x32_bf16 v[92:95], v[40:43], v[222:225], v[92:95]
	v_mfma_f32_16x16x32_bf16 v[88:91], v[162:165], v[222:225], v[88:91]
	v_mfma_f32_16x16x32_bf16 v[140:143], v[48:51], v[202:205], v[140:143]
	v_mfma_f32_16x16x32_bf16 v[136:139], v[166:169], v[202:205], v[136:139]
	v_mfma_f32_16x16x32_bf16 v[124:127], v[48:51], v[210:213], v[124:127]
	v_mfma_f32_16x16x32_bf16 v[120:123], v[166:169], v[210:213], v[120:123]
	v_mfma_f32_16x16x32_bf16 v[108:111], v[48:51], v[218:221], v[108:111]
	v_mfma_f32_16x16x32_bf16 v[104:107], v[166:169], v[218:221], v[104:107]
	v_mfma_f32_16x16x32_bf16 v[92:95], v[48:51], v[226:229], v[92:95]
	v_mfma_f32_16x16x32_bf16 v[88:91], v[166:169], v[226:229], v[88:91]
	s_barrier
	v_add_u32_e32 v161, 0x14000, v38
	ds_read_b128 v[40:43], v161
	ds_read_b128 v[48:51], v161 offset:1024
	ds_read_b128 v[162:165], v161 offset:2048
	ds_read_b128 v[166:169], v161 offset:3072
	ds_read_b128 v[198:201], v39 offset:16384
	ds_read_b128 v[202:205], v39 offset:17408
	ds_read_b128 v[206:209], v39 offset:18432
	ds_read_b128 v[210:213], v39 offset:19456
	ds_read_b128 v[214:217], v39 offset:20480
	ds_read_b128 v[218:221], v39 offset:21504
	ds_read_b128 v[222:225], v39 offset:22528
	ds_read_b128 v[226:229], v39 offset:23552
	v_lshl_add_u64 v[178:179], s[14:15], 0, v[144:145]
	s_add_i32 m0, s1, 0x8000
	v_lshl_add_u64 v[230:231], s[14:15], 0, v[28:29]
	global_load_lds_dwordx4 v[178:179], off
	s_add_i32 m0, s1, 0xa000
	v_lshl_add_u64 v[232:233], s[2:3], 0, v[144:145]
	global_load_lds_dwordx4 v[230:231], off
	s_add_i32 m0, s1, 0x18000
	v_lshl_add_u64 v[234:235], s[2:3], 0, v[28:29]
	global_load_lds_dwordx4 v[232:233], off
	s_add_i32 m0, s1, 0x1a000
	s_add_u32 s14, s14, 0x80
	s_addc_u32 s15, s15, 0
	global_load_lds_dwordx4 v[234:235], off
	s_add_u32 s2, s2, 0x80
	s_addc_u32 s3, s3, 0
	s_waitcnt vmcnt(8)
	s_waitcnt lgkmcnt(0)
	s_barrier
	v_mfma_f32_16x16x32_bf16 v[140:143], v[40:43], v[198:201], v[140:143]
	v_mfma_f32_16x16x32_bf16 v[136:139], v[162:165], v[198:201], v[136:139]
	v_mfma_f32_16x16x32_bf16 v[124:127], v[40:43], v[206:209], v[124:127]
	v_mfma_f32_16x16x32_bf16 v[120:123], v[162:165], v[206:209], v[120:123]
	v_mfma_f32_16x16x32_bf16 v[108:111], v[40:43], v[214:217], v[108:111]
	v_mfma_f32_16x16x32_bf16 v[104:107], v[162:165], v[214:217], v[104:107]
	v_mfma_f32_16x16x32_bf16 v[92:95], v[40:43], v[222:225], v[92:95]
	v_mfma_f32_16x16x32_bf16 v[88:91], v[162:165], v[222:225], v[88:91]
	v_mfma_f32_16x16x32_bf16 v[140:143], v[48:51], v[202:205], v[140:143]
	v_mfma_f32_16x16x32_bf16 v[136:139], v[166:169], v[202:205], v[136:139]
	v_mfma_f32_16x16x32_bf16 v[124:127], v[48:51], v[210:213], v[124:127]
	v_mfma_f32_16x16x32_bf16 v[120:123], v[166:169], v[210:213], v[120:123]
	v_mfma_f32_16x16x32_bf16 v[108:111], v[48:51], v[218:221], v[108:111]
	v_mfma_f32_16x16x32_bf16 v[104:107], v[166:169], v[218:221], v[104:107]
	v_mfma_f32_16x16x32_bf16 v[92:95], v[48:51], v[226:229], v[92:95]
	v_mfma_f32_16x16x32_bf16 v[88:91], v[166:169], v[226:229], v[88:91]
	s_barrier
	v_add_u32_e32 v161, 0x1c000, v38
	ds_read_b128 v[40:43], v161
	ds_read_b128 v[48:51], v161 offset:1024
	ds_read_b128 v[162:165], v161 offset:2048
	ds_read_b128 v[166:169], v161 offset:3072
	ds_read_b128 v[198:201], v39 offset:49152
	ds_read_b128 v[202:205], v39 offset:50176
	ds_read_b128 v[206:209], v39 offset:51200
	ds_read_b128 v[210:213], v39 offset:52224
	ds_read_b128 v[214:217], v39 offset:53248
	ds_read_b128 v[218:221], v39 offset:54272
	ds_read_b128 v[222:225], v39 offset:55296
	ds_read_b128 v[226:229], v39 offset:56320
	v_lshl_add_u64 v[178:179], s[14:15], 0, v[144:145]
	s_add_i32 m0, s1, 0x4000
	v_lshl_add_u64 v[230:231], s[14:15], 0, v[28:29]
	global_load_lds_dwordx4 v[178:179], off
	s_add_i32 m0, s1, 0x6000
	v_lshl_add_u64 v[232:233], s[2:3], 0, v[144:145]
	global_load_lds_dwordx4 v[230:231], off
	s_add_i32 m0, s1, 0x14000
	v_lshl_add_u64 v[234:235], s[2:3], 0, v[28:29]
	global_load_lds_dwordx4 v[232:233], off
	s_add_i32 m0, s1, 0x16000
	s_add_u32 s14, s14, 0x80
	s_addc_u32 s15, s15, 0
	global_load_lds_dwordx4 v[234:235], off
	s_add_u32 s2, s2, 0x80
	s_addc_u32 s3, s3, 0
	s_waitcnt vmcnt(8)
	s_waitcnt lgkmcnt(0)
	s_barrier
	v_mfma_f32_16x16x32_bf16 v[140:143], v[40:43], v[198:201], v[140:143]
	v_mfma_f32_16x16x32_bf16 v[136:139], v[162:165], v[198:201], v[136:139]
	v_mfma_f32_16x16x32_bf16 v[124:127], v[40:43], v[206:209], v[124:127]
	v_mfma_f32_16x16x32_bf16 v[120:123], v[162:165], v[206:209], v[120:123]
	v_mfma_f32_16x16x32_bf16 v[108:111], v[40:43], v[214:217], v[108:111]
	v_mfma_f32_16x16x32_bf16 v[104:107], v[162:165], v[214:217], v[104:107]
	v_mfma_f32_16x16x32_bf16 v[92:95], v[40:43], v[222:225], v[92:95]
	v_mfma_f32_16x16x32_bf16 v[88:91], v[162:165], v[222:225], v[88:91]
	v_mfma_f32_16x16x32_bf16 v[140:143], v[48:51], v[202:205], v[140:143]
	v_mfma_f32_16x16x32_bf16 v[136:139], v[166:169], v[202:205], v[136:139]
	v_mfma_f32_16x16x32_bf16 v[124:127], v[48:51], v[210:213], v[124:127]
	v_mfma_f32_16x16x32_bf16 v[120:123], v[166:169], v[210:213], v[120:123]
	v_mfma_f32_16x16x32_bf16 v[108:111], v[48:51], v[218:221], v[108:111]
	v_mfma_f32_16x16x32_bf16 v[104:107], v[166:169], v[218:221], v[104:107]
	v_mfma_f32_16x16x32_bf16 v[92:95], v[48:51], v[226:229], v[92:95]
	v_mfma_f32_16x16x32_bf16 v[88:91], v[166:169], v[226:229], v[88:91]
	s_barrier
	s_add_i32 s55, s55, 1
	s_cmp_lt_u32 s55, 7
	s_cbranch_scc1 .Lq_smp_0_k
	v_add_u32_e32 v161, 0x10000, v38
	ds_read_b128 v[40:43], v161
	ds_read_b128 v[48:51], v161 offset:1024
	ds_read_b128 v[162:165], v161 offset:2048
	ds_read_b128 v[166:169], v161 offset:3072
	ds_read_b128 v[198:201], v39 offset:0
	ds_read_b128 v[202:205], v39 offset:1024
	ds_read_b128 v[206:209], v39 offset:2048
	ds_read_b128 v[210:213], v39 offset:3072
	ds_read_b128 v[214:217], v39 offset:4096
	ds_read_b128 v[218:221], v39 offset:5120
	ds_read_b128 v[222:225], v39 offset:6144
	ds_read_b128 v[226:229], v39 offset:7168
	v_lshl_add_u64 v[178:179], s[14:15], 0, v[144:145]
	s_add_i32 m0, s1, 0xc000
	v_lshl_add_u64 v[230:231], s[14:15], 0, v[28:29]
	global_load_lds_dwordx4 v[178:179], off
	s_add_i32 m0, s1, 0xe000
	v_lshl_add_u64 v[232:233], s[2:3], 0, v[144:145]
	global_load_lds_dwordx4 v[230:231], off
	s_add_i32 m0, s1, 0x1c000
	v_lshl_add_u64 v[234:235], s[2:3], 0, v[28:29]
	global_load_lds_dwordx4 v[232:233], off
	s_add_i32 m0, s1, 0x1e000
	s_add_u32 s14, s14, 0x80
	s_addc_u32 s15, s15, 0
	global_load_lds_dwordx4 v[234:235], off
	s_add_u32 s2, s2, 0x80
	s_addc_u32 s3, s3, 0
	s_waitcnt vmcnt(8)
	s_waitcnt lgkmcnt(0)
	s_barrier
	v_mfma_f32_16x16x32_bf16 v[140:143], v[40:43], v[198:201], v[140:143]
	v_mfma_f32_16x16x32_bf16 v[136:139], v[162:165], v[198:201], v[136:139]
	v_mfma_f32_16x16x32_bf16 v[124:127], v[40:43], v[206:209], v[124:127]
	v_mfma_f32_16x16x32_bf16 v[120:123], v[162:165], v[206:209], v[120:123]
	v_mfma_f32_16x16x32_bf16 v[108:111], v[40:43], v[214:217], v[108:111]
	v_mfma_f32_16x16x32_bf16 v[104:107], v[162:165], v[214:217], v[104:107]
	v_mfma_f32_16x16x32_bf16 v[92:95], v[40:43], v[222:225], v[92:95]
	v_mfma_f32_16x16x32_bf16 v[88:91], v[162:165], v[222:225], v[88:91]
	v_mfma_f32_16x16x32_bf16 v[140:143], v[48:51], v[202:205], v[140:143]
	v_mfma_f32_16x16x32_bf16 v[136:139], v[166:169], v[202:205], v[136:139]
	v_mfma_f32_16x16x32_bf16 v[124:127], v[48:51], v[210:213], v[124:127]
	v_mfma_f32_16x16x32_bf16 v[120:123], v[166:169], v[210:213], v[120:123]
	v_mfma_f32_16x16x32_bf16 v[108:111], v[48:51], v[218:221], v[108:111]
	v_mfma_f32_16x16x32_bf16 v[104:107], v[166:169], v[218:221], v[104:107]
	v_mfma_f32_16x16x32_bf16 v[92:95], v[48:51], v[226:229], v[92:95]
	v_mfma_f32_16x16x32_bf16 v[88:91], v[166:169], v[226:229], v[88:91]
	s_barrier
	v_add_u32_e32 v161, 0x18000, v38
	ds_read_b128 v[40:43], v161
	ds_read_b128 v[48:51], v161 offset:1024
	ds_read_b128 v[162:165], v161 offset:2048
	ds_read_b128 v[166:169], v161 offset:3072
	ds_read_b128 v[198:201], v39 offset:32768
	ds_read_b128 v[202:205], v39 offset:33792
	ds_read_b128 v[206:209], v39 offset:34816
	ds_read_b128 v[210:213], v39 offset:35840
	ds_read_b128 v[214:217], v39 offset:36864
	ds_read_b128 v[218:221], v39 offset:37888
	ds_read_b128 v[222:225], v39 offset:38912
	ds_read_b128 v[226:229], v39 offset:39936
	s_waitcnt vmcnt(4)
	s_waitcnt lgkmcnt(0)
	s_barrier
	v_mfma_f32_16x16x32_bf16 v[140:143], v[40:43], v[198:201], v[140:143]
	v_mfma_f32_16x16x32_bf16 v[136:139], v[162:165], v[198:201], v[136:139]
	v_mfma_f32_16x16x32_bf16 v[124:127], v[40:43], v[206:209], v[124:127]
	v_mfma_f32_16x16x32_bf16 v[120:123], v[162:165], v[206:209], v[120:123]
	v_mfma_f32_16x16x32_bf16 v[108:111], v[40:43], v[214:217], v[108:111]
	v_mfma_f32_16x16x32_bf16 v[104:107], v[162:165], v[214:217], v[104:107]
	v_mfma_f32_16x16x32_bf16 v[92:95], v[40:43], v[222:225], v[92:95]
	v_mfma_f32_16x16x32_bf16 v[88:91], v[162:165], v[222:225], v[88:91]
	v_mfma_f32_16x16x32_bf16 v[140:143], v[48:51], v[202:205], v[140:143]
	v_mfma_f32_16x16x32_bf16 v[136:139], v[166:169], v[202:205], v[136:139]
	v_mfma_f32_16x16x32_bf16 v[124:127], v[48:51], v[210:213], v[124:127]
	v_mfma_f32_16x16x32_bf16 v[120:123], v[166:169], v[210:213], v[120:123]
	v_mfma_f32_16x16x32_bf16 v[108:111], v[48:51], v[218:221], v[108:111]
	v_mfma_f32_16x16x32_bf16 v[104:107], v[166:169], v[218:221], v[104:107]
	v_mfma_f32_16x16x32_bf16 v[92:95], v[48:51], v[226:229], v[92:95]
	v_mfma_f32_16x16x32_bf16 v[88:91], v[166:169], v[226:229], v[88:91]
	s_barrier
	v_add_u32_e32 v161, 0x14000, v38
	ds_read_b128 v[40:43], v161
	ds_read_b128 v[48:51], v161 offset:1024
	ds_read_b128 v[162:165], v161 offset:2048
	ds_read_b128 v[166:169], v161 offset:3072
	ds_read_b128 v[198:201], v39 offset:16384
	ds_read_b128 v[202:205], v39 offset:17408
	ds_read_b128 v[206:209], v39 offset:18432
	ds_read_b128 v[210:213], v39 offset:19456
	ds_read_b128 v[214:217], v39 offset:20480
	ds_read_b128 v[218:221], v39 offset:21504
	ds_read_b128 v[222:225], v39 offset:22528
	ds_read_b128 v[226:229], v39 offset:23552
	s_waitcnt vmcnt(0)
	s_waitcnt lgkmcnt(0)
	s_barrier
	v_mfma_f32_16x16x32_bf16 v[140:143], v[40:43], v[198:201], v[140:143]
	v_mfma_f32_16x16x32_bf16 v[136:139], v[162:165], v[198:201], v[136:139]
	v_mfma_f32_16x16x32_bf16 v[124:127], v[40:43], v[206:209], v[124:127]
	v_mfma_f32_16x16x32_bf16 v[120:123], v[162:165], v[206:209], v[120:123]
	v_mfma_f32_16x16x32_bf16 v[108:111], v[40:43], v[214:217], v[108:111]
	v_mfma_f32_16x16x32_bf16 v[104:107], v[162:165], v[214:217], v[104:107]
	v_mfma_f32_16x16x32_bf16 v[92:95], v[40:43], v[222:225], v[92:95]
	v_mfma_f32_16x16x32_bf16 v[88:91], v[162:165], v[222:225], v[88:91]
	v_mfma_f32_16x16x32_bf16 v[140:143], v[48:51], v[202:205], v[140:143]
	v_mfma_f32_16x16x32_bf16 v[136:139], v[166:169], v[202:205], v[136:139]
	v_mfma_f32_16x16x32_bf16 v[124:127], v[48:51], v[210:213], v[124:127]
	v_mfma_f32_16x16x32_bf16 v[120:123], v[166:169], v[210:213], v[120:123]
	v_mfma_f32_16x16x32_bf16 v[108:111], v[48:51], v[218:221], v[108:111]
	v_mfma_f32_16x16x32_bf16 v[104:107], v[166:169], v[218:221], v[104:107]
	v_mfma_f32_16x16x32_bf16 v[92:95], v[48:51], v[226:229], v[92:95]
	v_mfma_f32_16x16x32_bf16 v[88:91], v[166:169], v[226:229], v[88:91]
	s_barrier
	v_add_u32_e32 v161, 0x1c000, v38
	ds_read_b128 v[40:43], v161
	ds_read_b128 v[48:51], v161 offset:1024
	ds_read_b128 v[162:165], v161 offset:2048
	ds_read_b128 v[166:169], v161 offset:3072
	ds_read_b128 v[198:201], v39 offset:49152
	ds_read_b128 v[202:205], v39 offset:50176
	ds_read_b128 v[206:209], v39 offset:51200
	ds_read_b128 v[210:213], v39 offset:52224
	ds_read_b128 v[214:217], v39 offset:53248
	ds_read_b128 v[218:221], v39 offset:54272
	ds_read_b128 v[222:225], v39 offset:55296
	ds_read_b128 v[226:229], v39 offset:56320
	s_waitcnt lgkmcnt(0)
	s_barrier
	v_mfma_f32_16x16x32_bf16 v[140:143], v[40:43], v[198:201], v[140:143]
	v_mfma_f32_16x16x32_bf16 v[136:139], v[162:165], v[198:201], v[136:139]
	v_mfma_f32_16x16x32_bf16 v[124:127], v[40:43], v[206:209], v[124:127]
	v_mfma_f32_16x16x32_bf16 v[120:123], v[162:165], v[206:209], v[120:123]
	v_mfma_f32_16x16x32_bf16 v[108:111], v[40:43], v[214:217], v[108:111]
	v_mfma_f32_16x16x32_bf16 v[104:107], v[162:165], v[214:217], v[104:107]
	v_mfma_f32_16x16x32_bf16 v[92:95], v[40:43], v[222:225], v[92:95]
	v_mfma_f32_16x16x32_bf16 v[88:91], v[162:165], v[222:225], v[88:91]
	v_mfma_f32_16x16x32_bf16 v[140:143], v[48:51], v[202:205], v[140:143]
	v_mfma_f32_16x16x32_bf16 v[136:139], v[166:169], v[202:205], v[136:139]
	v_mfma_f32_16x16x32_bf16 v[124:127], v[48:51], v[210:213], v[124:127]
	v_mfma_f32_16x16x32_bf16 v[120:123], v[166:169], v[210:213], v[120:123]
	v_mfma_f32_16x16x32_bf16 v[108:111], v[48:51], v[218:221], v[108:111]
	v_mfma_f32_16x16x32_bf16 v[104:107], v[166:169], v[218:221], v[104:107]
	v_mfma_f32_16x16x32_bf16 v[92:95], v[48:51], v[226:229], v[92:95]
	v_mfma_f32_16x16x32_bf16 v[88:91], v[166:169], v[226:229], v[88:91]
	s_barrier
	s_branch .Lq_smp_exit

.Lq_smp_1_k:
	v_add_u32_e32 v161, 0x14000, v38
	ds_read_b128 v[170:173], v161
	ds_read_b128 v[174:177], v161 offset:1024
	ds_read_b128 v[190:193], v161 offset:2048
	ds_read_b128 v[194:197], v161 offset:3072
	ds_read_b128 v[198:201], v39 offset:0
	ds_read_b128 v[202:205], v39 offset:1024
	ds_read_b128 v[206:209], v39 offset:2048
	ds_read_b128 v[210:213], v39 offset:3072
	ds_read_b128 v[214:217], v39 offset:4096
	ds_read_b128 v[218:221], v39 offset:5120
	ds_read_b128 v[222:225], v39 offset:6144
	ds_read_b128 v[226:229], v39 offset:7168
	v_lshl_add_u64 v[178:179], s[14:15], 0, v[144:145]
	s_add_i32 m0, s1, 0xc000
	v_lshl_add_u64 v[230:231], s[14:15], 0, v[28:29]
	global_load_lds_dwordx4 v[178:179], off
	s_add_i32 m0, s1, 0xe000
	v_lshl_add_u64 v[232:233], s[2:3], 0, v[144:145]
	global_load_lds_dwordx4 v[230:231], off
	s_add_i32 m0, s1, 0x18000
	v_lshl_add_u64 v[234:235], s[2:3], 0, v[28:29]
	global_load_lds_dwordx4 v[232:233], off
	s_add_i32 m0, s1, 0x1a000
	s_add_u32 s14, s14, 0x80
	s_addc_u32 s15, s15, 0
	global_load_lds_dwordx4 v[234:235], off
	s_add_u32 s2, s2, 0x80
	s_addc_u32 s3, s3, 0
	s_waitcnt vmcnt(8)
	s_waitcnt lgkmcnt(0)
	s_barrier
	v_mfma_f32_16x16x32_bf16 v[132:135], v[170:173], v[198:201], v[132:135]
	v_mfma_f32_16x16x32_bf16 v[128:131], v[190:193], v[198:201], v[128:131]
	v_mfma_f32_16x16x32_bf16 v[116:119], v[170:173], v[206:209], v[116:119]
	v_mfma_f32_16x16x32_bf16 v[112:115], v[190:193], v[206:209], v[112:115]
	v_mfma_f32_16x16x32_bf16 v[100:103], v[170:173], v[214:217], v[100:103]
	v_mfma_f32_16x16x32_bf16 v[96:99], v[190:193], v[214:217], v[96:99]
	v_mfma_f32_16x16x32_bf16 v[84:87], v[170:173], v[222:225], v[84:87]
	v_mfma_f32_16x16x32_bf16 v[80:83], v[190:193], v[222:225], v[80:83]
	v_mfma_f32_16x16x32_bf16 v[132:135], v[174:177], v[202:205], v[132:135]
	v_mfma_f32_16x16x32_bf16 v[128:131], v[194:197], v[202:205], v[128:131]
	v_mfma_f32_16x16x32_bf16 v[116:119], v[174:177], v[210:213], v[116:119]
	v_mfma_f32_16x16x32_bf16 v[112:115], v[194:197], v[210:213], v[112:115]
	v_mfma_f32_16x16x32_bf16 v[100:103], v[174:177], v[218:221], v[100:103]
	v_mfma_f32_16x16x32_bf16 v[96:99], v[194:197], v[218:221], v[96:99]
	v_mfma_f32_16x16x32_bf16 v[84:87], v[174:177], v[226:229], v[84:87]
	v_mfma_f32_16x16x32_bf16 v[80:83], v[194:197], v[226:229], v[80:83]
	s_barrier
	v_add_u32_e32 v161, 0x1c000, v38
	ds_read_b128 v[170:173], v161
	ds_read_b128 v[174:177], v161 offset:1024
	ds_read_b128 v[190:193], v161 offset:2048
	ds_read_b128 v[194:197], v161 offset:3072
	ds_read_b128 v[198:201], v39 offset:32768
	ds_read_b128 v[202:205], v39 offset:33792
	ds_read_b128 v[206:209], v39 offset:34816
	ds_read_b128 v[210:213], v39 offset:35840
	ds_read_b128 v[214:217], v39 offset:36864
	ds_read_b128 v[218:221], v39 offset:37888
	ds_read_b128 v[222:225], v39 offset:38912
	ds_read_b128 v[226:229], v39 offset:39936
	v_lshl_add_u64 v[178:179], s[14:15], 0, v[144:145]
	s_add_i32 m0, s1, 0x0
	v_lshl_add_u64 v[230:231], s[14:15], 0, v[28:29]
	global_load_lds_dwordx4 v[178:179], off
	s_add_i32 m0, s1, 0x2000
	v_lshl_add_u64 v[232:233], s[2:3], 0, v[144:145]
	global_load_lds_dwordx4 v[230:231], off
	s_add_i32 m0, s1, 0x14000
	v_lshl_add_u64 v[234:235], s[2:3], 0, v[28:29]
	global_load_lds_dwordx4 v[232:233], off
	s_add_i32 m0, s1, 0x16000
	s_add_u32 s14, s14, 0x80
	s_addc_u32 s15, s15, 0
	global_load_lds_dwordx4 v[234:235], off
	s_add_u32 s2, s2, 0x80
	s_addc_u32 s3, s3, 0
	s_waitcnt vmcnt(8)
	s_waitcnt lgkmcnt(0)
	s_barrier
	v_mfma_f32_16x16x32_bf16 v[132:135], v[170:173], v[198:201], v[132:135]
	v_mfma_f32_16x16x32_bf16 v[128:131], v[190:193], v[198:201], v[128:131]
	v_mfma_f32_16x16x32_bf16 v[116:119], v[170:173], v[206:209], v[116:119]
	v_mfma_f32_16x16x32_bf16 v[112:115], v[190:193], v[206:209], v[112:115]
	v_mfma_f32_16x16x32_bf16 v[100:103], v[170:173], v[214:217], v[100:103]
	v_mfma_f32_16x16x32_bf16 v[96:99], v[190:193], v[214:217], v[96:99]
	v_mfma_f32_16x16x32_bf16 v[84:87], v[170:173], v[222:225], v[84:87]
	v_mfma_f32_16x16x32_bf16 v[80:83], v[190:193], v[222:225], v[80:83]
	v_mfma_f32_16x16x32_bf16 v[132:135], v[174:177], v[202:205], v[132:135]
	v_mfma_f32_16x16x32_bf16 v[128:131], v[194:197], v[202:205], v[128:131]
	v_mfma_f32_16x16x32_bf16 v[116:119], v[174:177], v[210:213], v[116:119]
	v_mfma_f32_16x16x32_bf16 v[112:115], v[194:197], v[210:213], v[112:115]
	v_mfma_f32_16x16x32_bf16 v[100:103], v[174:177], v[218:221], v[100:103]
	v_mfma_f32_16x16x32_bf16 v[96:99], v[194:197], v[218:221], v[96:99]
	v_mfma_f32_16x16x32_bf16 v[84:87], v[174:177], v[226:229], v[84:87]
	v_mfma_f32_16x16x32_bf16 v[80:83], v[194:197], v[226:229], v[80:83]
	s_barrier
	v_add_u32_e32 v161, 0x10000, v38
	ds_read_b128 v[170:173], v161
	ds_read_b128 v[174:177], v161 offset:1024
	ds_read_b128 v[190:193], v161 offset:2048
	ds_read_b128 v[194:197], v161 offset:3072
	ds_read_b128 v[198:201], v39 offset:16384
	ds_read_b128 v[202:205], v39 offset:17408
	ds_read_b128 v[206:209], v39 offset:18432
	ds_read_b128 v[210:213], v39 offset:19456
	ds_read_b128 v[214:217], v39 offset:20480
	ds_read_b128 v[218:221], v39 offset:21504
	ds_read_b128 v[222:225], v39 offset:22528
	ds_read_b128 v[226:229], v39 offset:23552
	v_lshl_add_u64 v[178:179], s[14:15], 0, v[144:145]
	s_add_i32 m0, s1, 0x8000
	v_lshl_add_u64 v[230:231], s[14:15], 0, v[28:29]
	global_load_lds_dwordx4 v[178:179], off
	s_add_i32 m0, s1, 0xa000
	v_lshl_add_u64 v[232:233], s[2:3], 0, v[144:145]
	global_load_lds_dwordx4 v[230:231], off
	s_add_i32 m0, s1, 0x1c000
	v_lshl_add_u64 v[234:235], s[2:3], 0, v[28:29]
	global_load_lds_dwordx4 v[232:233], off
	s_add_i32 m0, s1, 0x1e000
	s_add_u32 s14, s14, 0x80
	s_addc_u32 s15, s15, 0
	global_load_lds_dwordx4 v[234:235], off
	s_add_u32 s2, s2, 0x80
	s_addc_u32 s3, s3, 0
	s_waitcnt vmcnt(8)
	s_waitcnt lgkmcnt(0)
	s_barrier
	v_mfma_f32_16x16x32_bf16 v[132:135], v[170:173], v[198:201], v[132:135]
	v_mfma_f32_16x16x32_bf16 v[128:131], v[190:193], v[198:201], v[128:131]
	v_mfma_f32_16x16x32_bf16 v[116:119], v[170:173], v[206:209], v[116:119]
	v_mfma_f32_16x16x32_bf16 v[112:115], v[190:193], v[206:209], v[112:115]
	v_mfma_f32_16x16x32_bf16 v[100:103], v[170:173], v[214:217], v[100:103]
	v_mfma_f32_16x16x32_bf16 v[96:99], v[190:193], v[214:217], v[96:99]
	v_mfma_f32_16x16x32_bf16 v[84:87], v[170:173], v[222:225], v[84:87]
	v_mfma_f32_16x16x32_bf16 v[80:83], v[190:193], v[222:225], v[80:83]
	v_mfma_f32_16x16x32_bf16 v[132:135], v[174:177], v[202:205], v[132:135]
	v_mfma_f32_16x16x32_bf16 v[128:131], v[194:197], v[202:205], v[128:131]
	v_mfma_f32_16x16x32_bf16 v[116:119], v[174:177], v[210:213], v[116:119]
	v_mfma_f32_16x16x32_bf16 v[112:115], v[194:197], v[210:213], v[112:115]
	v_mfma_f32_16x16x32_bf16 v[100:103], v[174:177], v[218:221], v[100:103]
	v_mfma_f32_16x16x32_bf16 v[96:99], v[194:197], v[218:221], v[96:99]
	v_mfma_f32_16x16x32_bf16 v[84:87], v[174:177], v[226:229], v[84:87]
	v_mfma_f32_16x16x32_bf16 v[80:83], v[194:197], v[226:229], v[80:83]
	s_barrier
	v_add_u32_e32 v161, 0x18000, v38
	ds_read_b128 v[170:173], v161
	ds_read_b128 v[174:177], v161 offset:1024
	ds_read_b128 v[190:193], v161 offset:2048
	ds_read_b128 v[194:197], v161 offset:3072
	ds_read_b128 v[198:201], v39 offset:49152
	ds_read_b128 v[202:205], v39 offset:50176
	ds_read_b128 v[206:209], v39 offset:51200
	ds_read_b128 v[210:213], v39 offset:52224
	ds_read_b128 v[214:217], v39 offset:53248
	ds_read_b128 v[218:221], v39 offset:54272
	ds_read_b128 v[222:225], v39 offset:55296
	ds_read_b128 v[226:229], v39 offset:56320
	v_lshl_add_u64 v[178:179], s[14:15], 0, v[144:145]
	s_add_i32 m0, s1, 0x4000
	v_lshl_add_u64 v[230:231], s[14:15], 0, v[28:29]
	global_load_lds_dwordx4 v[178:179], off
	s_add_i32 m0, s1, 0x6000
	v_lshl_add_u64 v[232:233], s[2:3], 0, v[144:145]
	global_load_lds_dwordx4 v[230:231], off
	s_add_i32 m0, s1, 0x10000
	v_lshl_add_u64 v[234:235], s[2:3], 0, v[28:29]
	global_load_lds_dwordx4 v[232:233], off
	s_add_i32 m0, s1, 0x12000
	s_add_u32 s14, s14, 0x80
	s_addc_u32 s15, s15, 0
	global_load_lds_dwordx4 v[234:235], off
	s_add_u32 s2, s2, 0x80
	s_addc_u32 s3, s3, 0
	s_waitcnt vmcnt(8)
	s_waitcnt lgkmcnt(0)
	s_barrier
	v_mfma_f32_16x16x32_bf16 v[132:135], v[170:173], v[198:201], v[132:135]
	v_mfma_f32_16x16x32_bf16 v[128:131], v[190:193], v[198:201], v[128:131]
	v_mfma_f32_16x16x32_bf16 v[116:119], v[170:173], v[206:209], v[116:119]
	v_mfma_f32_16x16x32_bf16 v[112:115], v[190:193], v[206:209], v[112:115]
	v_mfma_f32_16x16x32_bf16 v[100:103], v[170:173], v[214:217], v[100:103]
	v_mfma_f32_16x16x32_bf16 v[96:99], v[190:193], v[214:217], v[96:99]
	v_mfma_f32_16x16x32_bf16 v[84:87], v[170:173], v[222:225], v[84:87]
	v_mfma_f32_16x16x32_bf16 v[80:83], v[190:193], v[222:225], v[80:83]
	v_mfma_f32_16x16x32_bf16 v[132:135], v[174:177], v[202:205], v[132:135]
	v_mfma_f32_16x16x32_bf16 v[128:131], v[194:197], v[202:205], v[128:131]
	v_mfma_f32_16x16x32_bf16 v[116:119], v[174:177], v[210:213], v[116:119]
	v_mfma_f32_16x16x32_bf16 v[112:115], v[194:197], v[210:213], v[112:115]
	v_mfma_f32_16x16x32_bf16 v[100:103], v[174:177], v[218:221], v[100:103]
	v_mfma_f32_16x16x32_bf16 v[96:99], v[194:197], v[218:221], v[96:99]
	v_mfma_f32_16x16x32_bf16 v[84:87], v[174:177], v[226:229], v[84:87]
	v_mfma_f32_16x16x32_bf16 v[80:83], v[194:197], v[226:229], v[80:83]
	s_barrier
	s_add_i32 s55, s55, 1
	s_cmp_lt_u32 s55, 7
	s_cbranch_scc1 .Lq_smp_1_k
	v_add_u32_e32 v161, 0x14000, v38
	ds_read_b128 v[170:173], v161
	ds_read_b128 v[174:177], v161 offset:1024
	ds_read_b128 v[190:193], v161 offset:2048
	ds_read_b128 v[194:197], v161 offset:3072
	ds_read_b128 v[198:201], v39 offset:0
	ds_read_b128 v[202:205], v39 offset:1024
	ds_read_b128 v[206:209], v39 offset:2048
	ds_read_b128 v[210:213], v39 offset:3072
	ds_read_b128 v[214:217], v39 offset:4096
	ds_read_b128 v[218:221], v39 offset:5120
	ds_read_b128 v[222:225], v39 offset:6144
	ds_read_b128 v[226:229], v39 offset:7168
	v_lshl_add_u64 v[178:179], s[14:15], 0, v[144:145]
	s_add_i32 m0, s1, 0xc000
	v_lshl_add_u64 v[230:231], s[14:15], 0, v[28:29]
	global_load_lds_dwordx4 v[178:179], off
	s_add_i32 m0, s1, 0xe000
	v_lshl_add_u64 v[232:233], s[2:3], 0, v[144:145]
	global_load_lds_dwordx4 v[230:231], off
	s_add_i32 m0, s1, 0x18000
	v_lshl_add_u64 v[234:235], s[2:3], 0, v[28:29]
	global_load_lds_dwordx4 v[232:233], off
	s_add_i32 m0, s1, 0x1a000
	s_add_u32 s14, s14, 0x80
	s_addc_u32 s15, s15, 0
	global_load_lds_dwordx4 v[234:235], off
	s_add_u32 s2, s2, 0x80
	s_addc_u32 s3, s3, 0
	s_waitcnt vmcnt(8)
	s_waitcnt lgkmcnt(0)
	s_barrier
	v_mfma_f32_16x16x32_bf16 v[132:135], v[170:173], v[198:201], v[132:135]
	v_mfma_f32_16x16x32_bf16 v[128:131], v[190:193], v[198:201], v[128:131]
	v_mfma_f32_16x16x32_bf16 v[116:119], v[170:173], v[206:209], v[116:119]
	v_mfma_f32_16x16x32_bf16 v[112:115], v[190:193], v[206:209], v[112:115]
	v_mfma_f32_16x16x32_bf16 v[100:103], v[170:173], v[214:217], v[100:103]
	v_mfma_f32_16x16x32_bf16 v[96:99], v[190:193], v[214:217], v[96:99]
	v_mfma_f32_16x16x32_bf16 v[84:87], v[170:173], v[222:225], v[84:87]
	v_mfma_f32_16x16x32_bf16 v[80:83], v[190:193], v[222:225], v[80:83]
	v_mfma_f32_16x16x32_bf16 v[132:135], v[174:177], v[202:205], v[132:135]
	v_mfma_f32_16x16x32_bf16 v[128:131], v[194:197], v[202:205], v[128:131]
	v_mfma_f32_16x16x32_bf16 v[116:119], v[174:177], v[210:213], v[116:119]
	v_mfma_f32_16x16x32_bf16 v[112:115], v[194:197], v[210:213], v[112:115]
	v_mfma_f32_16x16x32_bf16 v[100:103], v[174:177], v[218:221], v[100:103]
	v_mfma_f32_16x16x32_bf16 v[96:99], v[194:197], v[218:221], v[96:99]
	v_mfma_f32_16x16x32_bf16 v[84:87], v[174:177], v[226:229], v[84:87]
	v_mfma_f32_16x16x32_bf16 v[80:83], v[194:197], v[226:229], v[80:83]
	s_barrier
	v_add_u32_e32 v161, 0x1c000, v38
	ds_read_b128 v[170:173], v161
	ds_read_b128 v[174:177], v161 offset:1024
	ds_read_b128 v[190:193], v161 offset:2048
	ds_read_b128 v[194:197], v161 offset:3072
	ds_read_b128 v[198:201], v39 offset:32768
	ds_read_b128 v[202:205], v39 offset:33792
	ds_read_b128 v[206:209], v39 offset:34816
	ds_read_b128 v[210:213], v39 offset:35840
	ds_read_b128 v[214:217], v39 offset:36864
	ds_read_b128 v[218:221], v39 offset:37888
	ds_read_b128 v[222:225], v39 offset:38912
	ds_read_b128 v[226:229], v39 offset:39936
	s_waitcnt vmcnt(4)
	s_waitcnt lgkmcnt(0)
	s_barrier
	v_mfma_f32_16x16x32_bf16 v[132:135], v[170:173], v[198:201], v[132:135]
	v_mfma_f32_16x16x32_bf16 v[128:131], v[190:193], v[198:201], v[128:131]
	v_mfma_f32_16x16x32_bf16 v[116:119], v[170:173], v[206:209], v[116:119]
	v_mfma_f32_16x16x32_bf16 v[112:115], v[190:193], v[206:209], v[112:115]
	v_mfma_f32_16x16x32_bf16 v[100:103], v[170:173], v[214:217], v[100:103]
	v_mfma_f32_16x16x32_bf16 v[96:99], v[190:193], v[214:217], v[96:99]
	v_mfma_f32_16x16x32_bf16 v[84:87], v[170:173], v[222:225], v[84:87]
	v_mfma_f32_16x16x32_bf16 v[80:83], v[190:193], v[222:225], v[80:83]
	v_mfma_f32_16x16x32_bf16 v[132:135], v[174:177], v[202:205], v[132:135]
	v_mfma_f32_16x16x32_bf16 v[128:131], v[194:197], v[202:205], v[128:131]
	v_mfma_f32_16x16x32_bf16 v[116:119], v[174:177], v[210:213], v[116:119]
	v_mfma_f32_16x16x32_bf16 v[112:115], v[194:197], v[210:213], v[112:115]
	v_mfma_f32_16x16x32_bf16 v[100:103], v[174:177], v[218:221], v[100:103]
	v_mfma_f32_16x16x32_bf16 v[96:99], v[194:197], v[218:221], v[96:99]
	v_mfma_f32_16x16x32_bf16 v[84:87], v[174:177], v[226:229], v[84:87]
	v_mfma_f32_16x16x32_bf16 v[80:83], v[194:197], v[226:229], v[80:83]
	s_barrier
	v_add_u32_e32 v161, 0x10000, v38
	ds_read_b128 v[170:173], v161
	ds_read_b128 v[174:177], v161 offset:1024
	ds_read_b128 v[190:193], v161 offset:2048
	ds_read_b128 v[194:197], v161 offset:3072
	ds_read_b128 v[198:201], v39 offset:16384
	ds_read_b128 v[202:205], v39 offset:17408
	ds_read_b128 v[206:209], v39 offset:18432
	ds_read_b128 v[210:213], v39 offset:19456
	ds_read_b128 v[214:217], v39 offset:20480
	ds_read_b128 v[218:221], v39 offset:21504
	ds_read_b128 v[222:225], v39 offset:22528
	ds_read_b128 v[226:229], v39 offset:23552
	s_waitcnt vmcnt(0)
	s_waitcnt lgkmcnt(0)
	s_barrier
	v_mfma_f32_16x16x32_bf16 v[132:135], v[170:173], v[198:201], v[132:135]
	v_mfma_f32_16x16x32_bf16 v[128:131], v[190:193], v[198:201], v[128:131]
	v_mfma_f32_16x16x32_bf16 v[116:119], v[170:173], v[206:209], v[116:119]
	v_mfma_f32_16x16x32_bf16 v[112:115], v[190:193], v[206:209], v[112:115]
	v_mfma_f32_16x16x32_bf16 v[100:103], v[170:173], v[214:217], v[100:103]
	v_mfma_f32_16x16x32_bf16 v[96:99], v[190:193], v[214:217], v[96:99]
	v_mfma_f32_16x16x32_bf16 v[84:87], v[170:173], v[222:225], v[84:87]
	v_mfma_f32_16x16x32_bf16 v[80:83], v[190:193], v[222:225], v[80:83]
	v_mfma_f32_16x16x32_bf16 v[132:135], v[174:177], v[202:205], v[132:135]
	v_mfma_f32_16x16x32_bf16 v[128:131], v[194:197], v[202:205], v[128:131]
	v_mfma_f32_16x16x32_bf16 v[116:119], v[174:177], v[210:213], v[116:119]
	v_mfma_f32_16x16x32_bf16 v[112:115], v[194:197], v[210:213], v[112:115]
	v_mfma_f32_16x16x32_bf16 v[100:103], v[174:177], v[218:221], v[100:103]
	v_mfma_f32_16x16x32_bf16 v[96:99], v[194:197], v[218:221], v[96:99]
	v_mfma_f32_16x16x32_bf16 v[84:87], v[174:177], v[226:229], v[84:87]
	v_mfma_f32_16x16x32_bf16 v[80:83], v[194:197], v[226:229], v[80:83]
	s_barrier
	v_add_u32_e32 v161, 0x18000, v38
	ds_read_b128 v[170:173], v161
	ds_read_b128 v[174:177], v161 offset:1024
	ds_read_b128 v[190:193], v161 offset:2048
	ds_read_b128 v[194:197], v161 offset:3072
	ds_read_b128 v[198:201], v39 offset:49152
	ds_read_b128 v[202:205], v39 offset:50176
	ds_read_b128 v[206:209], v39 offset:51200
	ds_read_b128 v[210:213], v39 offset:52224
	ds_read_b128 v[214:217], v39 offset:53248
	ds_read_b128 v[218:221], v39 offset:54272
	ds_read_b128 v[222:225], v39 offset:55296
	ds_read_b128 v[226:229], v39 offset:56320
	s_waitcnt lgkmcnt(0)
	s_barrier
	v_mfma_f32_16x16x32_bf16 v[132:135], v[170:173], v[198:201], v[132:135]
	v_mfma_f32_16x16x32_bf16 v[128:131], v[190:193], v[198:201], v[128:131]
	v_mfma_f32_16x16x32_bf16 v[116:119], v[170:173], v[206:209], v[116:119]
	v_mfma_f32_16x16x32_bf16 v[112:115], v[190:193], v[206:209], v[112:115]
	v_mfma_f32_16x16x32_bf16 v[100:103], v[170:173], v[214:217], v[100:103]
	v_mfma_f32_16x16x32_bf16 v[96:99], v[190:193], v[214:217], v[96:99]
	v_mfma_f32_16x16x32_bf16 v[84:87], v[170:173], v[222:225], v[84:87]
	v_mfma_f32_16x16x32_bf16 v[80:83], v[190:193], v[222:225], v[80:83]
	v_mfma_f32_16x16x32_bf16 v[132:135], v[174:177], v[202:205], v[132:135]
	v_mfma_f32_16x16x32_bf16 v[128:131], v[194:197], v[202:205], v[128:131]
	v_mfma_f32_16x16x32_bf16 v[116:119], v[174:177], v[210:213], v[116:119]
	v_mfma_f32_16x16x32_bf16 v[112:115], v[194:197], v[210:213], v[112:115]
	v_mfma_f32_16x16x32_bf16 v[100:103], v[174:177], v[218:221], v[100:103]
	v_mfma_f32_16x16x32_bf16 v[96:99], v[194:197], v[218:221], v[96:99]
	v_mfma_f32_16x16x32_bf16 v[84:87], v[174:177], v[226:229], v[84:87]
	v_mfma_f32_16x16x32_bf16 v[80:83], v[194:197], v[226:229], v[80:83]
	s_barrier
	s_branch .Lq_smp_exit

.Lq_smp_2_k:
	v_add_u32_e32 v161, 0x10000, v38
	ds_read_b128 v[40:43], v161
	ds_read_b128 v[48:51], v161 offset:1024
	ds_read_b128 v[162:165], v161 offset:2048
	ds_read_b128 v[166:169], v161 offset:3072
	ds_read_b128 v[198:201], v39 offset:16384
	ds_read_b128 v[202:205], v39 offset:17408
	ds_read_b128 v[206:209], v39 offset:18432
	ds_read_b128 v[210:213], v39 offset:19456
	ds_read_b128 v[214:217], v39 offset:20480
	ds_read_b128 v[218:221], v39 offset:21504
	ds_read_b128 v[222:225], v39 offset:22528
	ds_read_b128 v[226:229], v39 offset:23552
	v_lshl_add_u64 v[178:179], s[14:15], 0, v[144:145]
	s_add_i32 m0, s1, 0x8000
	v_lshl_add_u64 v[230:231], s[14:15], 0, v[28:29]
	global_load_lds_dwordx4 v[178:179], off
	s_add_i32 m0, s1, 0xa000
	v_lshl_add_u64 v[232:233], s[2:3], 0, v[144:145]
	global_load_lds_dwordx4 v[230:231], off
	s_add_i32 m0, s1, 0x1c000
	v_lshl_add_u64 v[234:235], s[2:3], 0, v[28:29]
	global_load_lds_dwordx4 v[232:233], off
	s_add_i32 m0, s1, 0x1e000
	s_add_u32 s14, s14, 0x80
	s_addc_u32 s15, s15, 0
	global_load_lds_dwordx4 v[234:235], off
	s_add_u32 s2, s2, 0x80
	s_addc_u32 s3, s3, 0
	s_waitcnt vmcnt(8)
	s_waitcnt lgkmcnt(0)
	s_barrier
	v_mfma_f32_16x16x32_bf16 v[76:79], v[40:43], v[198:201], v[76:79]
	v_mfma_f32_16x16x32_bf16 v[72:75], v[162:165], v[198:201], v[72:75]
	v_mfma_f32_16x16x32_bf16 v[60:63], v[40:43], v[206:209], v[60:63]
	v_mfma_f32_16x16x32_bf16 v[56:59], v[162:165], v[206:209], v[56:59]
	v_mfma_f32_16x16x32_bf16 v[32:35], v[40:43], v[214:217], v[32:35]
	v_mfma_f32_16x16x32_bf16 v[24:27], v[162:165], v[214:217], v[24:27]
	v_mfma_f32_16x16x32_bf16 v[12:15], v[40:43], v[222:225], v[12:15]
	v_mfma_f32_16x16x32_bf16 v[8:11], v[162:165], v[222:225], v[8:11]
	v_mfma_f32_16x16x32_bf16 v[76:79], v[48:51], v[202:205], v[76:79]
	v_mfma_f32_16x16x32_bf16 v[72:75], v[166:169], v[202:205], v[72:75]
	v_mfma_f32_16x16x32_bf16 v[60:63], v[48:51], v[210:213], v[60:63]
	v_mfma_f32_16x16x32_bf16 v[56:59], v[166:169], v[210:213], v[56:59]
	v_mfma_f32_16x16x32_bf16 v[32:35], v[48:51], v[218:221], v[32:35]
	v_mfma_f32_16x16x32_bf16 v[24:27], v[166:169], v[218:221], v[24:27]
	v_mfma_f32_16x16x32_bf16 v[12:15], v[48:51], v[226:229], v[12:15]
	v_mfma_f32_16x16x32_bf16 v[8:11], v[166:169], v[226:229], v[8:11]
	s_barrier
	v_add_u32_e32 v161, 0x18000, v38
	ds_read_b128 v[40:43], v161
	ds_read_b128 v[48:51], v161 offset:1024
	ds_read_b128 v[162:165], v161 offset:2048
	ds_read_b128 v[166:169], v161 offset:3072
	ds_read_b128 v[198:201], v39 offset:49152
	ds_read_b128 v[202:205], v39 offset:50176
	ds_read_b128 v[206:209], v39 offset:51200
	ds_read_b128 v[210:213], v39 offset:52224
	ds_read_b128 v[214:217], v39 offset:53248
	ds_read_b128 v[218:221], v39 offset:54272
	ds_read_b128 v[222:225], v39 offset:55296
	ds_read_b128 v[226:229], v39 offset:56320
	v_lshl_add_u64 v[178:179], s[14:15], 0, v[144:145]
	s_add_i32 m0, s1, 0x4000
	v_lshl_add_u64 v[230:231], s[14:15], 0, v[28:29]
	global_load_lds_dwordx4 v[178:179], off
	s_add_i32 m0, s1, 0x6000
	v_lshl_add_u64 v[232:233], s[2:3], 0, v[144:145]
	global_load_lds_dwordx4 v[230:231], off
	s_add_i32 m0, s1, 0x10000
	v_lshl_add_u64 v[234:235], s[2:3], 0, v[28:29]
	global_load_lds_dwordx4 v[232:233], off
	s_add_i32 m0, s1, 0x12000
	s_add_u32 s14, s14, 0x80
	s_addc_u32 s15, s15, 0
	global_load_lds_dwordx4 v[234:235], off
	s_add_u32 s2, s2, 0x80
	s_addc_u32 s3, s3, 0
	s_waitcnt vmcnt(8)
	s_waitcnt lgkmcnt(0)
	s_barrier
	v_mfma_f32_16x16x32_bf16 v[76:79], v[40:43], v[198:201], v[76:79]
	v_mfma_f32_16x16x32_bf16 v[72:75], v[162:165], v[198:201], v[72:75]
	v_mfma_f32_16x16x32_bf16 v[60:63], v[40:43], v[206:209], v[60:63]
	v_mfma_f32_16x16x32_bf16 v[56:59], v[162:165], v[206:209], v[56:59]
	v_mfma_f32_16x16x32_bf16 v[32:35], v[40:43], v[214:217], v[32:35]
	v_mfma_f32_16x16x32_bf16 v[24:27], v[162:165], v[214:217], v[24:27]
	v_mfma_f32_16x16x32_bf16 v[12:15], v[40:43], v[222:225], v[12:15]
	v_mfma_f32_16x16x32_bf16 v[8:11], v[162:165], v[222:225], v[8:11]
	v_mfma_f32_16x16x32_bf16 v[76:79], v[48:51], v[202:205], v[76:79]
	v_mfma_f32_16x16x32_bf16 v[72:75], v[166:169], v[202:205], v[72:75]
	v_mfma_f32_16x16x32_bf16 v[60:63], v[48:51], v[210:213], v[60:63]
	v_mfma_f32_16x16x32_bf16 v[56:59], v[166:169], v[210:213], v[56:59]
	v_mfma_f32_16x16x32_bf16 v[32:35], v[48:51], v[218:221], v[32:35]
	v_mfma_f32_16x16x32_bf16 v[24:27], v[166:169], v[218:221], v[24:27]
	v_mfma_f32_16x16x32_bf16 v[12:15], v[48:51], v[226:229], v[12:15]
	v_mfma_f32_16x16x32_bf16 v[8:11], v[166:169], v[226:229], v[8:11]
	s_barrier
	v_add_u32_e32 v161, 0x14000, v38
	ds_read_b128 v[40:43], v161
	ds_read_b128 v[48:51], v161 offset:1024
	ds_read_b128 v[162:165], v161 offset:2048
	ds_read_b128 v[166:169], v161 offset:3072
	ds_read_b128 v[198:201], v39 offset:0
	ds_read_b128 v[202:205], v39 offset:1024
	ds_read_b128 v[206:209], v39 offset:2048
	ds_read_b128 v[210:213], v39 offset:3072
	ds_read_b128 v[214:217], v39 offset:4096
	ds_read_b128 v[218:221], v39 offset:5120
	ds_read_b128 v[222:225], v39 offset:6144
	ds_read_b128 v[226:229], v39 offset:7168
	v_lshl_add_u64 v[178:179], s[14:15], 0, v[144:145]
	s_add_i32 m0, s1, 0xc000
	v_lshl_add_u64 v[230:231], s[14:15], 0, v[28:29]
	global_load_lds_dwordx4 v[178:179], off
	s_add_i32 m0, s1, 0xe000
	v_lshl_add_u64 v[232:233], s[2:3], 0, v[144:145]
	global_load_lds_dwordx4 v[230:231], off
	s_add_i32 m0, s1, 0x18000
	v_lshl_add_u64 v[234:235], s[2:3], 0, v[28:29]
	global_load_lds_dwordx4 v[232:233], off
	s_add_i32 m0, s1, 0x1a000
	s_add_u32 s14, s14, 0x80
	s_addc_u32 s15, s15, 0
	global_load_lds_dwordx4 v[234:235], off
	s_add_u32 s2, s2, 0x80
	s_addc_u32 s3, s3, 0
	s_waitcnt vmcnt(8)
	s_waitcnt lgkmcnt(0)
	s_barrier
	v_mfma_f32_16x16x32_bf16 v[76:79], v[40:43], v[198:201], v[76:79]
	v_mfma_f32_16x16x32_bf16 v[72:75], v[162:165], v[198:201], v[72:75]
	v_mfma_f32_16x16x32_bf16 v[60:63], v[40:43], v[206:209], v[60:63]
	v_mfma_f32_16x16x32_bf16 v[56:59], v[162:165], v[206:209], v[56:59]
	v_mfma_f32_16x16x32_bf16 v[32:35], v[40:43], v[214:217], v[32:35]
	v_mfma_f32_16x16x32_bf16 v[24:27], v[162:165], v[214:217], v[24:27]
	v_mfma_f32_16x16x32_bf16 v[12:15], v[40:43], v[222:225], v[12:15]
	v_mfma_f32_16x16x32_bf16 v[8:11], v[162:165], v[222:225], v[8:11]
	v_mfma_f32_16x16x32_bf16 v[76:79], v[48:51], v[202:205], v[76:79]
	v_mfma_f32_16x16x32_bf16 v[72:75], v[166:169], v[202:205], v[72:75]
	v_mfma_f32_16x16x32_bf16 v[60:63], v[48:51], v[210:213], v[60:63]
	v_mfma_f32_16x16x32_bf16 v[56:59], v[166:169], v[210:213], v[56:59]
	v_mfma_f32_16x16x32_bf16 v[32:35], v[48:51], v[218:221], v[32:35]
	v_mfma_f32_16x16x32_bf16 v[24:27], v[166:169], v[218:221], v[24:27]
	v_mfma_f32_16x16x32_bf16 v[12:15], v[48:51], v[226:229], v[12:15]
	v_mfma_f32_16x16x32_bf16 v[8:11], v[166:169], v[226:229], v[8:11]
	s_barrier
	v_add_u32_e32 v161, 0x1c000, v38
	ds_read_b128 v[40:43], v161
	ds_read_b128 v[48:51], v161 offset:1024
	ds_read_b128 v[162:165], v161 offset:2048
	ds_read_b128 v[166:169], v161 offset:3072
	ds_read_b128 v[198:201], v39 offset:32768
	ds_read_b128 v[202:205], v39 offset:33792
	ds_read_b128 v[206:209], v39 offset:34816
	ds_read_b128 v[210:213], v39 offset:35840
	ds_read_b128 v[214:217], v39 offset:36864
	ds_read_b128 v[218:221], v39 offset:37888
	ds_read_b128 v[222:225], v39 offset:38912
	ds_read_b128 v[226:229], v39 offset:39936
	v_lshl_add_u64 v[178:179], s[14:15], 0, v[144:145]
	s_add_i32 m0, s1, 0x0
	v_lshl_add_u64 v[230:231], s[14:15], 0, v[28:29]
	global_load_lds_dwordx4 v[178:179], off
	s_add_i32 m0, s1, 0x2000
	v_lshl_add_u64 v[232:233], s[2:3], 0, v[144:145]
	global_load_lds_dwordx4 v[230:231], off
	s_add_i32 m0, s1, 0x14000
	v_lshl_add_u64 v[234:235], s[2:3], 0, v[28:29]
	global_load_lds_dwordx4 v[232:233], off
	s_add_i32 m0, s1, 0x16000
	s_add_u32 s14, s14, 0x80
	s_addc_u32 s15, s15, 0
	global_load_lds_dwordx4 v[234:235], off
	s_add_u32 s2, s2, 0x80
	s_addc_u32 s3, s3, 0
	s_waitcnt vmcnt(8)
	s_waitcnt lgkmcnt(0)
	s_barrier
	v_mfma_f32_16x16x32_bf16 v[76:79], v[40:43], v[198:201], v[76:79]
	v_mfma_f32_16x16x32_bf16 v[72:75], v[162:165], v[198:201], v[72:75]
	v_mfma_f32_16x16x32_bf16 v[60:63], v[40:43], v[206:209], v[60:63]
	v_mfma_f32_16x16x32_bf16 v[56:59], v[162:165], v[206:209], v[56:59]
	v_mfma_f32_16x16x32_bf16 v[32:35], v[40:43], v[214:217], v[32:35]
	v_mfma_f32_16x16x32_bf16 v[24:27], v[162:165], v[214:217], v[24:27]
	v_mfma_f32_16x16x32_bf16 v[12:15], v[40:43], v[222:225], v[12:15]
	v_mfma_f32_16x16x32_bf16 v[8:11], v[162:165], v[222:225], v[8:11]
	v_mfma_f32_16x16x32_bf16 v[76:79], v[48:51], v[202:205], v[76:79]
	v_mfma_f32_16x16x32_bf16 v[72:75], v[166:169], v[202:205], v[72:75]
	v_mfma_f32_16x16x32_bf16 v[60:63], v[48:51], v[210:213], v[60:63]
	v_mfma_f32_16x16x32_bf16 v[56:59], v[166:169], v[210:213], v[56:59]
	v_mfma_f32_16x16x32_bf16 v[32:35], v[48:51], v[218:221], v[32:35]
	v_mfma_f32_16x16x32_bf16 v[24:27], v[166:169], v[218:221], v[24:27]
	v_mfma_f32_16x16x32_bf16 v[12:15], v[48:51], v[226:229], v[12:15]
	v_mfma_f32_16x16x32_bf16 v[8:11], v[166:169], v[226:229], v[8:11]
	s_barrier
	s_add_i32 s55, s55, 1
	s_cmp_lt_u32 s55, 7
	s_cbranch_scc1 .Lq_smp_2_k
	v_add_u32_e32 v161, 0x10000, v38
	ds_read_b128 v[40:43], v161
	ds_read_b128 v[48:51], v161 offset:1024
	ds_read_b128 v[162:165], v161 offset:2048
	ds_read_b128 v[166:169], v161 offset:3072
	ds_read_b128 v[198:201], v39 offset:16384
	ds_read_b128 v[202:205], v39 offset:17408
	ds_read_b128 v[206:209], v39 offset:18432
	ds_read_b128 v[210:213], v39 offset:19456
	ds_read_b128 v[214:217], v39 offset:20480
	ds_read_b128 v[218:221], v39 offset:21504
	ds_read_b128 v[222:225], v39 offset:22528
	ds_read_b128 v[226:229], v39 offset:23552
	v_lshl_add_u64 v[178:179], s[14:15], 0, v[144:145]
	s_add_i32 m0, s1, 0x8000
	v_lshl_add_u64 v[230:231], s[14:15], 0, v[28:29]
	global_load_lds_dwordx4 v[178:179], off
	s_add_i32 m0, s1, 0xa000
	v_lshl_add_u64 v[232:233], s[2:3], 0, v[144:145]
	global_load_lds_dwordx4 v[230:231], off
	s_add_i32 m0, s1, 0x1c000
	v_lshl_add_u64 v[234:235], s[2:3], 0, v[28:29]
	global_load_lds_dwordx4 v[232:233], off
	s_add_i32 m0, s1, 0x1e000
	s_add_u32 s14, s14, 0x80
	s_addc_u32 s15, s15, 0
	global_load_lds_dwordx4 v[234:235], off
	s_add_u32 s2, s2, 0x80
	s_addc_u32 s3, s3, 0
	s_waitcnt vmcnt(8)
	s_waitcnt lgkmcnt(0)
	s_barrier
	v_mfma_f32_16x16x32_bf16 v[76:79], v[40:43], v[198:201], v[76:79]
	v_mfma_f32_16x16x32_bf16 v[72:75], v[162:165], v[198:201], v[72:75]
	v_mfma_f32_16x16x32_bf16 v[60:63], v[40:43], v[206:209], v[60:63]
	v_mfma_f32_16x16x32_bf16 v[56:59], v[162:165], v[206:209], v[56:59]
	v_mfma_f32_16x16x32_bf16 v[32:35], v[40:43], v[214:217], v[32:35]
	v_mfma_f32_16x16x32_bf16 v[24:27], v[162:165], v[214:217], v[24:27]
	v_mfma_f32_16x16x32_bf16 v[12:15], v[40:43], v[222:225], v[12:15]
	v_mfma_f32_16x16x32_bf16 v[8:11], v[162:165], v[222:225], v[8:11]
	v_mfma_f32_16x16x32_bf16 v[76:79], v[48:51], v[202:205], v[76:79]
	v_mfma_f32_16x16x32_bf16 v[72:75], v[166:169], v[202:205], v[72:75]
	v_mfma_f32_16x16x32_bf16 v[60:63], v[48:51], v[210:213], v[60:63]
	v_mfma_f32_16x16x32_bf16 v[56:59], v[166:169], v[210:213], v[56:59]
	v_mfma_f32_16x16x32_bf16 v[32:35], v[48:51], v[218:221], v[32:35]
	v_mfma_f32_16x16x32_bf16 v[24:27], v[166:169], v[218:221], v[24:27]
	v_mfma_f32_16x16x32_bf16 v[12:15], v[48:51], v[226:229], v[12:15]
	v_mfma_f32_16x16x32_bf16 v[8:11], v[166:169], v[226:229], v[8:11]
	s_barrier
	v_add_u32_e32 v161, 0x18000, v38
	ds_read_b128 v[40:43], v161
	ds_read_b128 v[48:51], v161 offset:1024
	ds_read_b128 v[162:165], v161 offset:2048
	ds_read_b128 v[166:169], v161 offset:3072
	ds_read_b128 v[198:201], v39 offset:49152
	ds_read_b128 v[202:205], v39 offset:50176
	ds_read_b128 v[206:209], v39 offset:51200
	ds_read_b128 v[210:213], v39 offset:52224
	ds_read_b128 v[214:217], v39 offset:53248
	ds_read_b128 v[218:221], v39 offset:54272
	ds_read_b128 v[222:225], v39 offset:55296
	ds_read_b128 v[226:229], v39 offset:56320
	s_waitcnt vmcnt(4)
	s_waitcnt lgkmcnt(0)
	s_barrier
	v_mfma_f32_16x16x32_bf16 v[76:79], v[40:43], v[198:201], v[76:79]
	v_mfma_f32_16x16x32_bf16 v[72:75], v[162:165], v[198:201], v[72:75]
	v_mfma_f32_16x16x32_bf16 v[60:63], v[40:43], v[206:209], v[60:63]
	v_mfma_f32_16x16x32_bf16 v[56:59], v[162:165], v[206:209], v[56:59]
	v_mfma_f32_16x16x32_bf16 v[32:35], v[40:43], v[214:217], v[32:35]
	v_mfma_f32_16x16x32_bf16 v[24:27], v[162:165], v[214:217], v[24:27]
	v_mfma_f32_16x16x32_bf16 v[12:15], v[40:43], v[222:225], v[12:15]
	v_mfma_f32_16x16x32_bf16 v[8:11], v[162:165], v[222:225], v[8:11]
	v_mfma_f32_16x16x32_bf16 v[76:79], v[48:51], v[202:205], v[76:79]
	v_mfma_f32_16x16x32_bf16 v[72:75], v[166:169], v[202:205], v[72:75]
	v_mfma_f32_16x16x32_bf16 v[60:63], v[48:51], v[210:213], v[60:63]
	v_mfma_f32_16x16x32_bf16 v[56:59], v[166:169], v[210:213], v[56:59]
	v_mfma_f32_16x16x32_bf16 v[32:35], v[48:51], v[218:221], v[32:35]
	v_mfma_f32_16x16x32_bf16 v[24:27], v[166:169], v[218:221], v[24:27]
	v_mfma_f32_16x16x32_bf16 v[12:15], v[48:51], v[226:229], v[12:15]
	v_mfma_f32_16x16x32_bf16 v[8:11], v[166:169], v[226:229], v[8:11]
	s_barrier
	v_add_u32_e32 v161, 0x14000, v38
	ds_read_b128 v[40:43], v161
	ds_read_b128 v[48:51], v161 offset:1024
	ds_read_b128 v[162:165], v161 offset:2048
	ds_read_b128 v[166:169], v161 offset:3072
	ds_read_b128 v[198:201], v39 offset:0
	ds_read_b128 v[202:205], v39 offset:1024
	ds_read_b128 v[206:209], v39 offset:2048
	ds_read_b128 v[210:213], v39 offset:3072
	ds_read_b128 v[214:217], v39 offset:4096
	ds_read_b128 v[218:221], v39 offset:5120
	ds_read_b128 v[222:225], v39 offset:6144
	ds_read_b128 v[226:229], v39 offset:7168
	s_waitcnt vmcnt(0)
	s_waitcnt lgkmcnt(0)
	s_barrier
	v_mfma_f32_16x16x32_bf16 v[76:79], v[40:43], v[198:201], v[76:79]
	v_mfma_f32_16x16x32_bf16 v[72:75], v[162:165], v[198:201], v[72:75]
	v_mfma_f32_16x16x32_bf16 v[60:63], v[40:43], v[206:209], v[60:63]
	v_mfma_f32_16x16x32_bf16 v[56:59], v[162:165], v[206:209], v[56:59]
	v_mfma_f32_16x16x32_bf16 v[32:35], v[40:43], v[214:217], v[32:35]
	v_mfma_f32_16x16x32_bf16 v[24:27], v[162:165], v[214:217], v[24:27]
	v_mfma_f32_16x16x32_bf16 v[12:15], v[40:43], v[222:225], v[12:15]
	v_mfma_f32_16x16x32_bf16 v[8:11], v[162:165], v[222:225], v[8:11]
	v_mfma_f32_16x16x32_bf16 v[76:79], v[48:51], v[202:205], v[76:79]
	v_mfma_f32_16x16x32_bf16 v[72:75], v[166:169], v[202:205], v[72:75]
	v_mfma_f32_16x16x32_bf16 v[60:63], v[48:51], v[210:213], v[60:63]
	v_mfma_f32_16x16x32_bf16 v[56:59], v[166:169], v[210:213], v[56:59]
	v_mfma_f32_16x16x32_bf16 v[32:35], v[48:51], v[218:221], v[32:35]
	v_mfma_f32_16x16x32_bf16 v[24:27], v[166:169], v[218:221], v[24:27]
	v_mfma_f32_16x16x32_bf16 v[12:15], v[48:51], v[226:229], v[12:15]
	v_mfma_f32_16x16x32_bf16 v[8:11], v[166:169], v[226:229], v[8:11]
	s_barrier
	v_add_u32_e32 v161, 0x1c000, v38
	ds_read_b128 v[40:43], v161
	ds_read_b128 v[48:51], v161 offset:1024
	ds_read_b128 v[162:165], v161 offset:2048
	ds_read_b128 v[166:169], v161 offset:3072
	ds_read_b128 v[198:201], v39 offset:32768
	ds_read_b128 v[202:205], v39 offset:33792
	ds_read_b128 v[206:209], v39 offset:34816
	ds_read_b128 v[210:213], v39 offset:35840
	ds_read_b128 v[214:217], v39 offset:36864
	ds_read_b128 v[218:221], v39 offset:37888
	ds_read_b128 v[222:225], v39 offset:38912
	ds_read_b128 v[226:229], v39 offset:39936
	s_waitcnt lgkmcnt(0)
	s_barrier
	v_mfma_f32_16x16x32_bf16 v[76:79], v[40:43], v[198:201], v[76:79]
	v_mfma_f32_16x16x32_bf16 v[72:75], v[162:165], v[198:201], v[72:75]
	v_mfma_f32_16x16x32_bf16 v[60:63], v[40:43], v[206:209], v[60:63]
	v_mfma_f32_16x16x32_bf16 v[56:59], v[162:165], v[206:209], v[56:59]
	v_mfma_f32_16x16x32_bf16 v[32:35], v[40:43], v[214:217], v[32:35]
	v_mfma_f32_16x16x32_bf16 v[24:27], v[162:165], v[214:217], v[24:27]
	v_mfma_f32_16x16x32_bf16 v[12:15], v[40:43], v[222:225], v[12:15]
	v_mfma_f32_16x16x32_bf16 v[8:11], v[162:165], v[222:225], v[8:11]
	v_mfma_f32_16x16x32_bf16 v[76:79], v[48:51], v[202:205], v[76:79]
	v_mfma_f32_16x16x32_bf16 v[72:75], v[166:169], v[202:205], v[72:75]
	v_mfma_f32_16x16x32_bf16 v[60:63], v[48:51], v[210:213], v[60:63]
	v_mfma_f32_16x16x32_bf16 v[56:59], v[166:169], v[210:213], v[56:59]
	v_mfma_f32_16x16x32_bf16 v[32:35], v[48:51], v[218:221], v[32:35]
	v_mfma_f32_16x16x32_bf16 v[24:27], v[166:169], v[218:221], v[24:27]
	v_mfma_f32_16x16x32_bf16 v[12:15], v[48:51], v[226:229], v[12:15]
	v_mfma_f32_16x16x32_bf16 v[8:11], v[166:169], v[226:229], v[8:11]
	s_barrier
	s_branch .Lq_smp_exit

.Lq_smp_3_k:
	v_add_u32_e32 v161, 0x14000, v38
	ds_read_b128 v[170:173], v161
	ds_read_b128 v[174:177], v161 offset:1024
	ds_read_b128 v[190:193], v161 offset:2048
	ds_read_b128 v[194:197], v161 offset:3072
	ds_read_b128 v[198:201], v39 offset:16384
	ds_read_b128 v[202:205], v39 offset:17408
	ds_read_b128 v[206:209], v39 offset:18432
	ds_read_b128 v[210:213], v39 offset:19456
	ds_read_b128 v[214:217], v39 offset:20480
	ds_read_b128 v[218:221], v39 offset:21504
	ds_read_b128 v[222:225], v39 offset:22528
	ds_read_b128 v[226:229], v39 offset:23552
	v_lshl_add_u64 v[178:179], s[14:15], 0, v[144:145]
	s_add_i32 m0, s1, 0x8000
	v_lshl_add_u64 v[230:231], s[14:15], 0, v[28:29]
	global_load_lds_dwordx4 v[178:179], off
	s_add_i32 m0, s1, 0xa000
	v_lshl_add_u64 v[232:233], s[2:3], 0, v[144:145]
	global_load_lds_dwordx4 v[230:231], off
	s_add_i32 m0, s1, 0x18000
	v_lshl_add_u64 v[234:235], s[2:3], 0, v[28:29]
	global_load_lds_dwordx4 v[232:233], off
	s_add_i32 m0, s1, 0x1a000
	s_add_u32 s14, s14, 0x80
	s_addc_u32 s15, s15, 0
	global_load_lds_dwordx4 v[234:235], off
	s_add_u32 s2, s2, 0x80
	s_addc_u32 s3, s3, 0
	s_waitcnt vmcnt(8)
	s_waitcnt lgkmcnt(0)
	s_barrier
	v_mfma_f32_16x16x32_bf16 v[52:55], v[170:173], v[206:209], v[52:55]
	v_mfma_f32_16x16x32_bf16 v[44:47], v[190:193], v[206:209], v[44:47]
	v_mfma_f32_16x16x32_bf16 v[20:23], v[170:173], v[214:217], v[20:23]
	v_mfma_f32_16x16x32_bf16 v[16:19], v[190:193], v[214:217], v[16:19]
	v_mfma_f32_16x16x32_bf16 v[4:7], v[170:173], v[222:225], v[4:7]
	v_mfma_f32_16x16x32_bf16 v[0:3], v[190:193], v[222:225], v[0:3]
	v_mfma_f32_16x16x32_bf16 v[68:71], v[170:173], v[198:201], v[68:71]
	v_mfma_f32_16x16x32_bf16 v[64:67], v[190:193], v[198:201], v[64:67]
	v_mfma_f32_16x16x32_bf16 v[52:55], v[174:177], v[210:213], v[52:55]
	v_mfma_f32_16x16x32_bf16 v[44:47], v[194:197], v[210:213], v[44:47]
	v_mfma_f32_16x16x32_bf16 v[20:23], v[174:177], v[218:221], v[20:23]
	v_mfma_f32_16x16x32_bf16 v[16:19], v[194:197], v[218:221], v[16:19]
	v_mfma_f32_16x16x32_bf16 v[4:7], v[174:177], v[226:229], v[4:7]
	v_mfma_f32_16x16x32_bf16 v[0:3], v[194:197], v[226:229], v[0:3]
	v_mfma_f32_16x16x32_bf16 v[68:71], v[174:177], v[202:205], v[68:71]
	v_mfma_f32_16x16x32_bf16 v[64:67], v[194:197], v[202:205], v[64:67]
	s_barrier
	v_add_u32_e32 v161, 0x1c000, v38
	ds_read_b128 v[170:173], v161
	ds_read_b128 v[174:177], v161 offset:1024
	ds_read_b128 v[190:193], v161 offset:2048
	ds_read_b128 v[194:197], v161 offset:3072
	ds_read_b128 v[198:201], v39 offset:49152
	ds_read_b128 v[202:205], v39 offset:50176
	ds_read_b128 v[206:209], v39 offset:51200
	ds_read_b128 v[210:213], v39 offset:52224
	ds_read_b128 v[214:217], v39 offset:53248
	ds_read_b128 v[218:221], v39 offset:54272
	ds_read_b128 v[222:225], v39 offset:55296
	ds_read_b128 v[226:229], v39 offset:56320
	v_lshl_add_u64 v[178:179], s[14:15], 0, v[144:145]
	s_add_i32 m0, s1, 0x4000
	v_lshl_add_u64 v[230:231], s[14:15], 0, v[28:29]
	global_load_lds_dwordx4 v[178:179], off
	s_add_i32 m0, s1, 0x6000
	v_lshl_add_u64 v[232:233], s[2:3], 0, v[144:145]
	global_load_lds_dwordx4 v[230:231], off
	s_add_i32 m0, s1, 0x14000
	v_lshl_add_u64 v[234:235], s[2:3], 0, v[28:29]
	global_load_lds_dwordx4 v[232:233], off
	s_add_i32 m0, s1, 0x16000
	s_add_u32 s14, s14, 0x80
	s_addc_u32 s15, s15, 0
	global_load_lds_dwordx4 v[234:235], off
	s_add_u32 s2, s2, 0x80
	s_addc_u32 s3, s3, 0
	s_waitcnt vmcnt(8)
	s_waitcnt lgkmcnt(0)
	s_barrier
	v_mfma_f32_16x16x32_bf16 v[52:55], v[170:173], v[206:209], v[52:55]
	v_mfma_f32_16x16x32_bf16 v[44:47], v[190:193], v[206:209], v[44:47]
	v_mfma_f32_16x16x32_bf16 v[20:23], v[170:173], v[214:217], v[20:23]
	v_mfma_f32_16x16x32_bf16 v[16:19], v[190:193], v[214:217], v[16:19]
	v_mfma_f32_16x16x32_bf16 v[4:7], v[170:173], v[222:225], v[4:7]
	v_mfma_f32_16x16x32_bf16 v[0:3], v[190:193], v[222:225], v[0:3]
	v_mfma_f32_16x16x32_bf16 v[68:71], v[170:173], v[198:201], v[68:71]
	v_mfma_f32_16x16x32_bf16 v[64:67], v[190:193], v[198:201], v[64:67]
	v_mfma_f32_16x16x32_bf16 v[52:55], v[174:177], v[210:213], v[52:55]
	v_mfma_f32_16x16x32_bf16 v[44:47], v[194:197], v[210:213], v[44:47]
	v_mfma_f32_16x16x32_bf16 v[20:23], v[174:177], v[218:221], v[20:23]
	v_mfma_f32_16x16x32_bf16 v[16:19], v[194:197], v[218:221], v[16:19]
	v_mfma_f32_16x16x32_bf16 v[4:7], v[174:177], v[226:229], v[4:7]
	v_mfma_f32_16x16x32_bf16 v[0:3], v[194:197], v[226:229], v[0:3]
	v_mfma_f32_16x16x32_bf16 v[68:71], v[174:177], v[202:205], v[68:71]
	v_mfma_f32_16x16x32_bf16 v[64:67], v[194:197], v[202:205], v[64:67]
	s_barrier
	v_add_u32_e32 v161, 0x10000, v38
	ds_read_b128 v[170:173], v161
	ds_read_b128 v[174:177], v161 offset:1024
	ds_read_b128 v[190:193], v161 offset:2048
	ds_read_b128 v[194:197], v161 offset:3072
	ds_read_b128 v[198:201], v39 offset:0
	ds_read_b128 v[202:205], v39 offset:1024
	ds_read_b128 v[206:209], v39 offset:2048
	ds_read_b128 v[210:213], v39 offset:3072
	ds_read_b128 v[214:217], v39 offset:4096
	ds_read_b128 v[218:221], v39 offset:5120
	ds_read_b128 v[222:225], v39 offset:6144
	ds_read_b128 v[226:229], v39 offset:7168
	v_lshl_add_u64 v[178:179], s[14:15], 0, v[144:145]
	s_add_i32 m0, s1, 0xc000
	v_lshl_add_u64 v[230:231], s[14:15], 0, v[28:29]
	global_load_lds_dwordx4 v[178:179], off
	s_add_i32 m0, s1, 0xe000
	v_lshl_add_u64 v[232:233], s[2:3], 0, v[144:145]
	global_load_lds_dwordx4 v[230:231], off
	s_add_i32 m0, s1, 0x1c000
	v_lshl_add_u64 v[234:235], s[2:3], 0, v[28:29]
	global_load_lds_dwordx4 v[232:233], off
	s_add_i32 m0, s1, 0x1e000
	s_add_u32 s14, s14, 0x80
	s_addc_u32 s15, s15, 0
	global_load_lds_dwordx4 v[234:235], off
	s_add_u32 s2, s2, 0x80
	s_addc_u32 s3, s3, 0
	s_waitcnt vmcnt(8)
	s_waitcnt lgkmcnt(0)
	s_barrier
	v_mfma_f32_16x16x32_bf16 v[52:55], v[170:173], v[206:209], v[52:55]
	v_mfma_f32_16x16x32_bf16 v[44:47], v[190:193], v[206:209], v[44:47]
	v_mfma_f32_16x16x32_bf16 v[20:23], v[170:173], v[214:217], v[20:23]
	v_mfma_f32_16x16x32_bf16 v[16:19], v[190:193], v[214:217], v[16:19]
	v_mfma_f32_16x16x32_bf16 v[4:7], v[170:173], v[222:225], v[4:7]
	v_mfma_f32_16x16x32_bf16 v[0:3], v[190:193], v[222:225], v[0:3]
	v_mfma_f32_16x16x32_bf16 v[68:71], v[170:173], v[198:201], v[68:71]
	v_mfma_f32_16x16x32_bf16 v[64:67], v[190:193], v[198:201], v[64:67]
	v_mfma_f32_16x16x32_bf16 v[52:55], v[174:177], v[210:213], v[52:55]
	v_mfma_f32_16x16x32_bf16 v[44:47], v[194:197], v[210:213], v[44:47]
	v_mfma_f32_16x16x32_bf16 v[20:23], v[174:177], v[218:221], v[20:23]
	v_mfma_f32_16x16x32_bf16 v[16:19], v[194:197], v[218:221], v[16:19]
	v_mfma_f32_16x16x32_bf16 v[4:7], v[174:177], v[226:229], v[4:7]
	v_mfma_f32_16x16x32_bf16 v[0:3], v[194:197], v[226:229], v[0:3]
	v_mfma_f32_16x16x32_bf16 v[68:71], v[174:177], v[202:205], v[68:71]
	v_mfma_f32_16x16x32_bf16 v[64:67], v[194:197], v[202:205], v[64:67]
	s_barrier
	v_add_u32_e32 v161, 0x18000, v38
	ds_read_b128 v[170:173], v161
	ds_read_b128 v[174:177], v161 offset:1024
	ds_read_b128 v[190:193], v161 offset:2048
	ds_read_b128 v[194:197], v161 offset:3072
	ds_read_b128 v[198:201], v39 offset:32768
	ds_read_b128 v[202:205], v39 offset:33792
	ds_read_b128 v[206:209], v39 offset:34816
	ds_read_b128 v[210:213], v39 offset:35840
	ds_read_b128 v[214:217], v39 offset:36864
	ds_read_b128 v[218:221], v39 offset:37888
	ds_read_b128 v[222:225], v39 offset:38912
	ds_read_b128 v[226:229], v39 offset:39936
	v_lshl_add_u64 v[178:179], s[14:15], 0, v[144:145]
	s_add_i32 m0, s1, 0x0
	v_lshl_add_u64 v[230:231], s[14:15], 0, v[28:29]
	global_load_lds_dwordx4 v[178:179], off
	s_add_i32 m0, s1, 0x2000
	v_lshl_add_u64 v[232:233], s[2:3], 0, v[144:145]
	global_load_lds_dwordx4 v[230:231], off
	s_add_i32 m0, s1, 0x10000
	v_lshl_add_u64 v[234:235], s[2:3], 0, v[28:29]
	global_load_lds_dwordx4 v[232:233], off
	s_add_i32 m0, s1, 0x12000
	s_add_u32 s14, s14, 0x80
	s_addc_u32 s15, s15, 0
	global_load_lds_dwordx4 v[234:235], off
	s_add_u32 s2, s2, 0x80
	s_addc_u32 s3, s3, 0
	s_waitcnt vmcnt(8)
	s_waitcnt lgkmcnt(0)
	s_barrier
	v_mfma_f32_16x16x32_bf16 v[52:55], v[170:173], v[206:209], v[52:55]
	v_mfma_f32_16x16x32_bf16 v[44:47], v[190:193], v[206:209], v[44:47]
	v_mfma_f32_16x16x32_bf16 v[20:23], v[170:173], v[214:217], v[20:23]
	v_mfma_f32_16x16x32_bf16 v[16:19], v[190:193], v[214:217], v[16:19]
	v_mfma_f32_16x16x32_bf16 v[4:7], v[170:173], v[222:225], v[4:7]
	v_mfma_f32_16x16x32_bf16 v[0:3], v[190:193], v[222:225], v[0:3]
	v_mfma_f32_16x16x32_bf16 v[68:71], v[170:173], v[198:201], v[68:71]
	v_mfma_f32_16x16x32_bf16 v[64:67], v[190:193], v[198:201], v[64:67]
	v_mfma_f32_16x16x32_bf16 v[52:55], v[174:177], v[210:213], v[52:55]
	v_mfma_f32_16x16x32_bf16 v[44:47], v[194:197], v[210:213], v[44:47]
	v_mfma_f32_16x16x32_bf16 v[20:23], v[174:177], v[218:221], v[20:23]
	v_mfma_f32_16x16x32_bf16 v[16:19], v[194:197], v[218:221], v[16:19]
	v_mfma_f32_16x16x32_bf16 v[4:7], v[174:177], v[226:229], v[4:7]
	v_mfma_f32_16x16x32_bf16 v[0:3], v[194:197], v[226:229], v[0:3]
	v_mfma_f32_16x16x32_bf16 v[68:71], v[174:177], v[202:205], v[68:71]
	v_mfma_f32_16x16x32_bf16 v[64:67], v[194:197], v[202:205], v[64:67]
	s_barrier
	s_add_i32 s55, s55, 1
	s_cmp_lt_u32 s55, 7
	s_cbranch_scc1 .Lq_smp_3_k
	v_add_u32_e32 v161, 0x14000, v38
	ds_read_b128 v[170:173], v161
	ds_read_b128 v[174:177], v161 offset:1024
	ds_read_b128 v[190:193], v161 offset:2048
	ds_read_b128 v[194:197], v161 offset:3072
	ds_read_b128 v[198:201], v39 offset:16384
	ds_read_b128 v[202:205], v39 offset:17408
	ds_read_b128 v[206:209], v39 offset:18432
	ds_read_b128 v[210:213], v39 offset:19456
	ds_read_b128 v[214:217], v39 offset:20480
	ds_read_b128 v[218:221], v39 offset:21504
	ds_read_b128 v[222:225], v39 offset:22528
	ds_read_b128 v[226:229], v39 offset:23552
	v_lshl_add_u64 v[178:179], s[14:15], 0, v[144:145]
	s_add_i32 m0, s1, 0x8000
	v_lshl_add_u64 v[230:231], s[14:15], 0, v[28:29]
	global_load_lds_dwordx4 v[178:179], off
	s_add_i32 m0, s1, 0xa000
	v_lshl_add_u64 v[232:233], s[2:3], 0, v[144:145]
	global_load_lds_dwordx4 v[230:231], off
	s_add_i32 m0, s1, 0x18000
	v_lshl_add_u64 v[234:235], s[2:3], 0, v[28:29]
	global_load_lds_dwordx4 v[232:233], off
	s_add_i32 m0, s1, 0x1a000
	s_add_u32 s14, s14, 0x80
	s_addc_u32 s15, s15, 0
	global_load_lds_dwordx4 v[234:235], off
	s_add_u32 s2, s2, 0x80
	s_addc_u32 s3, s3, 0
	s_waitcnt vmcnt(8)
	s_waitcnt lgkmcnt(0)
	s_barrier
	v_mfma_f32_16x16x32_bf16 v[52:55], v[170:173], v[206:209], v[52:55]
	v_mfma_f32_16x16x32_bf16 v[44:47], v[190:193], v[206:209], v[44:47]
	v_mfma_f32_16x16x32_bf16 v[20:23], v[170:173], v[214:217], v[20:23]
	v_mfma_f32_16x16x32_bf16 v[16:19], v[190:193], v[214:217], v[16:19]
	v_mfma_f32_16x16x32_bf16 v[4:7], v[170:173], v[222:225], v[4:7]
	v_mfma_f32_16x16x32_bf16 v[0:3], v[190:193], v[222:225], v[0:3]
	v_mfma_f32_16x16x32_bf16 v[68:71], v[170:173], v[198:201], v[68:71]
	v_mfma_f32_16x16x32_bf16 v[64:67], v[190:193], v[198:201], v[64:67]
	v_mfma_f32_16x16x32_bf16 v[52:55], v[174:177], v[210:213], v[52:55]
	v_mfma_f32_16x16x32_bf16 v[44:47], v[194:197], v[210:213], v[44:47]
	v_mfma_f32_16x16x32_bf16 v[20:23], v[174:177], v[218:221], v[20:23]
	v_mfma_f32_16x16x32_bf16 v[16:19], v[194:197], v[218:221], v[16:19]
	v_mfma_f32_16x16x32_bf16 v[4:7], v[174:177], v[226:229], v[4:7]
	v_mfma_f32_16x16x32_bf16 v[0:3], v[194:197], v[226:229], v[0:3]
	v_mfma_f32_16x16x32_bf16 v[68:71], v[174:177], v[202:205], v[68:71]
	v_mfma_f32_16x16x32_bf16 v[64:67], v[194:197], v[202:205], v[64:67]
	s_barrier
	v_add_u32_e32 v161, 0x1c000, v38
	ds_read_b128 v[170:173], v161
	ds_read_b128 v[174:177], v161 offset:1024
	ds_read_b128 v[190:193], v161 offset:2048
	ds_read_b128 v[194:197], v161 offset:3072
	ds_read_b128 v[198:201], v39 offset:49152
	ds_read_b128 v[202:205], v39 offset:50176
	ds_read_b128 v[206:209], v39 offset:51200
	ds_read_b128 v[210:213], v39 offset:52224
	ds_read_b128 v[214:217], v39 offset:53248
	ds_read_b128 v[218:221], v39 offset:54272
	ds_read_b128 v[222:225], v39 offset:55296
	ds_read_b128 v[226:229], v39 offset:56320
	s_waitcnt vmcnt(4)
	s_waitcnt lgkmcnt(0)
	s_barrier
	v_mfma_f32_16x16x32_bf16 v[52:55], v[170:173], v[206:209], v[52:55]
	v_mfma_f32_16x16x32_bf16 v[44:47], v[190:193], v[206:209], v[44:47]
	v_mfma_f32_16x16x32_bf16 v[20:23], v[170:173], v[214:217], v[20:23]
	v_mfma_f32_16x16x32_bf16 v[16:19], v[190:193], v[214:217], v[16:19]
	v_mfma_f32_16x16x32_bf16 v[4:7], v[170:173], v[222:225], v[4:7]
	v_mfma_f32_16x16x32_bf16 v[0:3], v[190:193], v[222:225], v[0:3]
	v_mfma_f32_16x16x32_bf16 v[68:71], v[170:173], v[198:201], v[68:71]
	v_mfma_f32_16x16x32_bf16 v[64:67], v[190:193], v[198:201], v[64:67]
	v_mfma_f32_16x16x32_bf16 v[52:55], v[174:177], v[210:213], v[52:55]
	v_mfma_f32_16x16x32_bf16 v[44:47], v[194:197], v[210:213], v[44:47]
	v_mfma_f32_16x16x32_bf16 v[20:23], v[174:177], v[218:221], v[20:23]
	v_mfma_f32_16x16x32_bf16 v[16:19], v[194:197], v[218:221], v[16:19]
	v_mfma_f32_16x16x32_bf16 v[4:7], v[174:177], v[226:229], v[4:7]
	v_mfma_f32_16x16x32_bf16 v[0:3], v[194:197], v[226:229], v[0:3]
	v_mfma_f32_16x16x32_bf16 v[68:71], v[174:177], v[202:205], v[68:71]
	v_mfma_f32_16x16x32_bf16 v[64:67], v[194:197], v[202:205], v[64:67]
	s_barrier
	v_add_u32_e32 v161, 0x10000, v38
	ds_read_b128 v[170:173], v161
	ds_read_b128 v[174:177], v161 offset:1024
	ds_read_b128 v[190:193], v161 offset:2048
	ds_read_b128 v[194:197], v161 offset:3072
	ds_read_b128 v[198:201], v39 offset:0
	ds_read_b128 v[202:205], v39 offset:1024
	ds_read_b128 v[206:209], v39 offset:2048
	ds_read_b128 v[210:213], v39 offset:3072
	ds_read_b128 v[214:217], v39 offset:4096
	ds_read_b128 v[218:221], v39 offset:5120
	ds_read_b128 v[222:225], v39 offset:6144
	ds_read_b128 v[226:229], v39 offset:7168
	s_waitcnt vmcnt(0)
	s_waitcnt lgkmcnt(0)
	s_barrier
	v_mfma_f32_16x16x32_bf16 v[52:55], v[170:173], v[206:209], v[52:55]
	v_mfma_f32_16x16x32_bf16 v[44:47], v[190:193], v[206:209], v[44:47]
	v_mfma_f32_16x16x32_bf16 v[20:23], v[170:173], v[214:217], v[20:23]
	v_mfma_f32_16x16x32_bf16 v[16:19], v[190:193], v[214:217], v[16:19]
	v_mfma_f32_16x16x32_bf16 v[4:7], v[170:173], v[222:225], v[4:7]
	v_mfma_f32_16x16x32_bf16 v[0:3], v[190:193], v[222:225], v[0:3]
	v_mfma_f32_16x16x32_bf16 v[68:71], v[170:173], v[198:201], v[68:71]
	v_mfma_f32_16x16x32_bf16 v[64:67], v[190:193], v[198:201], v[64:67]
	v_mfma_f32_16x16x32_bf16 v[52:55], v[174:177], v[210:213], v[52:55]
	v_mfma_f32_16x16x32_bf16 v[44:47], v[194:197], v[210:213], v[44:47]
	v_mfma_f32_16x16x32_bf16 v[20:23], v[174:177], v[218:221], v[20:23]
	v_mfma_f32_16x16x32_bf16 v[16:19], v[194:197], v[218:221], v[16:19]
	v_mfma_f32_16x16x32_bf16 v[4:7], v[174:177], v[226:229], v[4:7]
	v_mfma_f32_16x16x32_bf16 v[0:3], v[194:197], v[226:229], v[0:3]
	v_mfma_f32_16x16x32_bf16 v[68:71], v[174:177], v[202:205], v[68:71]
	v_mfma_f32_16x16x32_bf16 v[64:67], v[194:197], v[202:205], v[64:67]
	s_barrier
	v_add_u32_e32 v161, 0x18000, v38
	ds_read_b128 v[170:173], v161
	ds_read_b128 v[174:177], v161 offset:1024
	ds_read_b128 v[190:193], v161 offset:2048
	ds_read_b128 v[194:197], v161 offset:3072
	ds_read_b128 v[198:201], v39 offset:32768
	ds_read_b128 v[202:205], v39 offset:33792
	ds_read_b128 v[206:209], v39 offset:34816
	ds_read_b128 v[210:213], v39 offset:35840
	ds_read_b128 v[214:217], v39 offset:36864
	ds_read_b128 v[218:221], v39 offset:37888
	ds_read_b128 v[222:225], v39 offset:38912
	ds_read_b128 v[226:229], v39 offset:39936
	s_waitcnt lgkmcnt(0)
	s_barrier
	v_mfma_f32_16x16x32_bf16 v[52:55], v[170:173], v[206:209], v[52:55]
	v_mfma_f32_16x16x32_bf16 v[44:47], v[190:193], v[206:209], v[44:47]
	v_mfma_f32_16x16x32_bf16 v[20:23], v[170:173], v[214:217], v[20:23]
	v_mfma_f32_16x16x32_bf16 v[16:19], v[190:193], v[214:217], v[16:19]
	v_mfma_f32_16x16x32_bf16 v[4:7], v[170:173], v[222:225], v[4:7]
	v_mfma_f32_16x16x32_bf16 v[0:3], v[190:193], v[222:225], v[0:3]
	v_mfma_f32_16x16x32_bf16 v[68:71], v[170:173], v[198:201], v[68:71]
	v_mfma_f32_16x16x32_bf16 v[64:67], v[190:193], v[198:201], v[64:67]
	v_mfma_f32_16x16x32_bf16 v[52:55], v[174:177], v[210:213], v[52:55]
	v_mfma_f32_16x16x32_bf16 v[44:47], v[194:197], v[210:213], v[44:47]
	v_mfma_f32_16x16x32_bf16 v[20:23], v[174:177], v[218:221], v[20:23]
	v_mfma_f32_16x16x32_bf16 v[16:19], v[194:197], v[218:221], v[16:19]
	v_mfma_f32_16x16x32_bf16 v[4:7], v[174:177], v[226:229], v[4:7]
	v_mfma_f32_16x16x32_bf16 v[0:3], v[194:197], v[226:229], v[0:3]
	v_mfma_f32_16x16x32_bf16 v[68:71], v[174:177], v[202:205], v[68:71]
	v_mfma_f32_16x16x32_bf16 v[64:67], v[194:197], v[202:205], v[64:67]
	s_barrier
	s_branch .Lq_smp_exit
